# attention: LDS fragment reads run one piece ahead of the MFMAs (two fragment buffers, five pieces in flight), packed softmax subtract/sum, single-instruction row clamp; pool scale loaded once per phas
# speedup vs baseline: 1.0310x; 1.0022x over previous
.LBB0_296:
	v_writelane_b32 v244, s2, 31
	v_writelane_b32 v244, s84, 32
	v_writelane_b32 v244, s85, 33
	v_writelane_b32 v244, s86, 34
	v_writelane_b32 v244, s87, 35
	v_writelane_b32 v244, s96, 36
	v_writelane_b32 v244, s97, 37
	v_writelane_b32 v244, s50, 38
	v_writelane_b32 v244, s51, 39
	s_mov_b64 s[46:47], s[86:87]
	s_mov_b32 s10, s72
	v_readlane_b32 s11, v244, 0
	s_add_u32 s48, s46, 0x18800200
	s_addc_u32 s49, s47, 0
	s_add_u32 s50, s46, 0x1b00000
	s_addc_u32 s51, s47, 0
	s_mul_i32 s90, s10, 0x2800
	s_add_i32 s90, s90, 0x10800
	s_add_i32 s12, s90, 0x0
	s_add_i32 s13, s90, 0x800
	s_add_i32 s14, s90, 0x1000
	s_add_i32 s15, s90, 0x1800
	s_add_i32 s16, s90, 0x2000
	v_and_b32_e32 v146, 63, v214
	v_and_b32_e32 v216, 15, v146
	v_lshrrev_b32_e32 v217, 4, v146
	v_lshrrev_b32_e32 v218, 3, v146
	v_and_b32_e32 v219, 7, v146
	v_lshlrev_b32_e32 v229, 2, v217
	v_mov_b32_e32 v230, 0xff800000
	v_lshrrev_b32_e32 v147, 1, v218
	v_xor_b32_e32 v220, v219, v147
	v_xor_b32_e32 v221, 4, v220
	v_lshlrev_b32_e32 v220, 4, v220
	v_lshlrev_b32_e32 v221, 4, v221
	v_lshlrev_b32_e32 v148, 1, v147
	v_xor_b32_e32 v222, v219, v148
	v_lshlrev_b32_e32 v222, 4, v222
	v_lshrrev_b32_e32 v147, 1, v216
	v_xor_b32_e32 v148, v217, v147
	v_or_b32_e32 v149, 4, v217
	v_xor_b32_e32 v149, v149, v147
	v_lshlrev_b32_e32 v150, 7, v216
	v_lshl_add_u32 v223, v148, 4, v150
	v_lshl_add_u32 v224, v149, 4, v150
	v_lshrrev_b32_e32 v147, 2, v216
	v_lshl_add_u32 v147, v217, 2, v147
	v_and_b32_e32 v148, 3, v216
	v_lshrrev_b32_e32 v149, 1, v148
	v_bfe_u32 v150, v147, 1, 2
	v_lshlrev_b32_e32 v150, 1, v150
	v_and_b32_e32 v151, 1, v148
	v_lshlrev_b32_e32 v151, 3, v151
	v_lshl_add_u32 v151, v147, 7, v151
	v_or_b32_e32 v152, 0, v149
	v_xor_b32_e32 v152, v152, v150
	v_lshl_add_u32 v225, v152, 4, v151
	v_or_b32_e32 v152, 2, v149
	v_xor_b32_e32 v152, v152, v150
	v_lshl_add_u32 v226, v152, 4, v151
	v_or_b32_e32 v152, 4, v149
	v_xor_b32_e32 v152, v152, v150
	v_lshl_add_u32 v227, v152, 4, v151
	v_or_b32_e32 v152, 6, v149
	v_xor_b32_e32 v152, v152, v150
	v_lshl_add_u32 v228, v152, 4, v151
	v_and_b32_e32 v147, 1, v217
	v_lshrrev_b32_e32 v148, 1, v217
	v_lshlrev_b32_e32 v147, 5, v147
	v_lshl_add_u32 v233, v148, 4, v147
	v_or_b32_e32 v147, 0, v229
	v_cmp_lt_u32_e64 s[52:53], v147, v216
	v_cmp_gt_u32_e64 s[62:63], v147, v216
	v_or_b32_e32 v147, 1, v229
	v_cmp_lt_u32_e64 s[56:57], v147, v216
	v_cmp_gt_u32_e64 s[64:65], v147, v216
	v_or_b32_e32 v147, 2, v229
	v_cmp_lt_u32_e64 s[58:59], v147, v216
	v_cmp_gt_u32_e64 s[70:71], v147, v216
	v_or_b32_e32 v147, 3, v229
	v_cmp_lt_u32_e64 s[60:61], v147, v216
	v_cmp_gt_u32_e64 s[72:73], v147, v216
	v_cmp_eq_u32_e64 s[74:75], 0, v217
	s_lshl_b32 s82, s10, 5
	s_lshr_b32 s90, s10, 2
	s_and_b32 s91, s10, 3
	s_lshl_b32 s90, s90, 7
	s_add_i32 s83, s90, s91
	s_mov_b32 s84, s10
	s_add_i32 s85, s10, 8
	s_mul_hi_u32 s43, s11, 0xaaaaaaab
	s_lshr_b32 s43, s43, 7
	s_mul_i32 s90, s43, 0xc0
	s_sub_i32 s90, s11, s90
	s_lshl_b32 s42, s90, 8
	s_cmp_lt_u32 s90, 64
	s_mov_b32 s91, 0x7fffc000
	s_cselect_b32 s91, 0xfffff800, s91
	s_movk_i32 s40, 0x3fff
	s_cselect_b32 s40, 0x7ff, s40
	s_and_b32 s91, s91, s42
	s_sub_i32 s38, s42, s91
	s_mul_i32 s90, s43, 0x600000
	s_lshl_b32 s91, s91, 7
	s_add_u32 s90, s90, s91
	s_add_u32 s18, s46, 0x9800000
	s_addc_u32 s19, s47, 0
	s_add_u32 s18, s18, s90
	s_addc_u32 s19, s19, 0
	s_add_u32 s20, s46, 0xe000000
	s_addc_u32 s21, s47, 0
	s_add_u32 s20, s20, s90
	s_addc_u32 s21, s21, 0
	s_add_u32 s24, s46, 0x12800000
	s_addc_u32 s25, s47, 0
	s_add_u32 s24, s24, s90
	s_addc_u32 s25, s25, 0
	s_add_i32 s76, s38, s82
	v_lshlrev_b32_e32 v231, 0, v218
	v_add_u32_e32 v232, 8, v218
	v_lshlrev_b32_e32 v232, 0, v232
	s_add_i32 s93, s76, 0
	s_mov_b32 m0, s12
	v_add_u32_e32 v164, s93, v231
	v_lshl_or_b32 v164, v164, 7, v220
	global_load_lds_dwordx4 v164, s[18:19]
	s_add_i32 m0, s12, 0x400
	v_add_u32_e32 v165, s93, v232
	v_lshl_or_b32 v165, v165, 7, v221
	global_load_lds_dwordx4 v165, s[18:19]
	s_add_i32 s93, s76, 16
	s_mov_b32 m0, s13
	v_add_u32_e32 v164, s93, v231
	v_lshl_or_b32 v164, v164, 7, v220
	global_load_lds_dwordx4 v164, s[18:19]
	s_add_i32 m0, s13, 0x400
	v_add_u32_e32 v165, s93, v232
	v_lshl_or_b32 v165, v165, 7, v221
	global_load_lds_dwordx4 v165, s[18:19]
	s_add_i32 s93, s76, 0xffffffc0
	s_mov_b32 m0, s14
	v_add_u32_e32 v164, s93, v231
	v_med3_i32 v164, v164, 0, s40
	v_lshl_or_b32 v164, v164, 7, v220
	global_load_lds_dwordx4 v164, s[20:21]
	s_add_i32 m0, s14, 0x400
	v_add_u32_e32 v165, s93, v232
	v_med3_i32 v165, v165, 0, s40
	v_lshl_or_b32 v165, v165, 7, v221
	global_load_lds_dwordx4 v165, s[20:21]
	s_add_i32 s93, s76, 0xffffffd0
	s_mov_b32 m0, s15
	v_add_u32_e32 v164, s93, v231
	v_med3_i32 v164, v164, 0, s40
	v_lshl_or_b32 v164, v164, 7, v220
	global_load_lds_dwordx4 v164, s[20:21]
	s_add_i32 m0, s15, 0x400
	v_add_u32_e32 v165, s93, v232
	v_med3_i32 v165, v165, 0, s40
	v_lshl_or_b32 v165, v165, 7, v221
	global_load_lds_dwordx4 v165, s[20:21]
	s_add_i32 s93, s76, 0xffffffe0
	s_mov_b32 m0, s16
	v_add_u32_e32 v164, s93, v231
	v_med3_i32 v164, v164, 0, s40
	v_lshl_or_b32 v164, v164, 7, v220
	global_load_lds_dwordx4 v164, s[20:21]
	s_add_i32 m0, s16, 0x400
	v_add_u32_e32 v165, s93, v232
	v_med3_i32 v165, v165, 0, s40
	v_lshl_or_b32 v165, v165, 7, v221
	global_load_lds_dwordx4 v165, s[20:21]
.Latt_unit:
	s_add_i32 s92, s11, s66
	s_cmpk_lt_u32 s92, 0x900
	s_cselect_b32 s92, s92, s11
	s_mul_hi_u32 s45, s92, 0xaaaaaaab
	s_lshr_b32 s45, s45, 7
	s_mul_i32 s90, s45, 0xc0
	s_sub_i32 s90, s92, s90
	s_lshl_b32 s44, s90, 8
	s_cmp_lt_u32 s90, 64
	s_mov_b32 s91, 0x7fffc000
	s_cselect_b32 s91, 0xfffff800, s91
	s_movk_i32 s41, 0x3fff
	s_cselect_b32 s41, 0x7ff, s41
	s_and_b32 s91, s91, s44
	s_sub_i32 s39, s44, s91
	s_mul_i32 s90, s45, 0x600000
	s_lshl_b32 s91, s91, 7
	s_add_u32 s90, s90, s91
	s_add_u32 s30, s46, 0x9800000
	s_addc_u32 s31, s47, 0
	s_add_u32 s30, s30, s90
	s_addc_u32 s31, s31, 0
	s_add_u32 s34, s46, 0xe000000
	s_addc_u32 s35, s47, 0
	s_add_u32 s34, s34, s90
	s_addc_u32 s35, s35, 0
	s_add_u32 s36, s46, 0x12800000
	s_addc_u32 s37, s47, 0
	s_add_u32 s36, s36, s90
	s_addc_u32 s37, s37, 0
	s_add_i32 s76, s38, s82
	s_add_i32 s79, s38, s83
	v_lshlrev_b32_e32 v231, 0, v218
	v_add_u32_e32 v232, 8, v218
	v_lshlrev_b32_e32 v232, 0, v232
	v_lshlrev_b32_e32 v162, 2, v218
	v_add_u32_e32 v163, 8, v218
	v_lshlrev_b32_e32 v163, 2, v163
	s_waitcnt vmcnt(8)
	v_add_u32_e32 v154, s12, v223
	v_add_u32_e32 v155, s12, v224
	ds_read_b128 v[72:75], v154
	ds_read_b128 v[76:79], v155
	s_waitcnt lgkmcnt(0)
	s_add_i32 s93, s76, -16
	s_mov_b32 m0, s12
	v_add_u32_e32 v164, s93, v231
	v_med3_i32 v164, v164, 0, s40
	v_lshl_or_b32 v164, v164, 7, v220
	global_load_lds_dwordx4 v164, s[20:21]
	s_add_i32 m0, s12, 0x400
	v_add_u32_e32 v165, s93, v232
	v_med3_i32 v165, v165, 0, s40
	v_lshl_or_b32 v165, v165, 7, v221
	global_load_lds_dwordx4 v165, s[20:21]
	s_waitcnt vmcnt(8)
	v_add_u32_e32 v154, s13, v223
	v_add_u32_e32 v155, s13, v224
	ds_read_b128 v[80:83], v154
	ds_read_b128 v[84:87], v155
	s_waitcnt lgkmcnt(0)
	s_add_i32 s93, s76, 0
	s_mov_b32 m0, s13
	v_add_u32_e32 v164, s93, v231
	v_med3_i32 v164, v164, 0, s40
	v_lshl_or_b32 v164, v164, 7, v220
	global_load_lds_dwordx4 v164, s[20:21]
	s_add_i32 m0, s13, 0x400
	v_add_u32_e32 v165, s93, v232
	v_med3_i32 v165, v165, 0, s40
	v_lshl_or_b32 v165, v165, 7, v221
	global_load_lds_dwordx4 v165, s[20:21]
	s_waitcnt vmcnt(8)
	v_add_u32_e32 v154, s14, v223
	v_add_u32_e32 v155, s14, v224
	ds_read_b128 v[88:91], v154
	ds_read_b128 v[92:95], v155
	s_waitcnt lgkmcnt(0)
	s_add_i32 s93, s76, 16
	s_mov_b32 m0, s14
	v_add_u32_e32 v164, s93, v231
	v_med3_i32 v164, v164, 0, s40
	v_lshl_or_b32 v164, v164, 7, v220
	global_load_lds_dwordx4 v164, s[20:21]
	s_add_i32 m0, s14, 0x400
	v_add_u32_e32 v165, s93, v232
	v_med3_i32 v165, v165, 0, s40
	v_lshl_or_b32 v165, v165, 7, v221
	global_load_lds_dwordx4 v165, s[20:21]
	s_waitcnt vmcnt(8)
	v_add_u32_e32 v154, s15, v223
	v_add_u32_e32 v155, s15, v224
	ds_read_b128 v[202:205], v154
	ds_read_b128 v[206:209], v155
	v_mfma_f32_16x16x32_bf16 v[0:3], v[88:91], v[72:75], 0
	v_mfma_f32_16x16x32_bf16 v[0:3], v[92:95], v[76:79], v[0:3]
	s_waitcnt lgkmcnt(0)
	s_add_i32 s93, s76, 32
	s_mov_b32 m0, s15
	v_add_u32_e32 v164, s93, v231
	v_med3_i32 v164, v164, 0, s40
	v_lshl_or_b32 v164, v164, 7, v220
	global_load_lds_dwordx4 v164, s[20:21]
	s_add_i32 m0, s15, 0x400
	v_add_u32_e32 v165, s93, v232
	v_med3_i32 v165, v165, 0, s40
	v_lshl_or_b32 v165, v165, 7, v221
	global_load_lds_dwordx4 v165, s[20:21]
	s_waitcnt vmcnt(8)
	v_add_u32_e32 v154, s16, v223
	v_add_u32_e32 v155, s16, v224
	ds_read_b128 v[88:91], v154
	ds_read_b128 v[92:95], v155
	v_mfma_f32_16x16x32_bf16 v[4:7], v[202:205], v[72:75], 0
	v_mfma_f32_16x16x32_bf16 v[36:39], v[202:205], v[80:83], 0
	v_mfma_f32_16x16x32_bf16 v[4:7], v[206:209], v[76:79], v[4:7]
	v_mfma_f32_16x16x32_bf16 v[36:39], v[206:209], v[84:87], v[36:39]
	s_waitcnt lgkmcnt(0)
	s_add_i32 s93, s76, 48
	s_mov_b32 m0, s16
	v_add_u32_e32 v164, s93, v231
	v_med3_i32 v164, v164, 0, s40
	v_lshl_or_b32 v164, v164, 7, v220
	global_load_lds_dwordx4 v164, s[20:21]
	s_add_i32 m0, s16, 0x400
	v_add_u32_e32 v165, s93, v232
	v_med3_i32 v165, v165, 0, s40
	v_lshl_or_b32 v165, v165, 7, v221
	global_load_lds_dwordx4 v165, s[20:21]
	s_waitcnt vmcnt(8)
	v_add_u32_e32 v154, s12, v223
	v_add_u32_e32 v155, s12, v224
	ds_read_b128 v[202:205], v154
	ds_read_b128 v[206:209], v155
	v_mfma_f32_16x16x32_bf16 v[8:11], v[88:91], v[72:75], 0
	v_mfma_f32_16x16x32_bf16 v[40:43], v[88:91], v[80:83], 0
	v_mfma_f32_16x16x32_bf16 v[8:11], v[92:95], v[76:79], v[8:11]
	v_mfma_f32_16x16x32_bf16 v[40:43], v[92:95], v[84:87], v[40:43]
	s_waitcnt lgkmcnt(0)
	s_add_i32 s93, s76, 64
	s_mov_b32 m0, s12
	v_add_u32_e32 v164, s93, v231
	v_med3_i32 v164, v164, 0, s40
	v_lshl_or_b32 v164, v164, 7, v220
	global_load_lds_dwordx4 v164, s[20:21]
	s_add_i32 m0, s12, 0x400
	v_add_u32_e32 v165, s93, v232
	v_med3_i32 v165, v165, 0, s40
	v_lshl_or_b32 v165, v165, 7, v221
	global_load_lds_dwordx4 v165, s[20:21]
	s_waitcnt vmcnt(8)
	v_add_u32_e32 v154, s13, v223
	v_add_u32_e32 v155, s13, v224
	ds_read_b128 v[88:91], v154
	ds_read_b128 v[92:95], v155
	v_mfma_f32_16x16x32_bf16 v[12:15], v[202:205], v[72:75], 0
	v_mfma_f32_16x16x32_bf16 v[44:47], v[202:205], v[80:83], 0
	v_mfma_f32_16x16x32_bf16 v[12:15], v[206:209], v[76:79], v[12:15]
	v_mfma_f32_16x16x32_bf16 v[44:47], v[206:209], v[84:87], v[44:47]
	s_waitcnt lgkmcnt(0)
	s_add_i32 s93, s76, 0x50
	s_mov_b32 m0, s13
	v_add_u32_e32 v164, s93, v231
	v_med3_i32 v164, v164, 0, s40
	v_lshl_or_b32 v164, v164, 7, v220
	global_load_lds_dwordx4 v164, s[20:21]
	s_add_i32 m0, s13, 0x400
	v_add_u32_e32 v165, s93, v232
	v_med3_i32 v165, v165, 0, s40
	v_lshl_or_b32 v165, v165, 7, v221
	global_load_lds_dwordx4 v165, s[20:21]
	s_waitcnt vmcnt(8)
	v_add_u32_e32 v154, s14, v223
	v_add_u32_e32 v155, s14, v224
	ds_read_b128 v[202:205], v154
	ds_read_b128 v[206:209], v155
	v_mfma_f32_16x16x32_bf16 v[16:19], v[88:91], v[72:75], 0
	v_mfma_f32_16x16x32_bf16 v[48:51], v[88:91], v[80:83], 0
	v_mfma_f32_16x16x32_bf16 v[16:19], v[92:95], v[76:79], v[16:19]
	v_mfma_f32_16x16x32_bf16 v[48:51], v[92:95], v[84:87], v[48:51]
	s_waitcnt lgkmcnt(0)
	s_add_i32 s93, s76, 0xffffffc0
	s_mov_b32 m0, s14
	v_add_u32_e32 v164, s93, v231
	v_med3_i32 v164, v164, 0, s40
	v_lshl_or_b32 v164, v164, 7, v222
	global_load_lds_dwordx4 v164, s[24:25]
	s_add_i32 m0, s14, 0x400
	v_add_u32_e32 v165, s93, v232
	v_med3_i32 v165, v165, 0, s40
	v_lshl_or_b32 v165, v165, 7, v222
	global_load_lds_dwordx4 v165, s[24:25]
	s_waitcnt vmcnt(8)
	v_add_u32_e32 v154, s15, v223
	v_add_u32_e32 v155, s15, v224
	ds_read_b128 v[88:91], v154
	ds_read_b128 v[92:95], v155
	v_mfma_f32_16x16x32_bf16 v[20:23], v[202:205], v[72:75], 0
	v_mfma_f32_16x16x32_bf16 v[52:55], v[202:205], v[80:83], 0
	v_mfma_f32_16x16x32_bf16 v[20:23], v[206:209], v[76:79], v[20:23]
	v_mfma_f32_16x16x32_bf16 v[52:55], v[206:209], v[84:87], v[52:55]
	s_waitcnt lgkmcnt(0)
	s_add_i32 s93, s76, 0xffffffd0
	s_mov_b32 m0, s15
	v_add_u32_e32 v164, s93, v231
	v_med3_i32 v164, v164, 0, s40
	v_lshl_or_b32 v164, v164, 7, v222
	global_load_lds_dwordx4 v164, s[24:25]
	s_add_i32 m0, s15, 0x400
	v_add_u32_e32 v165, s93, v232
	v_med3_i32 v165, v165, 0, s40
	v_lshl_or_b32 v165, v165, 7, v222
	global_load_lds_dwordx4 v165, s[24:25]
	s_waitcnt vmcnt(8)
	v_add_u32_e32 v154, s16, v223
	v_add_u32_e32 v155, s16, v224
	ds_read_b128 v[202:205], v154
	ds_read_b128 v[206:209], v155
	v_mfma_f32_16x16x32_bf16 v[24:27], v[88:91], v[72:75], 0
	v_mfma_f32_16x16x32_bf16 v[56:59], v[88:91], v[80:83], 0
	v_mfma_f32_16x16x32_bf16 v[24:27], v[92:95], v[76:79], v[24:27]
	v_mfma_f32_16x16x32_bf16 v[56:59], v[92:95], v[84:87], v[56:59]
	s_waitcnt lgkmcnt(0)
	s_add_i32 s93, s76, 0xffffffe0
	s_mov_b32 m0, s16
	v_add_u32_e32 v164, s93, v231
	v_med3_i32 v164, v164, 0, s40
	v_lshl_or_b32 v164, v164, 7, v222
	global_load_lds_dwordx4 v164, s[24:25]
	s_add_i32 m0, s16, 0x400
	v_add_u32_e32 v165, s93, v232
	v_med3_i32 v165, v165, 0, s40
	v_lshl_or_b32 v165, v165, 7, v222
	global_load_lds_dwordx4 v165, s[24:25]
	s_waitcnt vmcnt(8)
	v_add_u32_e32 v154, s12, v223
	v_add_u32_e32 v155, s12, v224
	ds_read_b128 v[88:91], v154
	ds_read_b128 v[92:95], v155
	v_mfma_f32_16x16x32_bf16 v[28:31], v[202:205], v[72:75], 0
	v_mfma_f32_16x16x32_bf16 v[60:63], v[202:205], v[80:83], 0
	v_mfma_f32_16x16x32_bf16 v[28:31], v[206:209], v[76:79], v[28:31]
	v_mfma_f32_16x16x32_bf16 v[60:63], v[206:209], v[84:87], v[60:63]
	s_waitcnt lgkmcnt(0)
	s_add_i32 s93, s76, -16
	s_mov_b32 m0, s12
	v_add_u32_e32 v164, s93, v231
	v_med3_i32 v164, v164, 0, s40
	v_lshl_or_b32 v164, v164, 7, v222
	global_load_lds_dwordx4 v164, s[24:25]
	s_add_i32 m0, s12, 0x400
	v_add_u32_e32 v165, s93, v232
	v_med3_i32 v165, v165, 0, s40
	v_lshl_or_b32 v165, v165, 7, v222
	global_load_lds_dwordx4 v165, s[24:25]
	s_waitcnt vmcnt(8)
	v_add_u32_e32 v154, s13, v223
	v_add_u32_e32 v155, s13, v224
	ds_read_b128 v[202:205], v154
	ds_read_b128 v[206:209], v155
	v_mfma_f32_16x16x32_bf16 v[32:35], v[88:91], v[72:75], 0
	v_mfma_f32_16x16x32_bf16 v[64:67], v[88:91], v[80:83], 0
	v_mfma_f32_16x16x32_bf16 v[32:35], v[92:95], v[76:79], v[32:35]
	v_mfma_f32_16x16x32_bf16 v[64:67], v[92:95], v[84:87], v[64:67]
	s_waitcnt lgkmcnt(0)
	s_add_i32 s93, s76, 0
	s_mov_b32 m0, s13
	v_add_u32_e32 v164, s93, v231
	v_med3_i32 v164, v164, 0, s40
	v_lshl_or_b32 v164, v164, 7, v222
	global_load_lds_dwordx4 v164, s[24:25]
	s_add_i32 m0, s13, 0x400
	v_add_u32_e32 v165, s93, v232
	v_med3_i32 v165, v165, 0, s40
	v_lshl_or_b32 v165, v165, 7, v222
	global_load_lds_dwordx4 v165, s[24:25]
	s_waitcnt vmcnt(8)
	v_add_u32_e32 v154, s14, v225
	v_add_u32_e32 v155, s14, v226
	v_add_u32_e32 v156, s14, v227
	v_add_u32_e32 v157, s14, v228
	ds_read_b64_tr_b16 v[88:89], v154
	ds_read_b64_tr_b16 v[90:91], v155
	ds_read_b64_tr_b16 v[92:93], v156
	ds_read_b64_tr_b16 v[94:95], v157
	v_mfma_f32_16x16x32_bf16 v[68:71], v[202:205], v[80:83], 0
	v_mfma_f32_16x16x32_bf16 v[68:71], v[206:209], v[84:87], v[68:71]
	v_mov_b32_e32 v188, s82
	v_add_u32_e32 v188, v216, v188
	v_lshrrev_b32_e32 v146, 4, v188
	v_xor_b32_e32 v146, v146, v188
	v_and_b32_e32 v146, 15, v146
	v_lshlrev_b32_e32 v147, 8, v188
	v_or_b32_e32 v148, 0, v217
	v_xor_b32_e32 v148, v148, v146
	v_lshl_add_u32 v190, v148, 4, v147
	v_or_b32_e32 v148, 4, v217
	v_xor_b32_e32 v148, v148, v146
	v_lshl_add_u32 v191, v148, 4, v147
	v_or_b32_e32 v148, 8, v217
	v_xor_b32_e32 v148, v148, v146
	v_lshl_add_u32 v192, v148, 4, v147
	v_or_b32_e32 v148, 12, v217
	v_xor_b32_e32 v148, v148, v146
	v_lshl_add_u32 v193, v148, 4, v147
	v_lshlrev_b32_e32 v194, 3, v188
	v_add_u32_e32 v194, 0x10000, v194
	v_mov_b32_e32 v189, s82
	v_add_u32_e32 v189, v216, v189
	v_add_u32_e32 v189, 16, v189
	v_lshrrev_b32_e32 v146, 4, v189
	v_xor_b32_e32 v146, v146, v189
	v_and_b32_e32 v146, 15, v146
	v_lshlrev_b32_e32 v147, 8, v189
	v_or_b32_e32 v148, 0, v217
	v_xor_b32_e32 v148, v148, v146
	v_lshl_add_u32 v195, v148, 4, v147
	v_or_b32_e32 v148, 4, v217
	v_xor_b32_e32 v148, v148, v146
	v_lshl_add_u32 v196, v148, 4, v147
	v_or_b32_e32 v148, 8, v217
	v_xor_b32_e32 v148, v148, v146
	v_lshl_add_u32 v197, v148, 4, v147
	v_or_b32_e32 v148, 12, v217
	v_xor_b32_e32 v148, v148, v146
	v_lshl_add_u32 v198, v148, 4, v147
	v_lshlrev_b32_e32 v199, 3, v189
	v_add_u32_e32 v199, 0x10000, v199
	s_add_i32 s90, s76, 0x5f
	s_cmp_gt_i32 s90, s40
	s_cselect_b32 s96, 1, 0
	s_cmp_lt_i32 s76, 64
	s_cselect_b32 s96, 1, s96
	s_ashr_i32 s77, s76, 0
	s_sub_i32 s77, 64, s77
	s_sub_i32 s78, s40, s76
	s_ashr_i32 s78, s78, 0
	s_add_i32 s78, s78, 64
	v_cndmask_b32_e64 v0, v0, v230, s[52:53]
	v_cndmask_b32_e64 v32, v32, v230, s[62:63]
	v_cndmask_b32_e64 v1, v1, v230, s[56:57]
	v_cndmask_b32_e64 v33, v33, v230, s[64:65]
	v_cndmask_b32_e64 v2, v2, v230, s[58:59]
	v_cndmask_b32_e64 v34, v34, v230, s[70:71]
	v_cndmask_b32_e64 v3, v3, v230, s[60:61]
	v_cndmask_b32_e64 v35, v35, v230, s[72:73]
	s_cmp_eq_u32 s96, 0
	s_cbranch_scc1 .Latt_noedge_1
	v_sub_u32_e32 v200, s77, v229
	s_sub_i32 s91, s78, s77
	v_sub_u32_e32 v150, 0, v200
	v_sub_u32_e32 v151, 1, v200
	v_sub_u32_e32 v152, 2, v200
	v_sub_u32_e32 v153, 3, v200
	v_cmp_lt_u32_e64 s[94:95], s91, v150
	v_cmp_lt_u32_e64 s[86:87], s91, v151
	v_cmp_lt_u32_e64 s[0:1], s91, v152
	v_cmp_lt_u32_e64 s[2:3], s91, v153
	v_cndmask_b32_e64 v0, v0, v230, s[94:95]
	v_cndmask_b32_e64 v1, v1, v230, s[86:87]
	v_cndmask_b32_e64 v2, v2, v230, s[0:1]
	v_cndmask_b32_e64 v3, v3, v230, s[2:3]
	v_sub_u32_e32 v150, 16, v200
	v_sub_u32_e32 v151, 17, v200
	v_sub_u32_e32 v152, 18, v200
	v_sub_u32_e32 v153, 19, v200
	v_cmp_lt_u32_e64 s[94:95], s91, v150
	v_cmp_lt_u32_e64 s[86:87], s91, v151
	v_cmp_lt_u32_e64 s[0:1], s91, v152
	v_cmp_lt_u32_e64 s[2:3], s91, v153
	v_cndmask_b32_e64 v4, v4, v230, s[94:95]
	v_cndmask_b32_e64 v5, v5, v230, s[86:87]
	v_cndmask_b32_e64 v6, v6, v230, s[0:1]
	v_cndmask_b32_e64 v7, v7, v230, s[2:3]
	v_sub_u32_e32 v150, 32, v200
	v_sub_u32_e32 v151, 33, v200
	v_sub_u32_e32 v152, 34, v200
	v_sub_u32_e32 v153, 35, v200
	v_cmp_lt_u32_e64 s[94:95], s91, v150
	v_cmp_lt_u32_e64 s[86:87], s91, v151
	v_cmp_lt_u32_e64 s[0:1], s91, v152
	v_cmp_lt_u32_e64 s[2:3], s91, v153
	v_cndmask_b32_e64 v8, v8, v230, s[94:95]
	v_cndmask_b32_e64 v9, v9, v230, s[86:87]
	v_cndmask_b32_e64 v10, v10, v230, s[0:1]
	v_cndmask_b32_e64 v11, v11, v230, s[2:3]
	v_sub_u32_e32 v150, 48, v200
	v_sub_u32_e32 v151, 49, v200
	v_sub_u32_e32 v152, 50, v200
	v_sub_u32_e32 v153, 51, v200
	v_cmp_lt_u32_e64 s[94:95], s91, v150
	v_cmp_lt_u32_e64 s[86:87], s91, v151
	v_cmp_lt_u32_e64 s[0:1], s91, v152
	v_cmp_lt_u32_e64 s[2:3], s91, v153
	v_cndmask_b32_e64 v12, v12, v230, s[94:95]
	v_cndmask_b32_e64 v13, v13, v230, s[86:87]
	v_cndmask_b32_e64 v14, v14, v230, s[0:1]
	v_cndmask_b32_e64 v15, v15, v230, s[2:3]
	v_sub_u32_e32 v150, 64, v200
	v_sub_u32_e32 v151, 0x41, v200
	v_sub_u32_e32 v152, 0x42, v200
	v_sub_u32_e32 v153, 0x43, v200
	v_cmp_lt_u32_e64 s[94:95], s91, v150
	v_cmp_lt_u32_e64 s[86:87], s91, v151
	v_cmp_lt_u32_e64 s[0:1], s91, v152
	v_cmp_lt_u32_e64 s[2:3], s91, v153
	v_cndmask_b32_e64 v16, v16, v230, s[94:95]
	v_cndmask_b32_e64 v17, v17, v230, s[86:87]
	v_cndmask_b32_e64 v18, v18, v230, s[0:1]
	v_cndmask_b32_e64 v19, v19, v230, s[2:3]
	v_sub_u32_e32 v150, 0x50, v200
	v_sub_u32_e32 v151, 0x51, v200
	v_sub_u32_e32 v152, 0x52, v200
	v_sub_u32_e32 v153, 0x53, v200
	v_cmp_lt_u32_e64 s[94:95], s91, v150
	v_cmp_lt_u32_e64 s[86:87], s91, v151
	v_cmp_lt_u32_e64 s[0:1], s91, v152
	v_cmp_lt_u32_e64 s[2:3], s91, v153
	v_cndmask_b32_e64 v20, v20, v230, s[94:95]
	v_cndmask_b32_e64 v21, v21, v230, s[86:87]
	v_cndmask_b32_e64 v22, v22, v230, s[0:1]
	v_cndmask_b32_e64 v23, v23, v230, s[2:3]
	v_sub_u32_e32 v150, 0x60, v200
	v_sub_u32_e32 v151, 0x61, v200
	v_sub_u32_e32 v152, 0x62, v200
	v_sub_u32_e32 v153, 0x63, v200
	v_cmp_lt_u32_e64 s[94:95], s91, v150
	v_cmp_lt_u32_e64 s[86:87], s91, v151
	v_cmp_lt_u32_e64 s[0:1], s91, v152
	v_cmp_lt_u32_e64 s[2:3], s91, v153
	v_cndmask_b32_e64 v24, v24, v230, s[94:95]
	v_cndmask_b32_e64 v25, v25, v230, s[86:87]
	v_cndmask_b32_e64 v26, v26, v230, s[0:1]
	v_cndmask_b32_e64 v27, v27, v230, s[2:3]
	v_sub_u32_e32 v150, 0x70, v200
	v_sub_u32_e32 v151, 0x71, v200
	v_sub_u32_e32 v152, 0x72, v200
	v_sub_u32_e32 v153, 0x73, v200
	v_cmp_lt_u32_e64 s[94:95], s91, v150
	v_cmp_lt_u32_e64 s[86:87], s91, v151
	v_cmp_lt_u32_e64 s[0:1], s91, v152
	v_cmp_lt_u32_e64 s[2:3], s91, v153
	v_cndmask_b32_e64 v28, v28, v230, s[94:95]
	v_cndmask_b32_e64 v29, v29, v230, s[86:87]
	v_cndmask_b32_e64 v30, v30, v230, s[0:1]
	v_cndmask_b32_e64 v31, v31, v230, s[2:3]
	v_sub_u32_e32 v150, 0x80, v200
	v_sub_u32_e32 v151, 0x81, v200
	v_sub_u32_e32 v152, 0x82, v200
	v_sub_u32_e32 v153, 0x83, v200
	v_cmp_lt_u32_e64 s[94:95], s91, v150
	v_cmp_lt_u32_e64 s[86:87], s91, v151
	v_cmp_lt_u32_e64 s[0:1], s91, v152
	v_cmp_lt_u32_e64 s[2:3], s91, v153
	v_cndmask_b32_e64 v32, v32, v230, s[94:95]
	v_cndmask_b32_e64 v33, v33, v230, s[86:87]
	v_cndmask_b32_e64 v34, v34, v230, s[0:1]
	v_cndmask_b32_e64 v35, v35, v230, s[2:3]
.Latt_noedge_1:
	s_nop 1
	v_max3_f32 v184, v0, v1, v2
	v_max3_f32 v184, v184, v3, v4
	v_max3_f32 v184, v184, v5, v6
	v_max3_f32 v184, v184, v7, v8
	v_max3_f32 v184, v184, v9, v10
	v_max3_f32 v184, v184, v11, v12
	v_max3_f32 v184, v184, v13, v14
	v_max3_f32 v184, v184, v15, v16
	v_max3_f32 v184, v184, v17, v18
	v_max3_f32 v184, v184, v19, v20
	v_max3_f32 v184, v184, v21, v22
	v_max3_f32 v184, v184, v23, v24
	v_max3_f32 v184, v184, v25, v26
	v_max3_f32 v184, v184, v27, v28
	v_max3_f32 v184, v184, v29, v30
	v_max3_f32 v184, v184, v31, v32
	v_max3_f32 v184, v184, v33, v34
	v_max_f32_e32 v184, v184, v35
	v_mov_b32_e32 v146, v184
	s_nop 1
	v_permlane16_swap_b32_e32 v184, v146
	v_max_f32_e32 v184, v184, v146
	v_mov_b32_e32 v146, v184
	s_nop 1
	v_permlane32_swap_b32_e32 v184, v146
	v_max_f32_e32 v184, v184, v146
	v_pk_add_f32 v[0:1], v[0:1], v[184:185] op_sel_hi:[1,0] neg_lo:[0,1] neg_hi:[0,1]
	v_pk_add_f32 v[2:3], v[2:3], v[184:185] op_sel_hi:[1,0] neg_lo:[0,1] neg_hi:[0,1]
	v_pk_add_f32 v[4:5], v[4:5], v[184:185] op_sel_hi:[1,0] neg_lo:[0,1] neg_hi:[0,1]
	v_pk_add_f32 v[6:7], v[6:7], v[184:185] op_sel_hi:[1,0] neg_lo:[0,1] neg_hi:[0,1]
	v_exp_f32_e32 v0, v0
	v_exp_f32_e32 v1, v1
	v_exp_f32_e32 v2, v2
	v_exp_f32_e32 v3, v3
	v_pk_add_f32 v[8:9], v[8:9], v[184:185] op_sel_hi:[1,0] neg_lo:[0,1] neg_hi:[0,1]
	v_pk_add_f32 v[10:11], v[10:11], v[184:185] op_sel_hi:[1,0] neg_lo:[0,1] neg_hi:[0,1]
	v_exp_f32_e32 v4, v4
	v_exp_f32_e32 v5, v5
	v_exp_f32_e32 v6, v6
	v_exp_f32_e32 v7, v7
	v_pk_add_f32 v[12:13], v[12:13], v[184:185] op_sel_hi:[1,0] neg_lo:[0,1] neg_hi:[0,1]
	v_pk_add_f32 v[14:15], v[14:15], v[184:185] op_sel_hi:[1,0] neg_lo:[0,1] neg_hi:[0,1]
	v_exp_f32_e32 v8, v8
	v_exp_f32_e32 v9, v9
	v_exp_f32_e32 v10, v10
	v_exp_f32_e32 v11, v11
	v_pk_add_f32 v[16:17], v[16:17], v[184:185] op_sel_hi:[1,0] neg_lo:[0,1] neg_hi:[0,1]
	v_pk_add_f32 v[18:19], v[18:19], v[184:185] op_sel_hi:[1,0] neg_lo:[0,1] neg_hi:[0,1]
	v_exp_f32_e32 v12, v12
	v_exp_f32_e32 v13, v13
	v_exp_f32_e32 v14, v14
	v_exp_f32_e32 v15, v15
	v_pk_add_f32 v[20:21], v[20:21], v[184:185] op_sel_hi:[1,0] neg_lo:[0,1] neg_hi:[0,1]
	v_pk_add_f32 v[22:23], v[22:23], v[184:185] op_sel_hi:[1,0] neg_lo:[0,1] neg_hi:[0,1]
	v_exp_f32_e32 v16, v16
	v_exp_f32_e32 v17, v17
	v_exp_f32_e32 v18, v18
	v_exp_f32_e32 v19, v19
	v_pk_add_f32 v[24:25], v[24:25], v[184:185] op_sel_hi:[1,0] neg_lo:[0,1] neg_hi:[0,1]
	v_pk_add_f32 v[26:27], v[26:27], v[184:185] op_sel_hi:[1,0] neg_lo:[0,1] neg_hi:[0,1]
	v_exp_f32_e32 v20, v20
	v_exp_f32_e32 v21, v21
	v_exp_f32_e32 v22, v22
	v_exp_f32_e32 v23, v23
	v_pk_add_f32 v[28:29], v[28:29], v[184:185] op_sel_hi:[1,0] neg_lo:[0,1] neg_hi:[0,1]
	v_pk_add_f32 v[30:31], v[30:31], v[184:185] op_sel_hi:[1,0] neg_lo:[0,1] neg_hi:[0,1]
	v_exp_f32_e32 v24, v24
	v_exp_f32_e32 v25, v25
	v_exp_f32_e32 v26, v26
	v_exp_f32_e32 v27, v27
	v_pk_add_f32 v[32:33], v[32:33], v[184:185] op_sel_hi:[1,0] neg_lo:[0,1] neg_hi:[0,1]
	v_pk_add_f32 v[34:35], v[34:35], v[184:185] op_sel_hi:[1,0] neg_lo:[0,1] neg_hi:[0,1]
	v_exp_f32_e32 v28, v28
	v_exp_f32_e32 v29, v29
	v_exp_f32_e32 v30, v30
	v_exp_f32_e32 v31, v31
	v_exp_f32_e32 v32, v32
	v_exp_f32_e32 v33, v33
	v_exp_f32_e32 v34, v34
	v_exp_f32_e32 v35, v35
	s_nop 0
	v_pk_add_f32 v[146:147], v[0:1], v[2:3]
	v_pk_add_f32 v[148:149], v[4:5], v[6:7]
	v_pk_add_f32 v[146:147], v[146:147], v[8:9]
	v_pk_add_f32 v[148:149], v[148:149], v[10:11]
	v_pk_add_f32 v[146:147], v[146:147], v[12:13]
	v_pk_add_f32 v[148:149], v[148:149], v[14:15]
	v_pk_add_f32 v[146:147], v[146:147], v[16:17]
	v_pk_add_f32 v[148:149], v[148:149], v[18:19]
	v_pk_add_f32 v[146:147], v[146:147], v[20:21]
	v_pk_add_f32 v[148:149], v[148:149], v[22:23]
	v_pk_add_f32 v[146:147], v[146:147], v[24:25]
	v_pk_add_f32 v[148:149], v[148:149], v[26:27]
	v_pk_add_f32 v[146:147], v[146:147], v[28:29]
	v_pk_add_f32 v[148:149], v[148:149], v[30:31]
	v_pk_add_f32 v[146:147], v[146:147], v[32:33]
	v_pk_add_f32 v[148:149], v[148:149], v[34:35]
	s_nop 0
	v_pk_add_f32 v[146:147], v[146:147], v[148:149]
	s_nop 0
	v_add_f32_e32 v185, v146, v147
	v_cvt_pk_bf16_f32 v0, v0, v1
	v_cvt_pk_bf16_f32 v1, v2, v3
	v_cvt_pk_bf16_f32 v4, v4, v5
	v_cvt_pk_bf16_f32 v5, v6, v7
	v_cvt_pk_bf16_f32 v8, v8, v9
	v_cvt_pk_bf16_f32 v9, v10, v11
	v_cvt_pk_bf16_f32 v12, v12, v13
	v_cvt_pk_bf16_f32 v13, v14, v15
	v_cvt_pk_bf16_f32 v16, v16, v17
	v_cvt_pk_bf16_f32 v17, v18, v19
	v_cvt_pk_bf16_f32 v20, v20, v21
	v_cvt_pk_bf16_f32 v21, v22, v23
	v_cvt_pk_bf16_f32 v24, v24, v25
	v_cvt_pk_bf16_f32 v25, v26, v27
	v_cvt_pk_bf16_f32 v28, v28, v29
	v_cvt_pk_bf16_f32 v29, v30, v31
	v_cvt_pk_bf16_f32 v32, v32, v33
	v_cvt_pk_bf16_f32 v33, v34, v35
	v_mov_b32_e32 v146, v185
	s_nop 1
	v_permlane16_swap_b32_e32 v185, v146
	v_add_f32_e32 v185, v185, v146
	v_mov_b32_e32 v146, v185
	s_nop 1
	v_permlane32_swap_b32_e32 v185, v146
	v_add_f32_e32 v185, v185, v146
	v_cndmask_b32_e64 v36, v36, v230, s[52:53]
	v_cndmask_b32_e64 v68, v68, v230, s[62:63]
	v_cndmask_b32_e64 v37, v37, v230, s[56:57]
	v_cndmask_b32_e64 v69, v69, v230, s[64:65]
	v_cndmask_b32_e64 v38, v38, v230, s[58:59]
	v_cndmask_b32_e64 v70, v70, v230, s[70:71]
	v_cndmask_b32_e64 v39, v39, v230, s[60:61]
	v_cndmask_b32_e64 v71, v71, v230, s[72:73]
	s_cmp_eq_u32 s96, 0
	s_cbranch_scc1 .Latt_noedge_2
	v_sub_u32_e32 v200, s77, v229
	v_add_u32_e32 v200, -16, v200
	s_sub_i32 s91, s78, s77
	v_sub_u32_e32 v150, 0, v200
	v_sub_u32_e32 v151, 1, v200
	v_sub_u32_e32 v152, 2, v200
	v_sub_u32_e32 v153, 3, v200
	v_cmp_lt_u32_e64 s[94:95], s91, v150
	v_cmp_lt_u32_e64 s[86:87], s91, v151
	v_cmp_lt_u32_e64 s[0:1], s91, v152
	v_cmp_lt_u32_e64 s[2:3], s91, v153
	v_cndmask_b32_e64 v36, v36, v230, s[94:95]
	v_cndmask_b32_e64 v37, v37, v230, s[86:87]
	v_cndmask_b32_e64 v38, v38, v230, s[0:1]
	v_cndmask_b32_e64 v39, v39, v230, s[2:3]
	v_sub_u32_e32 v150, 16, v200
	v_sub_u32_e32 v151, 17, v200
	v_sub_u32_e32 v152, 18, v200
	v_sub_u32_e32 v153, 19, v200
	v_cmp_lt_u32_e64 s[94:95], s91, v150
	v_cmp_lt_u32_e64 s[86:87], s91, v151
	v_cmp_lt_u32_e64 s[0:1], s91, v152
	v_cmp_lt_u32_e64 s[2:3], s91, v153
	v_cndmask_b32_e64 v40, v40, v230, s[94:95]
	v_cndmask_b32_e64 v41, v41, v230, s[86:87]
	v_cndmask_b32_e64 v42, v42, v230, s[0:1]
	v_cndmask_b32_e64 v43, v43, v230, s[2:3]
	v_sub_u32_e32 v150, 32, v200
	v_sub_u32_e32 v151, 33, v200
	v_sub_u32_e32 v152, 34, v200
	v_sub_u32_e32 v153, 35, v200
	v_cmp_lt_u32_e64 s[94:95], s91, v150
	v_cmp_lt_u32_e64 s[86:87], s91, v151
	v_cmp_lt_u32_e64 s[0:1], s91, v152
	v_cmp_lt_u32_e64 s[2:3], s91, v153
	v_cndmask_b32_e64 v44, v44, v230, s[94:95]
	v_cndmask_b32_e64 v45, v45, v230, s[86:87]
	v_cndmask_b32_e64 v46, v46, v230, s[0:1]
	v_cndmask_b32_e64 v47, v47, v230, s[2:3]
	v_sub_u32_e32 v150, 48, v200
	v_sub_u32_e32 v151, 49, v200
	v_sub_u32_e32 v152, 50, v200
	v_sub_u32_e32 v153, 51, v200
	v_cmp_lt_u32_e64 s[94:95], s91, v150
	v_cmp_lt_u32_e64 s[86:87], s91, v151
	v_cmp_lt_u32_e64 s[0:1], s91, v152
	v_cmp_lt_u32_e64 s[2:3], s91, v153
	v_cndmask_b32_e64 v48, v48, v230, s[94:95]
	v_cndmask_b32_e64 v49, v49, v230, s[86:87]
	v_cndmask_b32_e64 v50, v50, v230, s[0:1]
	v_cndmask_b32_e64 v51, v51, v230, s[2:3]
	v_sub_u32_e32 v150, 64, v200
	v_sub_u32_e32 v151, 0x41, v200
	v_sub_u32_e32 v152, 0x42, v200
	v_sub_u32_e32 v153, 0x43, v200
	v_cmp_lt_u32_e64 s[94:95], s91, v150
	v_cmp_lt_u32_e64 s[86:87], s91, v151
	v_cmp_lt_u32_e64 s[0:1], s91, v152
	v_cmp_lt_u32_e64 s[2:3], s91, v153
	v_cndmask_b32_e64 v52, v52, v230, s[94:95]
	v_cndmask_b32_e64 v53, v53, v230, s[86:87]
	v_cndmask_b32_e64 v54, v54, v230, s[0:1]
	v_cndmask_b32_e64 v55, v55, v230, s[2:3]
	v_sub_u32_e32 v150, 0x50, v200
	v_sub_u32_e32 v151, 0x51, v200
	v_sub_u32_e32 v152, 0x52, v200
	v_sub_u32_e32 v153, 0x53, v200
	v_cmp_lt_u32_e64 s[94:95], s91, v150
	v_cmp_lt_u32_e64 s[86:87], s91, v151
	v_cmp_lt_u32_e64 s[0:1], s91, v152
	v_cmp_lt_u32_e64 s[2:3], s91, v153
	v_cndmask_b32_e64 v56, v56, v230, s[94:95]
	v_cndmask_b32_e64 v57, v57, v230, s[86:87]
	v_cndmask_b32_e64 v58, v58, v230, s[0:1]
	v_cndmask_b32_e64 v59, v59, v230, s[2:3]
	v_sub_u32_e32 v150, 0x60, v200
	v_sub_u32_e32 v151, 0x61, v200
	v_sub_u32_e32 v152, 0x62, v200
	v_sub_u32_e32 v153, 0x63, v200
	v_cmp_lt_u32_e64 s[94:95], s91, v150
	v_cmp_lt_u32_e64 s[86:87], s91, v151
	v_cmp_lt_u32_e64 s[0:1], s91, v152
	v_cmp_lt_u32_e64 s[2:3], s91, v153
	v_cndmask_b32_e64 v60, v60, v230, s[94:95]
	v_cndmask_b32_e64 v61, v61, v230, s[86:87]
	v_cndmask_b32_e64 v62, v62, v230, s[0:1]
	v_cndmask_b32_e64 v63, v63, v230, s[2:3]
	v_sub_u32_e32 v150, 0x70, v200
	v_sub_u32_e32 v151, 0x71, v200
	v_sub_u32_e32 v152, 0x72, v200
	v_sub_u32_e32 v153, 0x73, v200
	v_cmp_lt_u32_e64 s[94:95], s91, v150
	v_cmp_lt_u32_e64 s[86:87], s91, v151
	v_cmp_lt_u32_e64 s[0:1], s91, v152
	v_cmp_lt_u32_e64 s[2:3], s91, v153
	v_cndmask_b32_e64 v64, v64, v230, s[94:95]
	v_cndmask_b32_e64 v65, v65, v230, s[86:87]
	v_cndmask_b32_e64 v66, v66, v230, s[0:1]
	v_cndmask_b32_e64 v67, v67, v230, s[2:3]
	v_sub_u32_e32 v150, 0x80, v200
	v_sub_u32_e32 v151, 0x81, v200
	v_sub_u32_e32 v152, 0x82, v200
	v_sub_u32_e32 v153, 0x83, v200
	v_cmp_lt_u32_e64 s[94:95], s91, v150
	v_cmp_lt_u32_e64 s[86:87], s91, v151
	v_cmp_lt_u32_e64 s[0:1], s91, v152
	v_cmp_lt_u32_e64 s[2:3], s91, v153
	v_cndmask_b32_e64 v68, v68, v230, s[94:95]
	v_cndmask_b32_e64 v69, v69, v230, s[86:87]
	v_cndmask_b32_e64 v70, v70, v230, s[0:1]
	v_cndmask_b32_e64 v71, v71, v230, s[2:3]
.Latt_noedge_2:
	s_nop 1
	v_max3_f32 v186, v36, v37, v38
	v_max3_f32 v186, v186, v39, v40
	v_max3_f32 v186, v186, v41, v42
	v_max3_f32 v186, v186, v43, v44
	v_max3_f32 v186, v186, v45, v46
	v_max3_f32 v186, v186, v47, v48
	v_max3_f32 v186, v186, v49, v50
	v_max3_f32 v186, v186, v51, v52
	v_max3_f32 v186, v186, v53, v54
	v_max3_f32 v186, v186, v55, v56
	v_max3_f32 v186, v186, v57, v58
	v_max3_f32 v186, v186, v59, v60
	v_max3_f32 v186, v186, v61, v62
	v_max3_f32 v186, v186, v63, v64
	v_max3_f32 v186, v186, v65, v66
	v_max3_f32 v186, v186, v67, v68
	v_max3_f32 v186, v186, v69, v70
	v_max_f32_e32 v186, v186, v71
	v_mov_b32_e32 v146, v186
	s_nop 1
	v_permlane16_swap_b32_e32 v186, v146
	v_max_f32_e32 v186, v186, v146
	v_mov_b32_e32 v146, v186
	s_nop 1
	v_permlane32_swap_b32_e32 v186, v146
	v_max_f32_e32 v186, v186, v146
	v_pk_add_f32 v[36:37], v[36:37], v[186:187] op_sel_hi:[1,0] neg_lo:[0,1] neg_hi:[0,1]
	v_pk_add_f32 v[38:39], v[38:39], v[186:187] op_sel_hi:[1,0] neg_lo:[0,1] neg_hi:[0,1]
	v_pk_add_f32 v[40:41], v[40:41], v[186:187] op_sel_hi:[1,0] neg_lo:[0,1] neg_hi:[0,1]
	v_pk_add_f32 v[42:43], v[42:43], v[186:187] op_sel_hi:[1,0] neg_lo:[0,1] neg_hi:[0,1]
	v_exp_f32_e32 v36, v36
	v_exp_f32_e32 v37, v37
	v_exp_f32_e32 v38, v38
	v_exp_f32_e32 v39, v39
	v_pk_add_f32 v[44:45], v[44:45], v[186:187] op_sel_hi:[1,0] neg_lo:[0,1] neg_hi:[0,1]
	v_pk_add_f32 v[46:47], v[46:47], v[186:187] op_sel_hi:[1,0] neg_lo:[0,1] neg_hi:[0,1]
	v_exp_f32_e32 v40, v40
	v_exp_f32_e32 v41, v41
	v_exp_f32_e32 v42, v42
	v_exp_f32_e32 v43, v43
	v_pk_add_f32 v[48:49], v[48:49], v[186:187] op_sel_hi:[1,0] neg_lo:[0,1] neg_hi:[0,1]
	v_pk_add_f32 v[50:51], v[50:51], v[186:187] op_sel_hi:[1,0] neg_lo:[0,1] neg_hi:[0,1]
	v_exp_f32_e32 v44, v44
	v_exp_f32_e32 v45, v45
	v_exp_f32_e32 v46, v46
	v_exp_f32_e32 v47, v47
	v_pk_add_f32 v[52:53], v[52:53], v[186:187] op_sel_hi:[1,0] neg_lo:[0,1] neg_hi:[0,1]
	v_pk_add_f32 v[54:55], v[54:55], v[186:187] op_sel_hi:[1,0] neg_lo:[0,1] neg_hi:[0,1]
	v_exp_f32_e32 v48, v48
	v_exp_f32_e32 v49, v49
	v_exp_f32_e32 v50, v50
	v_exp_f32_e32 v51, v51
	v_pk_add_f32 v[56:57], v[56:57], v[186:187] op_sel_hi:[1,0] neg_lo:[0,1] neg_hi:[0,1]
	v_pk_add_f32 v[58:59], v[58:59], v[186:187] op_sel_hi:[1,0] neg_lo:[0,1] neg_hi:[0,1]
	v_exp_f32_e32 v52, v52
	v_exp_f32_e32 v53, v53
	v_exp_f32_e32 v54, v54
	v_exp_f32_e32 v55, v55
	v_pk_add_f32 v[60:61], v[60:61], v[186:187] op_sel_hi:[1,0] neg_lo:[0,1] neg_hi:[0,1]
	v_pk_add_f32 v[62:63], v[62:63], v[186:187] op_sel_hi:[1,0] neg_lo:[0,1] neg_hi:[0,1]
	v_exp_f32_e32 v56, v56
	v_exp_f32_e32 v57, v57
	v_exp_f32_e32 v58, v58
	v_exp_f32_e32 v59, v59
	v_pk_add_f32 v[64:65], v[64:65], v[186:187] op_sel_hi:[1,0] neg_lo:[0,1] neg_hi:[0,1]
	v_pk_add_f32 v[66:67], v[66:67], v[186:187] op_sel_hi:[1,0] neg_lo:[0,1] neg_hi:[0,1]
	v_exp_f32_e32 v60, v60
	v_exp_f32_e32 v61, v61
	v_exp_f32_e32 v62, v62
	v_exp_f32_e32 v63, v63
	v_pk_add_f32 v[68:69], v[68:69], v[186:187] op_sel_hi:[1,0] neg_lo:[0,1] neg_hi:[0,1]
	v_pk_add_f32 v[70:71], v[70:71], v[186:187] op_sel_hi:[1,0] neg_lo:[0,1] neg_hi:[0,1]
	v_exp_f32_e32 v64, v64
	v_exp_f32_e32 v65, v65
	v_exp_f32_e32 v66, v66
	v_exp_f32_e32 v67, v67
	v_exp_f32_e32 v68, v68
	v_exp_f32_e32 v69, v69
	v_exp_f32_e32 v70, v70
	v_exp_f32_e32 v71, v71
	s_nop 0
	v_pk_add_f32 v[146:147], v[36:37], v[38:39]
	v_pk_add_f32 v[148:149], v[40:41], v[42:43]
	v_pk_add_f32 v[146:147], v[146:147], v[44:45]
	v_pk_add_f32 v[148:149], v[148:149], v[46:47]
	v_pk_add_f32 v[146:147], v[146:147], v[48:49]
	v_pk_add_f32 v[148:149], v[148:149], v[50:51]
	v_pk_add_f32 v[146:147], v[146:147], v[52:53]
	v_pk_add_f32 v[148:149], v[148:149], v[54:55]
	v_pk_add_f32 v[146:147], v[146:147], v[56:57]
	v_pk_add_f32 v[148:149], v[148:149], v[58:59]
	v_pk_add_f32 v[146:147], v[146:147], v[60:61]
	v_pk_add_f32 v[148:149], v[148:149], v[62:63]
	v_pk_add_f32 v[146:147], v[146:147], v[64:65]
	v_pk_add_f32 v[148:149], v[148:149], v[66:67]
	v_pk_add_f32 v[146:147], v[146:147], v[68:69]
	v_pk_add_f32 v[148:149], v[148:149], v[70:71]
	s_nop 0
	v_pk_add_f32 v[146:147], v[146:147], v[148:149]
	s_nop 0
	v_add_f32_e32 v187, v146, v147
	v_cvt_pk_bf16_f32 v36, v36, v37
	v_cvt_pk_bf16_f32 v37, v38, v39
	v_cvt_pk_bf16_f32 v40, v40, v41
	v_cvt_pk_bf16_f32 v41, v42, v43
	v_cvt_pk_bf16_f32 v44, v44, v45
	v_cvt_pk_bf16_f32 v45, v46, v47
	v_cvt_pk_bf16_f32 v48, v48, v49
	v_cvt_pk_bf16_f32 v49, v50, v51
	v_cvt_pk_bf16_f32 v52, v52, v53
	v_cvt_pk_bf16_f32 v53, v54, v55
	v_cvt_pk_bf16_f32 v56, v56, v57
	v_cvt_pk_bf16_f32 v57, v58, v59
	v_cvt_pk_bf16_f32 v60, v60, v61
	v_cvt_pk_bf16_f32 v61, v62, v63
	v_cvt_pk_bf16_f32 v64, v64, v65
	v_cvt_pk_bf16_f32 v65, v66, v67
	v_cvt_pk_bf16_f32 v68, v68, v69
	v_cvt_pk_bf16_f32 v69, v70, v71
	v_mov_b32_e32 v146, v187
	s_nop 1
	v_permlane16_swap_b32_e32 v187, v146
	v_add_f32_e32 v187, v187, v146
	v_mov_b32_e32 v146, v187
	s_nop 1
	v_permlane32_swap_b32_e32 v187, v146
	v_add_f32_e32 v187, v187, v146
	s_waitcnt lgkmcnt(0)
	s_add_i32 s93, s76, 16
	s_mov_b32 m0, s14
	v_add_u32_e32 v164, s93, v231
	v_med3_i32 v164, v164, 0, s40
	v_lshl_or_b32 v164, v164, 7, v222
	global_load_lds_dwordx4 v164, s[24:25]
	s_add_i32 m0, s14, 0x400
	v_add_u32_e32 v165, s93, v232
	v_med3_i32 v165, v165, 0, s40
	v_lshl_or_b32 v165, v165, 7, v222
	global_load_lds_dwordx4 v165, s[24:25]
	s_waitcnt vmcnt(8)
	v_add_u32_e32 v154, s15, v225
	v_add_u32_e32 v155, s15, v226
	v_add_u32_e32 v156, s15, v227
	v_add_u32_e32 v157, s15, v228
	ds_read_b64_tr_b16 v[202:203], v154
	ds_read_b64_tr_b16 v[204:205], v155
	ds_read_b64_tr_b16 v[206:207], v156
	ds_read_b64_tr_b16 v[208:209], v157
	v_mfma_f32_16x16x16_bf16 v[96:99], v[88:89], v[0:1], 0
	v_mfma_f32_16x16x16_bf16 v[100:103], v[90:91], v[0:1], 0
	v_mfma_f32_16x16x16_bf16 v[104:107], v[92:93], v[0:1], 0
	v_mfma_f32_16x16x16_bf16 v[108:111], v[94:95], v[0:1], 0
	s_waitcnt lgkmcnt(0)
	s_add_i32 s93, s76, 32
	s_mov_b32 m0, s15
	v_add_u32_e32 v164, s93, v231
	v_med3_i32 v164, v164, 0, s40
	v_lshl_or_b32 v164, v164, 7, v222
	global_load_lds_dwordx4 v164, s[24:25]
	s_add_i32 m0, s15, 0x400
	v_add_u32_e32 v165, s93, v232
	v_med3_i32 v165, v165, 0, s40
	v_lshl_or_b32 v165, v165, 7, v222
	global_load_lds_dwordx4 v165, s[24:25]
	s_waitcnt vmcnt(8)
	v_add_u32_e32 v154, s16, v225
	v_add_u32_e32 v155, s16, v226
	v_add_u32_e32 v156, s16, v227
	v_add_u32_e32 v157, s16, v228
	ds_read_b64_tr_b16 v[88:89], v154
	ds_read_b64_tr_b16 v[90:91], v155
	ds_read_b64_tr_b16 v[92:93], v156
	ds_read_b64_tr_b16 v[94:95], v157
	v_mfma_f32_16x16x16_bf16 v[96:99], v[202:203], v[4:5], v[96:99]
	v_mfma_f32_16x16x16_bf16 v[112:115], v[202:203], v[36:37], 0
	v_mfma_f32_16x16x16_bf16 v[100:103], v[204:205], v[4:5], v[100:103]
	v_mfma_f32_16x16x16_bf16 v[116:119], v[204:205], v[36:37], 0
	v_mfma_f32_16x16x16_bf16 v[104:107], v[206:207], v[4:5], v[104:107]
	v_mfma_f32_16x16x16_bf16 v[120:123], v[206:207], v[36:37], 0
	v_mfma_f32_16x16x16_bf16 v[108:111], v[208:209], v[4:5], v[108:111]
	v_mfma_f32_16x16x16_bf16 v[124:127], v[208:209], v[36:37], 0
	s_waitcnt lgkmcnt(0)
	s_add_i32 s93, s76, 48
	s_mov_b32 m0, s16
	v_add_u32_e32 v164, s93, v231
	v_med3_i32 v164, v164, 0, s40
	v_lshl_or_b32 v164, v164, 7, v222
	global_load_lds_dwordx4 v164, s[24:25]
	s_add_i32 m0, s16, 0x400
	v_add_u32_e32 v165, s93, v232
	v_med3_i32 v165, v165, 0, s40
	v_lshl_or_b32 v165, v165, 7, v222
	global_load_lds_dwordx4 v165, s[24:25]
	s_waitcnt vmcnt(8)
	v_add_u32_e32 v154, s12, v225
	v_add_u32_e32 v155, s12, v226
	v_add_u32_e32 v156, s12, v227
	v_add_u32_e32 v157, s12, v228
	ds_read_b64_tr_b16 v[202:203], v154
	ds_read_b64_tr_b16 v[204:205], v155
	ds_read_b64_tr_b16 v[206:207], v156
	ds_read_b64_tr_b16 v[208:209], v157
	v_mfma_f32_16x16x16_bf16 v[96:99], v[88:89], v[8:9], v[96:99]
	v_mfma_f32_16x16x16_bf16 v[112:115], v[88:89], v[40:41], v[112:115]
	v_mfma_f32_16x16x16_bf16 v[100:103], v[90:91], v[8:9], v[100:103]
	v_mfma_f32_16x16x16_bf16 v[116:119], v[90:91], v[40:41], v[116:119]
	v_mfma_f32_16x16x16_bf16 v[104:107], v[92:93], v[8:9], v[104:107]
	v_mfma_f32_16x16x16_bf16 v[120:123], v[92:93], v[40:41], v[120:123]
	v_mfma_f32_16x16x16_bf16 v[108:111], v[94:95], v[8:9], v[108:111]
	v_mfma_f32_16x16x16_bf16 v[124:127], v[94:95], v[40:41], v[124:127]
	s_waitcnt lgkmcnt(0)
	s_add_i32 s93, s76, 64
	s_mov_b32 m0, s12
	v_add_u32_e32 v164, s93, v231
	v_med3_i32 v164, v164, 0, s40
	v_lshl_or_b32 v164, v164, 7, v222
	global_load_lds_dwordx4 v164, s[24:25]
	s_add_i32 m0, s12, 0x400
	v_add_u32_e32 v165, s93, v232
	v_med3_i32 v165, v165, 0, s40
	v_lshl_or_b32 v165, v165, 7, v222
	global_load_lds_dwordx4 v165, s[24:25]
	s_waitcnt vmcnt(8)
	v_add_u32_e32 v154, s13, v225
	v_add_u32_e32 v155, s13, v226
	v_add_u32_e32 v156, s13, v227
	v_add_u32_e32 v157, s13, v228
	ds_read_b64_tr_b16 v[88:89], v154
	ds_read_b64_tr_b16 v[90:91], v155
	ds_read_b64_tr_b16 v[92:93], v156
	ds_read_b64_tr_b16 v[94:95], v157
	v_mfma_f32_16x16x16_bf16 v[96:99], v[202:203], v[12:13], v[96:99]
	v_mfma_f32_16x16x16_bf16 v[112:115], v[202:203], v[44:45], v[112:115]
	v_mfma_f32_16x16x16_bf16 v[100:103], v[204:205], v[12:13], v[100:103]
	v_mfma_f32_16x16x16_bf16 v[116:119], v[204:205], v[44:45], v[116:119]
	v_mfma_f32_16x16x16_bf16 v[104:107], v[206:207], v[12:13], v[104:107]
	v_mfma_f32_16x16x16_bf16 v[120:123], v[206:207], v[44:45], v[120:123]
	v_mfma_f32_16x16x16_bf16 v[108:111], v[208:209], v[12:13], v[108:111]
	v_mfma_f32_16x16x16_bf16 v[124:127], v[208:209], v[44:45], v[124:127]
	s_waitcnt lgkmcnt(0)
	s_add_i32 s93, s76, 0x50
	s_mov_b32 m0, s13
	v_add_u32_e32 v164, s93, v231
	v_med3_i32 v164, v164, 0, s40
	v_lshl_or_b32 v164, v164, 7, v222
	global_load_lds_dwordx4 v164, s[24:25]
	s_add_i32 m0, s13, 0x400
	v_add_u32_e32 v165, s93, v232
	v_med3_i32 v165, v165, 0, s40
	v_lshl_or_b32 v165, v165, 7, v222
	global_load_lds_dwordx4 v165, s[24:25]
	s_waitcnt vmcnt(8)
	v_add_u32_e32 v154, s14, v225
	v_add_u32_e32 v155, s14, v226
	v_add_u32_e32 v156, s14, v227
	v_add_u32_e32 v157, s14, v228
	ds_read_b64_tr_b16 v[202:203], v154
	ds_read_b64_tr_b16 v[204:205], v155
	ds_read_b64_tr_b16 v[206:207], v156
	ds_read_b64_tr_b16 v[208:209], v157
	v_mfma_f32_16x16x16_bf16 v[96:99], v[88:89], v[16:17], v[96:99]
	v_mfma_f32_16x16x16_bf16 v[112:115], v[88:89], v[48:49], v[112:115]
	v_mfma_f32_16x16x16_bf16 v[100:103], v[90:91], v[16:17], v[100:103]
	v_mfma_f32_16x16x16_bf16 v[116:119], v[90:91], v[48:49], v[116:119]
	v_mfma_f32_16x16x16_bf16 v[104:107], v[92:93], v[16:17], v[104:107]
	v_mfma_f32_16x16x16_bf16 v[120:123], v[92:93], v[48:49], v[120:123]
	v_mfma_f32_16x16x16_bf16 v[108:111], v[94:95], v[16:17], v[108:111]
	v_mfma_f32_16x16x16_bf16 v[124:127], v[94:95], v[48:49], v[124:127]
	s_waitcnt lgkmcnt(0)
	s_add_i32 s93, s79, 0
	s_mov_b32 m0, s14
	v_add_u32_e32 v164, s93, v162
	v_lshl_or_b32 v164, v164, 7, v220
	global_load_lds_dwordx4 v164, s[18:19]
	s_add_i32 m0, s14, 0x400
	v_add_u32_e32 v165, s93, v163
	v_lshl_or_b32 v165, v165, 7, v221
	global_load_lds_dwordx4 v165, s[18:19]
	s_waitcnt vmcnt(8)
	v_add_u32_e32 v154, s15, v225
	v_add_u32_e32 v155, s15, v226
	v_add_u32_e32 v156, s15, v227
	v_add_u32_e32 v157, s15, v228
	ds_read_b64_tr_b16 v[88:89], v154
	ds_read_b64_tr_b16 v[90:91], v155
	ds_read_b64_tr_b16 v[92:93], v156
	ds_read_b64_tr_b16 v[94:95], v157
	v_mfma_f32_16x16x16_bf16 v[96:99], v[202:203], v[20:21], v[96:99]
	v_mfma_f32_16x16x16_bf16 v[112:115], v[202:203], v[52:53], v[112:115]
	v_mfma_f32_16x16x16_bf16 v[100:103], v[204:205], v[20:21], v[100:103]
	v_mfma_f32_16x16x16_bf16 v[116:119], v[204:205], v[52:53], v[116:119]
	v_mfma_f32_16x16x16_bf16 v[104:107], v[206:207], v[20:21], v[104:107]
	v_mfma_f32_16x16x16_bf16 v[120:123], v[206:207], v[52:53], v[120:123]
	v_mfma_f32_16x16x16_bf16 v[108:111], v[208:209], v[20:21], v[108:111]
	v_mfma_f32_16x16x16_bf16 v[124:127], v[208:209], v[52:53], v[124:127]
	s_waitcnt lgkmcnt(0)
	s_add_i32 s93, s79, 64
	s_mov_b32 m0, s15
	v_add_u32_e32 v164, s93, v162
	v_lshl_or_b32 v164, v164, 7, v220
	global_load_lds_dwordx4 v164, s[18:19]
	s_add_i32 m0, s15, 0x400
	v_add_u32_e32 v165, s93, v163
	v_lshl_or_b32 v165, v165, 7, v221
	global_load_lds_dwordx4 v165, s[18:19]
	s_waitcnt vmcnt(8)
	v_add_u32_e32 v154, s16, v225
	v_add_u32_e32 v155, s16, v226
	v_add_u32_e32 v156, s16, v227
	v_add_u32_e32 v157, s16, v228
	ds_read_b64_tr_b16 v[202:203], v154
	ds_read_b64_tr_b16 v[204:205], v155
	ds_read_b64_tr_b16 v[206:207], v156
	ds_read_b64_tr_b16 v[208:209], v157
	v_mfma_f32_16x16x16_bf16 v[96:99], v[88:89], v[24:25], v[96:99]
	v_mfma_f32_16x16x16_bf16 v[112:115], v[88:89], v[56:57], v[112:115]
	v_mfma_f32_16x16x16_bf16 v[100:103], v[90:91], v[24:25], v[100:103]
	v_mfma_f32_16x16x16_bf16 v[116:119], v[90:91], v[56:57], v[116:119]
	v_mfma_f32_16x16x16_bf16 v[104:107], v[92:93], v[24:25], v[104:107]
	v_mfma_f32_16x16x16_bf16 v[120:123], v[92:93], v[56:57], v[120:123]
	v_mfma_f32_16x16x16_bf16 v[108:111], v[94:95], v[24:25], v[108:111]
	v_mfma_f32_16x16x16_bf16 v[124:127], v[94:95], v[56:57], v[124:127]
	s_waitcnt lgkmcnt(0)
	s_add_i32 s93, s79, 0xffffff00
	s_mov_b32 m0, s16
	v_add_u32_e32 v164, s93, v162
	v_med3_i32 v164, v164, 0, s40
	v_lshl_or_b32 v164, v164, 7, v220
	global_load_lds_dwordx4 v164, s[20:21]
	s_add_i32 m0, s16, 0x400
	v_add_u32_e32 v165, s93, v163
	v_med3_i32 v165, v165, 0, s40
	v_lshl_or_b32 v165, v165, 7, v221
	global_load_lds_dwordx4 v165, s[20:21]
	s_waitcnt vmcnt(8)
	v_add_u32_e32 v154, s12, v225
	v_add_u32_e32 v155, s12, v226
	v_add_u32_e32 v156, s12, v227
	v_add_u32_e32 v157, s12, v228
	ds_read_b64_tr_b16 v[88:89], v154
	ds_read_b64_tr_b16 v[90:91], v155
	ds_read_b64_tr_b16 v[92:93], v156
	ds_read_b64_tr_b16 v[94:95], v157
	v_mfma_f32_16x16x16_bf16 v[96:99], v[202:203], v[28:29], v[96:99]
	v_mfma_f32_16x16x16_bf16 v[112:115], v[202:203], v[60:61], v[112:115]
	v_mfma_f32_16x16x16_bf16 v[100:103], v[204:205], v[28:29], v[100:103]
	v_mfma_f32_16x16x16_bf16 v[116:119], v[204:205], v[60:61], v[116:119]
	v_mfma_f32_16x16x16_bf16 v[104:107], v[206:207], v[28:29], v[104:107]
	v_mfma_f32_16x16x16_bf16 v[120:123], v[206:207], v[60:61], v[120:123]
	v_mfma_f32_16x16x16_bf16 v[108:111], v[208:209], v[28:29], v[108:111]
	v_mfma_f32_16x16x16_bf16 v[124:127], v[208:209], v[60:61], v[124:127]
	s_waitcnt lgkmcnt(0)
	s_add_i32 s93, s79, 0xffffff40
	s_mov_b32 m0, s12
	v_add_u32_e32 v164, s93, v162
	v_med3_i32 v164, v164, 0, s40
	v_lshl_or_b32 v164, v164, 7, v220
	global_load_lds_dwordx4 v164, s[20:21]
	s_add_i32 m0, s12, 0x400
	v_add_u32_e32 v165, s93, v163
	v_med3_i32 v165, v165, 0, s40
	v_lshl_or_b32 v165, v165, 7, v221
	global_load_lds_dwordx4 v165, s[20:21]
	s_waitcnt vmcnt(8)
	v_add_u32_e32 v154, s13, v225
	v_add_u32_e32 v155, s13, v226
	v_add_u32_e32 v156, s13, v227
	v_add_u32_e32 v157, s13, v228
	ds_read_b64_tr_b16 v[202:203], v154
	ds_read_b64_tr_b16 v[204:205], v155
	ds_read_b64_tr_b16 v[206:207], v156
	ds_read_b64_tr_b16 v[208:209], v157
	v_mfma_f32_16x16x16_bf16 v[96:99], v[88:89], v[32:33], v[96:99]
	v_mfma_f32_16x16x16_bf16 v[112:115], v[88:89], v[64:65], v[112:115]
	v_mfma_f32_16x16x16_bf16 v[100:103], v[90:91], v[32:33], v[100:103]
	v_mfma_f32_16x16x16_bf16 v[116:119], v[90:91], v[64:65], v[116:119]
	v_mfma_f32_16x16x16_bf16 v[104:107], v[92:93], v[32:33], v[104:107]
	v_mfma_f32_16x16x16_bf16 v[120:123], v[92:93], v[64:65], v[120:123]
	v_mfma_f32_16x16x16_bf16 v[108:111], v[94:95], v[32:33], v[108:111]
	v_mfma_f32_16x16x16_bf16 v[124:127], v[94:95], v[64:65], v[124:127]
	s_waitcnt lgkmcnt(0)
	s_add_i32 s93, s79, 0xffffff80
	s_mov_b32 m0, s13
	v_add_u32_e32 v164, s93, v162
	v_med3_i32 v164, v164, 0, s40
	v_lshl_or_b32 v164, v164, 7, v220
	global_load_lds_dwordx4 v164, s[20:21]
	s_add_i32 m0, s13, 0x400
	v_add_u32_e32 v165, s93, v163
	v_med3_i32 v165, v165, 0, s40
	v_lshl_or_b32 v165, v165, 7, v221
	global_load_lds_dwordx4 v165, s[20:21]
	v_mfma_f32_16x16x16_bf16 v[112:115], v[202:203], v[68:69], v[112:115]
	v_mfma_f32_16x16x16_bf16 v[116:119], v[204:205], v[68:69], v[116:119]
	v_mfma_f32_16x16x16_bf16 v[120:123], v[206:207], v[68:69], v[120:123]
	v_mfma_f32_16x16x16_bf16 v[124:127], v[208:209], v[68:69], v[124:127]
	s_and_saveexec_b64 s[80:81], s[74:75]
	ds_write_b64 v194, v[184:185]
	s_mov_b64 exec, s[80:81]
	ds_write_b128 v190, v[96:99]
	ds_write_b128 v191, v[100:103]
	ds_write_b128 v192, v[104:107]
	ds_write_b128 v193, v[108:111]
	s_and_saveexec_b64 s[80:81], s[74:75]
	ds_write_b64 v199, v[186:187]
	s_mov_b64 exec, s[80:81]
	ds_write_b128 v195, v[112:115]
	ds_write_b128 v196, v[116:119]
	ds_write_b128 v197, v[120:123]
	ds_write_b128 v198, v[124:127]
	s_waitcnt lgkmcnt(0)
	s_barrier
	s_add_i32 s76, s38, s83
	s_add_i32 s79, s38, s84
	v_lshlrev_b32_e32 v231, 2, v218
	v_add_u32_e32 v232, 8, v218
	v_lshlrev_b32_e32 v232, 2, v232
	v_lshlrev_b32_e32 v162, 4, v218
	v_add_u32_e32 v163, 8, v218
	v_lshlrev_b32_e32 v163, 4, v163
	s_waitcnt vmcnt(8)
	v_add_u32_e32 v154, s14, v223
	v_add_u32_e32 v155, s14, v224
	ds_read_b128 v[72:75], v154
	ds_read_b128 v[76:79], v155
	s_waitcnt lgkmcnt(0)
	s_add_i32 s93, s76, 0xffffffc0
	s_mov_b32 m0, s14
	v_add_u32_e32 v164, s93, v231
	v_med3_i32 v164, v164, 0, s40
	v_lshl_or_b32 v164, v164, 7, v220
	global_load_lds_dwordx4 v164, s[20:21]
	s_add_i32 m0, s14, 0x400
	v_add_u32_e32 v165, s93, v232
	v_med3_i32 v165, v165, 0, s40
	v_lshl_or_b32 v165, v165, 7, v221
	global_load_lds_dwordx4 v165, s[20:21]
	s_waitcnt vmcnt(8)
	v_add_u32_e32 v154, s15, v223
	v_add_u32_e32 v155, s15, v224
	ds_read_b128 v[80:83], v154
	ds_read_b128 v[84:87], v155
	s_waitcnt lgkmcnt(0)
	s_add_i32 s93, s76, 0
	s_mov_b32 m0, s15
	v_add_u32_e32 v164, s93, v231
	v_med3_i32 v164, v164, 0, s40
	v_lshl_or_b32 v164, v164, 7, v220
	global_load_lds_dwordx4 v164, s[20:21]
	s_add_i32 m0, s15, 0x400
	v_add_u32_e32 v165, s93, v232
	v_med3_i32 v165, v165, 0, s40
	v_lshl_or_b32 v165, v165, 7, v221
	global_load_lds_dwordx4 v165, s[20:21]
	s_waitcnt vmcnt(8)
	v_add_u32_e32 v154, s16, v223
	v_add_u32_e32 v155, s16, v224
	ds_read_b128 v[88:91], v154
	ds_read_b128 v[92:95], v155
	s_waitcnt lgkmcnt(0)
	s_add_i32 s93, s76, 64
	s_mov_b32 m0, s16
	v_add_u32_e32 v164, s93, v231
	v_med3_i32 v164, v164, 0, s40
	v_lshl_or_b32 v164, v164, 7, v220
	global_load_lds_dwordx4 v164, s[20:21]
	s_add_i32 m0, s16, 0x400
	v_add_u32_e32 v165, s93, v232
	v_med3_i32 v165, v165, 0, s40
	v_lshl_or_b32 v165, v165, 7, v221
	global_load_lds_dwordx4 v165, s[20:21]
	s_waitcnt vmcnt(8)
	v_add_u32_e32 v154, s12, v223
	v_add_u32_e32 v155, s12, v224
	ds_read_b128 v[202:205], v154
	ds_read_b128 v[206:209], v155
	v_mfma_f32_16x16x32_bf16 v[0:3], v[88:91], v[72:75], 0
	v_mfma_f32_16x16x32_bf16 v[0:3], v[92:95], v[76:79], v[0:3]
	s_waitcnt lgkmcnt(0)
	s_add_i32 s93, s76, 0x80
	s_mov_b32 m0, s12
	v_add_u32_e32 v164, s93, v231
	v_med3_i32 v164, v164, 0, s40
	v_lshl_or_b32 v164, v164, 7, v220
	global_load_lds_dwordx4 v164, s[20:21]
	s_add_i32 m0, s12, 0x400
	v_add_u32_e32 v165, s93, v232
	v_med3_i32 v165, v165, 0, s40
	v_lshl_or_b32 v165, v165, 7, v221
	global_load_lds_dwordx4 v165, s[20:21]
	s_waitcnt vmcnt(8)
	v_add_u32_e32 v154, s13, v223
	v_add_u32_e32 v155, s13, v224
	ds_read_b128 v[88:91], v154
	ds_read_b128 v[92:95], v155
	v_mfma_f32_16x16x32_bf16 v[4:7], v[202:205], v[72:75], 0
	v_mfma_f32_16x16x32_bf16 v[36:39], v[202:205], v[80:83], 0
	v_mfma_f32_16x16x32_bf16 v[4:7], v[206:209], v[76:79], v[4:7]
	v_mfma_f32_16x16x32_bf16 v[36:39], v[206:209], v[84:87], v[36:39]
	s_waitcnt lgkmcnt(0)
	s_add_i32 s93, s76, 0xc0
	s_mov_b32 m0, s13
	v_add_u32_e32 v164, s93, v231
	v_med3_i32 v164, v164, 0, s40
	v_lshl_or_b32 v164, v164, 7, v220
	global_load_lds_dwordx4 v164, s[20:21]
	s_add_i32 m0, s13, 0x400
	v_add_u32_e32 v165, s93, v232
	v_med3_i32 v165, v165, 0, s40
	v_lshl_or_b32 v165, v165, 7, v221
	global_load_lds_dwordx4 v165, s[20:21]
	s_waitcnt vmcnt(8)
	v_add_u32_e32 v154, s14, v223
	v_add_u32_e32 v155, s14, v224
	ds_read_b128 v[202:205], v154
	ds_read_b128 v[206:209], v155
	v_mfma_f32_16x16x32_bf16 v[8:11], v[88:91], v[72:75], 0
	v_mfma_f32_16x16x32_bf16 v[40:43], v[88:91], v[80:83], 0
	v_mfma_f32_16x16x32_bf16 v[8:11], v[92:95], v[76:79], v[8:11]
	v_mfma_f32_16x16x32_bf16 v[40:43], v[92:95], v[84:87], v[40:43]
	s_waitcnt lgkmcnt(0)
	s_add_i32 s93, s76, 0x100
	s_mov_b32 m0, s14
	v_add_u32_e32 v164, s93, v231
	v_med3_i32 v164, v164, 0, s40
	v_lshl_or_b32 v164, v164, 7, v220
	global_load_lds_dwordx4 v164, s[20:21]
	s_add_i32 m0, s14, 0x400
	v_add_u32_e32 v165, s93, v232
	v_med3_i32 v165, v165, 0, s40
	v_lshl_or_b32 v165, v165, 7, v221
	global_load_lds_dwordx4 v165, s[20:21]
	s_waitcnt vmcnt(8)
	v_add_u32_e32 v154, s15, v223
	v_add_u32_e32 v155, s15, v224
	ds_read_b128 v[88:91], v154
	ds_read_b128 v[92:95], v155
	v_mfma_f32_16x16x32_bf16 v[12:15], v[202:205], v[72:75], 0
	v_mfma_f32_16x16x32_bf16 v[44:47], v[202:205], v[80:83], 0
	v_mfma_f32_16x16x32_bf16 v[12:15], v[206:209], v[76:79], v[12:15]
	v_mfma_f32_16x16x32_bf16 v[44:47], v[206:209], v[84:87], v[44:47]
	s_waitcnt lgkmcnt(0)
	s_add_i32 s93, s76, 0x140
	s_mov_b32 m0, s15
	v_add_u32_e32 v164, s93, v231
	v_med3_i32 v164, v164, 0, s40
	v_lshl_or_b32 v164, v164, 7, v220
	global_load_lds_dwordx4 v164, s[20:21]
	s_add_i32 m0, s15, 0x400
	v_add_u32_e32 v165, s93, v232
	v_med3_i32 v165, v165, 0, s40
	v_lshl_or_b32 v165, v165, 7, v221
	global_load_lds_dwordx4 v165, s[20:21]
	s_waitcnt vmcnt(8)
	v_add_u32_e32 v154, s16, v223
	v_add_u32_e32 v155, s16, v224
	ds_read_b128 v[202:205], v154
	ds_read_b128 v[206:209], v155
	v_mfma_f32_16x16x32_bf16 v[16:19], v[88:91], v[72:75], 0
	v_mfma_f32_16x16x32_bf16 v[48:51], v[88:91], v[80:83], 0
	v_mfma_f32_16x16x32_bf16 v[16:19], v[92:95], v[76:79], v[16:19]
	v_mfma_f32_16x16x32_bf16 v[48:51], v[92:95], v[84:87], v[48:51]
	s_waitcnt lgkmcnt(0)
	s_add_i32 s93, s76, 0xffffff00
	s_mov_b32 m0, s16
	v_add_u32_e32 v164, s93, v231
	v_med3_i32 v164, v164, 0, s40
	v_lshl_or_b32 v164, v164, 7, v222
	global_load_lds_dwordx4 v164, s[24:25]
	s_add_i32 m0, s16, 0x400
	v_add_u32_e32 v165, s93, v232
	v_med3_i32 v165, v165, 0, s40
	v_lshl_or_b32 v165, v165, 7, v222
	global_load_lds_dwordx4 v165, s[24:25]
	s_waitcnt vmcnt(8)
	v_add_u32_e32 v154, s12, v223
	v_add_u32_e32 v155, s12, v224
	ds_read_b128 v[88:91], v154
	ds_read_b128 v[92:95], v155
	v_mfma_f32_16x16x32_bf16 v[20:23], v[202:205], v[72:75], 0
	v_mfma_f32_16x16x32_bf16 v[52:55], v[202:205], v[80:83], 0
	v_mfma_f32_16x16x32_bf16 v[20:23], v[206:209], v[76:79], v[20:23]
	v_mfma_f32_16x16x32_bf16 v[52:55], v[206:209], v[84:87], v[52:55]
	s_waitcnt lgkmcnt(0)
	s_add_i32 s93, s76, 0xffffff40
	s_mov_b32 m0, s12
	v_add_u32_e32 v164, s93, v231
	v_med3_i32 v164, v164, 0, s40
	v_lshl_or_b32 v164, v164, 7, v222
	global_load_lds_dwordx4 v164, s[24:25]
	s_add_i32 m0, s12, 0x400
	v_add_u32_e32 v165, s93, v232
	v_med3_i32 v165, v165, 0, s40
	v_lshl_or_b32 v165, v165, 7, v222
	global_load_lds_dwordx4 v165, s[24:25]
	s_waitcnt vmcnt(8)
	v_add_u32_e32 v154, s13, v223
	v_add_u32_e32 v155, s13, v224
	ds_read_b128 v[202:205], v154
	ds_read_b128 v[206:209], v155
	v_mfma_f32_16x16x32_bf16 v[24:27], v[88:91], v[72:75], 0
	v_mfma_f32_16x16x32_bf16 v[56:59], v[88:91], v[80:83], 0
	v_mfma_f32_16x16x32_bf16 v[24:27], v[92:95], v[76:79], v[24:27]
	v_mfma_f32_16x16x32_bf16 v[56:59], v[92:95], v[84:87], v[56:59]
	s_waitcnt lgkmcnt(0)
	s_add_i32 s93, s76, 0xffffff80
	s_mov_b32 m0, s13
	v_add_u32_e32 v164, s93, v231
	v_med3_i32 v164, v164, 0, s40
	v_lshl_or_b32 v164, v164, 7, v222
	global_load_lds_dwordx4 v164, s[24:25]
	s_add_i32 m0, s13, 0x400
	v_add_u32_e32 v165, s93, v232
	v_med3_i32 v165, v165, 0, s40
	v_lshl_or_b32 v165, v165, 7, v222
	global_load_lds_dwordx4 v165, s[24:25]
	s_waitcnt vmcnt(8)
	v_add_u32_e32 v154, s14, v223
	v_add_u32_e32 v155, s14, v224
	ds_read_b128 v[88:91], v154
	ds_read_b128 v[92:95], v155
	v_mfma_f32_16x16x32_bf16 v[28:31], v[202:205], v[72:75], 0
	v_mfma_f32_16x16x32_bf16 v[60:63], v[202:205], v[80:83], 0
	v_mfma_f32_16x16x32_bf16 v[28:31], v[206:209], v[76:79], v[28:31]
	v_mfma_f32_16x16x32_bf16 v[60:63], v[206:209], v[84:87], v[60:63]
	s_waitcnt lgkmcnt(0)
	s_add_i32 s93, s76, 0xffffffc0
	s_mov_b32 m0, s14
	v_add_u32_e32 v164, s93, v231
	v_med3_i32 v164, v164, 0, s40
	v_lshl_or_b32 v164, v164, 7, v222
	global_load_lds_dwordx4 v164, s[24:25]
	s_add_i32 m0, s14, 0x400
	v_add_u32_e32 v165, s93, v232
	v_med3_i32 v165, v165, 0, s40
	v_lshl_or_b32 v165, v165, 7, v222
	global_load_lds_dwordx4 v165, s[24:25]
	s_waitcnt vmcnt(8)
	v_add_u32_e32 v154, s15, v223
	v_add_u32_e32 v155, s15, v224
	ds_read_b128 v[202:205], v154
	ds_read_b128 v[206:209], v155
	v_mfma_f32_16x16x32_bf16 v[32:35], v[88:91], v[72:75], 0
	v_mfma_f32_16x16x32_bf16 v[64:67], v[88:91], v[80:83], 0
	v_mfma_f32_16x16x32_bf16 v[32:35], v[92:95], v[76:79], v[32:35]
	v_mfma_f32_16x16x32_bf16 v[64:67], v[92:95], v[84:87], v[64:67]
	s_waitcnt lgkmcnt(0)
	s_add_i32 s93, s76, 0
	s_mov_b32 m0, s15
	v_add_u32_e32 v164, s93, v231
	v_med3_i32 v164, v164, 0, s40
	v_lshl_or_b32 v164, v164, 7, v222
	global_load_lds_dwordx4 v164, s[24:25]
	s_add_i32 m0, s15, 0x400
	v_add_u32_e32 v165, s93, v232
	v_med3_i32 v165, v165, 0, s40
	v_lshl_or_b32 v165, v165, 7, v222
	global_load_lds_dwordx4 v165, s[24:25]
	s_waitcnt vmcnt(8)
	v_add_u32_e32 v154, s16, v225
	v_add_u32_e32 v155, s16, v226
	v_add_u32_e32 v156, s16, v227
	v_add_u32_e32 v157, s16, v228
	ds_read_b64_tr_b16 v[88:89], v154
	ds_read_b64_tr_b16 v[90:91], v155
	ds_read_b64_tr_b16 v[92:93], v156
	ds_read_b64_tr_b16 v[94:95], v157
	v_mfma_f32_16x16x32_bf16 v[68:71], v[202:205], v[80:83], 0
	v_mfma_f32_16x16x32_bf16 v[68:71], v[206:209], v[84:87], v[68:71]
	v_mov_b32_e32 v188, s83
	v_lshl_add_u32 v188, v216, 2, v188
	v_lshrrev_b32_e32 v146, 4, v188
	v_xor_b32_e32 v146, v146, v188
	v_and_b32_e32 v146, 15, v146
	v_lshlrev_b32_e32 v147, 8, v188
	v_or_b32_e32 v148, 0, v217
	v_xor_b32_e32 v148, v148, v146
	v_lshl_add_u32 v190, v148, 4, v147
	v_or_b32_e32 v148, 4, v217
	v_xor_b32_e32 v148, v148, v146
	v_lshl_add_u32 v191, v148, 4, v147
	v_or_b32_e32 v148, 8, v217
	v_xor_b32_e32 v148, v148, v146
	v_lshl_add_u32 v192, v148, 4, v147
	v_or_b32_e32 v148, 12, v217
	v_xor_b32_e32 v148, v148, v146
	v_lshl_add_u32 v193, v148, 4, v147
	v_lshlrev_b32_e32 v194, 3, v188
	v_add_u32_e32 v194, 0x10000, v194
	ds_read_b64 v[144:145], v194
	ds_read_b128 v[128:131], v190
	ds_read_b128 v[132:135], v191
	ds_read_b128 v[136:139], v192
	ds_read_b128 v[140:143], v193
	v_mov_b32_e32 v189, s83
	v_lshl_add_u32 v189, v216, 2, v189
	v_add_u32_e32 v189, 64, v189
	v_lshrrev_b32_e32 v146, 4, v189
	v_xor_b32_e32 v146, v146, v189
	v_and_b32_e32 v146, 15, v146
	v_lshlrev_b32_e32 v147, 8, v189
	v_or_b32_e32 v148, 0, v217
	v_xor_b32_e32 v148, v148, v146
	v_lshl_add_u32 v195, v148, 4, v147
	v_or_b32_e32 v148, 4, v217
	v_xor_b32_e32 v148, v148, v146
	v_lshl_add_u32 v196, v148, 4, v147
	v_or_b32_e32 v148, 8, v217
	v_xor_b32_e32 v148, v148, v146
	v_lshl_add_u32 v197, v148, 4, v147
	v_or_b32_e32 v148, 12, v217
	v_xor_b32_e32 v148, v148, v146
	v_lshl_add_u32 v198, v148, 4, v147
	v_lshlrev_b32_e32 v199, 3, v189
	v_add_u32_e32 v199, 0x10000, v199
	ds_read_b64 v[182:183], v199
	ds_read_b128 v[166:169], v195
	ds_read_b128 v[170:173], v196
	ds_read_b128 v[174:177], v197
	ds_read_b128 v[178:181], v198
	s_add_i32 s90, s76, 0x17c
	s_cmp_gt_i32 s90, s40
	s_cselect_b32 s96, 1, 0
	s_cmp_lt_i32 s76, 0x100
	s_cselect_b32 s96, 1, s96
	s_ashr_i32 s77, s76, 2
	s_sub_i32 s77, 64, s77
	s_sub_i32 s78, s40, s76
	s_ashr_i32 s78, s78, 2
	s_add_i32 s78, s78, 64
	v_cndmask_b32_e64 v0, v0, v230, s[52:53]
	v_cndmask_b32_e64 v32, v32, v230, s[62:63]
	v_cndmask_b32_e64 v1, v1, v230, s[56:57]
	v_cndmask_b32_e64 v33, v33, v230, s[64:65]
	v_cndmask_b32_e64 v2, v2, v230, s[58:59]
	v_cndmask_b32_e64 v34, v34, v230, s[70:71]
	v_cndmask_b32_e64 v3, v3, v230, s[60:61]
	v_cndmask_b32_e64 v35, v35, v230, s[72:73]
	s_cmp_eq_u32 s96, 0
	s_cbranch_scc1 .Latt_noedge_3
	v_sub_u32_e32 v200, s77, v229
	s_sub_i32 s91, s78, s77
	v_sub_u32_e32 v150, 0, v200
	v_sub_u32_e32 v151, 1, v200
	v_sub_u32_e32 v152, 2, v200
	v_sub_u32_e32 v153, 3, v200
	v_cmp_lt_u32_e64 s[94:95], s91, v150
	v_cmp_lt_u32_e64 s[86:87], s91, v151
	v_cmp_lt_u32_e64 s[0:1], s91, v152
	v_cmp_lt_u32_e64 s[2:3], s91, v153
	v_cndmask_b32_e64 v0, v0, v230, s[94:95]
	v_cndmask_b32_e64 v1, v1, v230, s[86:87]
	v_cndmask_b32_e64 v2, v2, v230, s[0:1]
	v_cndmask_b32_e64 v3, v3, v230, s[2:3]
	v_sub_u32_e32 v150, 16, v200
	v_sub_u32_e32 v151, 17, v200
	v_sub_u32_e32 v152, 18, v200
	v_sub_u32_e32 v153, 19, v200
	v_cmp_lt_u32_e64 s[94:95], s91, v150
	v_cmp_lt_u32_e64 s[86:87], s91, v151
	v_cmp_lt_u32_e64 s[0:1], s91, v152
	v_cmp_lt_u32_e64 s[2:3], s91, v153
	v_cndmask_b32_e64 v4, v4, v230, s[94:95]
	v_cndmask_b32_e64 v5, v5, v230, s[86:87]
	v_cndmask_b32_e64 v6, v6, v230, s[0:1]
	v_cndmask_b32_e64 v7, v7, v230, s[2:3]
	v_sub_u32_e32 v150, 32, v200
	v_sub_u32_e32 v151, 33, v200
	v_sub_u32_e32 v152, 34, v200
	v_sub_u32_e32 v153, 35, v200
	v_cmp_lt_u32_e64 s[94:95], s91, v150
	v_cmp_lt_u32_e64 s[86:87], s91, v151
	v_cmp_lt_u32_e64 s[0:1], s91, v152
	v_cmp_lt_u32_e64 s[2:3], s91, v153
	v_cndmask_b32_e64 v8, v8, v230, s[94:95]
	v_cndmask_b32_e64 v9, v9, v230, s[86:87]
	v_cndmask_b32_e64 v10, v10, v230, s[0:1]
	v_cndmask_b32_e64 v11, v11, v230, s[2:3]
	v_sub_u32_e32 v150, 48, v200
	v_sub_u32_e32 v151, 49, v200
	v_sub_u32_e32 v152, 50, v200
	v_sub_u32_e32 v153, 51, v200
	v_cmp_lt_u32_e64 s[94:95], s91, v150
	v_cmp_lt_u32_e64 s[86:87], s91, v151
	v_cmp_lt_u32_e64 s[0:1], s91, v152
	v_cmp_lt_u32_e64 s[2:3], s91, v153
	v_cndmask_b32_e64 v12, v12, v230, s[94:95]
	v_cndmask_b32_e64 v13, v13, v230, s[86:87]
	v_cndmask_b32_e64 v14, v14, v230, s[0:1]
	v_cndmask_b32_e64 v15, v15, v230, s[2:3]
	v_sub_u32_e32 v150, 64, v200
	v_sub_u32_e32 v151, 0x41, v200
	v_sub_u32_e32 v152, 0x42, v200
	v_sub_u32_e32 v153, 0x43, v200
	v_cmp_lt_u32_e64 s[94:95], s91, v150
	v_cmp_lt_u32_e64 s[86:87], s91, v151
	v_cmp_lt_u32_e64 s[0:1], s91, v152
	v_cmp_lt_u32_e64 s[2:3], s91, v153
	v_cndmask_b32_e64 v16, v16, v230, s[94:95]
	v_cndmask_b32_e64 v17, v17, v230, s[86:87]
	v_cndmask_b32_e64 v18, v18, v230, s[0:1]
	v_cndmask_b32_e64 v19, v19, v230, s[2:3]
	v_sub_u32_e32 v150, 0x50, v200
	v_sub_u32_e32 v151, 0x51, v200
	v_sub_u32_e32 v152, 0x52, v200
	v_sub_u32_e32 v153, 0x53, v200
	v_cmp_lt_u32_e64 s[94:95], s91, v150
	v_cmp_lt_u32_e64 s[86:87], s91, v151
	v_cmp_lt_u32_e64 s[0:1], s91, v152
	v_cmp_lt_u32_e64 s[2:3], s91, v153
	v_cndmask_b32_e64 v20, v20, v230, s[94:95]
	v_cndmask_b32_e64 v21, v21, v230, s[86:87]
	v_cndmask_b32_e64 v22, v22, v230, s[0:1]
	v_cndmask_b32_e64 v23, v23, v230, s[2:3]
	v_sub_u32_e32 v150, 0x60, v200
	v_sub_u32_e32 v151, 0x61, v200
	v_sub_u32_e32 v152, 0x62, v200
	v_sub_u32_e32 v153, 0x63, v200
	v_cmp_lt_u32_e64 s[94:95], s91, v150
	v_cmp_lt_u32_e64 s[86:87], s91, v151
	v_cmp_lt_u32_e64 s[0:1], s91, v152
	v_cmp_lt_u32_e64 s[2:3], s91, v153
	v_cndmask_b32_e64 v24, v24, v230, s[94:95]
	v_cndmask_b32_e64 v25, v25, v230, s[86:87]
	v_cndmask_b32_e64 v26, v26, v230, s[0:1]
	v_cndmask_b32_e64 v27, v27, v230, s[2:3]
	v_sub_u32_e32 v150, 0x70, v200
	v_sub_u32_e32 v151, 0x71, v200
	v_sub_u32_e32 v152, 0x72, v200
	v_sub_u32_e32 v153, 0x73, v200
	v_cmp_lt_u32_e64 s[94:95], s91, v150
	v_cmp_lt_u32_e64 s[86:87], s91, v151
	v_cmp_lt_u32_e64 s[0:1], s91, v152
	v_cmp_lt_u32_e64 s[2:3], s91, v153
	v_cndmask_b32_e64 v28, v28, v230, s[94:95]
	v_cndmask_b32_e64 v29, v29, v230, s[86:87]
	v_cndmask_b32_e64 v30, v30, v230, s[0:1]
	v_cndmask_b32_e64 v31, v31, v230, s[2:3]
	v_sub_u32_e32 v150, 0x80, v200
	v_sub_u32_e32 v151, 0x81, v200
	v_sub_u32_e32 v152, 0x82, v200
	v_sub_u32_e32 v153, 0x83, v200
	v_cmp_lt_u32_e64 s[94:95], s91, v150
	v_cmp_lt_u32_e64 s[86:87], s91, v151
	v_cmp_lt_u32_e64 s[0:1], s91, v152
	v_cmp_lt_u32_e64 s[2:3], s91, v153
	v_cndmask_b32_e64 v32, v32, v230, s[94:95]
	v_cndmask_b32_e64 v33, v33, v230, s[86:87]
	v_cndmask_b32_e64 v34, v34, v230, s[0:1]
	v_cndmask_b32_e64 v35, v35, v230, s[2:3]

.Latt_noedge_4:
	s_nop 1
	v_max3_f32 v186, v36, v37, v38
	v_max3_f32 v186, v186, v39, v40
	v_max3_f32 v186, v186, v41, v42
	v_max3_f32 v186, v186, v43, v44
	v_max3_f32 v186, v186, v45, v46
	v_max3_f32 v186, v186, v47, v48
	v_max3_f32 v186, v186, v49, v50
	v_max3_f32 v186, v186, v51, v52
	v_max3_f32 v186, v186, v53, v54
	v_max3_f32 v186, v186, v55, v56
	v_max3_f32 v186, v186, v57, v58
	v_max3_f32 v186, v186, v59, v60
	v_max3_f32 v186, v186, v61, v62
	v_max3_f32 v186, v186, v63, v64
	v_max3_f32 v186, v186, v65, v66
	v_max3_f32 v186, v186, v67, v68
	v_max3_f32 v186, v186, v69, v70
	v_max_f32_e32 v186, v186, v71
	v_mov_b32_e32 v146, v186
	s_nop 1
	v_permlane16_swap_b32_e32 v186, v146
	v_max_f32_e32 v186, v186, v146
	v_mov_b32_e32 v146, v186
	s_nop 1
	v_permlane32_swap_b32_e32 v186, v146
	v_max_f32_e32 v186, v186, v146
	v_pk_add_f32 v[36:37], v[36:37], v[186:187] op_sel_hi:[1,0] neg_lo:[0,1] neg_hi:[0,1]
	v_pk_add_f32 v[38:39], v[38:39], v[186:187] op_sel_hi:[1,0] neg_lo:[0,1] neg_hi:[0,1]
	v_pk_add_f32 v[40:41], v[40:41], v[186:187] op_sel_hi:[1,0] neg_lo:[0,1] neg_hi:[0,1]
	v_pk_add_f32 v[42:43], v[42:43], v[186:187] op_sel_hi:[1,0] neg_lo:[0,1] neg_hi:[0,1]
	v_exp_f32_e32 v36, v36
	v_exp_f32_e32 v37, v37
	v_exp_f32_e32 v38, v38
	v_exp_f32_e32 v39, v39
	v_pk_add_f32 v[44:45], v[44:45], v[186:187] op_sel_hi:[1,0] neg_lo:[0,1] neg_hi:[0,1]
	v_pk_add_f32 v[46:47], v[46:47], v[186:187] op_sel_hi:[1,0] neg_lo:[0,1] neg_hi:[0,1]
	v_exp_f32_e32 v40, v40
	v_exp_f32_e32 v41, v41
	v_exp_f32_e32 v42, v42
	v_exp_f32_e32 v43, v43
	v_pk_add_f32 v[48:49], v[48:49], v[186:187] op_sel_hi:[1,0] neg_lo:[0,1] neg_hi:[0,1]
	v_pk_add_f32 v[50:51], v[50:51], v[186:187] op_sel_hi:[1,0] neg_lo:[0,1] neg_hi:[0,1]
	v_exp_f32_e32 v44, v44
	v_exp_f32_e32 v45, v45
	v_exp_f32_e32 v46, v46
	v_exp_f32_e32 v47, v47
	v_pk_add_f32 v[52:53], v[52:53], v[186:187] op_sel_hi:[1,0] neg_lo:[0,1] neg_hi:[0,1]
	v_pk_add_f32 v[54:55], v[54:55], v[186:187] op_sel_hi:[1,0] neg_lo:[0,1] neg_hi:[0,1]
	v_exp_f32_e32 v48, v48
	v_exp_f32_e32 v49, v49
	v_exp_f32_e32 v50, v50
	v_exp_f32_e32 v51, v51
	v_pk_add_f32 v[56:57], v[56:57], v[186:187] op_sel_hi:[1,0] neg_lo:[0,1] neg_hi:[0,1]
	v_pk_add_f32 v[58:59], v[58:59], v[186:187] op_sel_hi:[1,0] neg_lo:[0,1] neg_hi:[0,1]
	v_exp_f32_e32 v52, v52
	v_exp_f32_e32 v53, v53
	v_exp_f32_e32 v54, v54
	v_exp_f32_e32 v55, v55
	v_pk_add_f32 v[60:61], v[60:61], v[186:187] op_sel_hi:[1,0] neg_lo:[0,1] neg_hi:[0,1]
	v_pk_add_f32 v[62:63], v[62:63], v[186:187] op_sel_hi:[1,0] neg_lo:[0,1] neg_hi:[0,1]
	v_exp_f32_e32 v56, v56
	v_exp_f32_e32 v57, v57
	v_exp_f32_e32 v58, v58
	v_exp_f32_e32 v59, v59
	v_pk_add_f32 v[64:65], v[64:65], v[186:187] op_sel_hi:[1,0] neg_lo:[0,1] neg_hi:[0,1]
	v_pk_add_f32 v[66:67], v[66:67], v[186:187] op_sel_hi:[1,0] neg_lo:[0,1] neg_hi:[0,1]
	v_exp_f32_e32 v60, v60
	v_exp_f32_e32 v61, v61
	v_exp_f32_e32 v62, v62
	v_exp_f32_e32 v63, v63
	v_pk_add_f32 v[68:69], v[68:69], v[186:187] op_sel_hi:[1,0] neg_lo:[0,1] neg_hi:[0,1]
	v_pk_add_f32 v[70:71], v[70:71], v[186:187] op_sel_hi:[1,0] neg_lo:[0,1] neg_hi:[0,1]
	v_exp_f32_e32 v64, v64
	v_exp_f32_e32 v65, v65
	v_exp_f32_e32 v66, v66
	v_exp_f32_e32 v67, v67
	v_exp_f32_e32 v68, v68
	v_exp_f32_e32 v69, v69
	v_exp_f32_e32 v70, v70
	v_exp_f32_e32 v71, v71
	s_nop 0
	v_pk_add_f32 v[146:147], v[36:37], v[38:39]
	v_pk_add_f32 v[148:149], v[40:41], v[42:43]
	v_pk_add_f32 v[146:147], v[146:147], v[44:45]
	v_pk_add_f32 v[148:149], v[148:149], v[46:47]
	v_pk_add_f32 v[146:147], v[146:147], v[48:49]
	v_pk_add_f32 v[148:149], v[148:149], v[50:51]
	v_pk_add_f32 v[146:147], v[146:147], v[52:53]
	v_pk_add_f32 v[148:149], v[148:149], v[54:55]
	v_pk_add_f32 v[146:147], v[146:147], v[56:57]
	v_pk_add_f32 v[148:149], v[148:149], v[58:59]
	v_pk_add_f32 v[146:147], v[146:147], v[60:61]
	v_pk_add_f32 v[148:149], v[148:149], v[62:63]
	v_pk_add_f32 v[146:147], v[146:147], v[64:65]
	v_pk_add_f32 v[148:149], v[148:149], v[66:67]
	v_pk_add_f32 v[146:147], v[146:147], v[68:69]
	v_pk_add_f32 v[148:149], v[148:149], v[70:71]
	s_nop 0
	v_pk_add_f32 v[146:147], v[146:147], v[148:149]
	s_nop 0
	v_add_f32_e32 v187, v146, v147
	v_cvt_pk_bf16_f32 v36, v36, v37
	v_cvt_pk_bf16_f32 v37, v38, v39
	v_cvt_pk_bf16_f32 v40, v40, v41
	v_cvt_pk_bf16_f32 v41, v42, v43
	v_cvt_pk_bf16_f32 v44, v44, v45
	v_cvt_pk_bf16_f32 v45, v46, v47
	v_cvt_pk_bf16_f32 v48, v48, v49
	v_cvt_pk_bf16_f32 v49, v50, v51
	v_cvt_pk_bf16_f32 v52, v52, v53
	v_cvt_pk_bf16_f32 v53, v54, v55
	v_cvt_pk_bf16_f32 v56, v56, v57
	v_cvt_pk_bf16_f32 v57, v58, v59
	v_cvt_pk_bf16_f32 v60, v60, v61
	v_cvt_pk_bf16_f32 v61, v62, v63
	v_cvt_pk_bf16_f32 v64, v64, v65
	v_cvt_pk_bf16_f32 v65, v66, v67
	v_cvt_pk_bf16_f32 v68, v68, v69
	v_cvt_pk_bf16_f32 v69, v70, v71
	v_mov_b32_e32 v146, v187
	s_nop 1
	v_permlane16_swap_b32_e32 v187, v146
	v_add_f32_e32 v187, v187, v146
	v_mov_b32_e32 v146, v187
	s_nop 1
	v_permlane32_swap_b32_e32 v187, v146
	v_add_f32_e32 v187, v187, v146
	s_waitcnt lgkmcnt(0)
	s_add_i32 s93, s76, 64
	s_mov_b32 m0, s16
	v_add_u32_e32 v164, s93, v231
	v_med3_i32 v164, v164, 0, s40
	v_lshl_or_b32 v164, v164, 7, v222
	global_load_lds_dwordx4 v164, s[24:25]
	s_add_i32 m0, s16, 0x400
	v_add_u32_e32 v165, s93, v232
	v_med3_i32 v165, v165, 0, s40
	v_lshl_or_b32 v165, v165, 7, v222
	global_load_lds_dwordx4 v165, s[24:25]
	s_waitcnt vmcnt(8)
	v_add_u32_e32 v154, s12, v225
	v_add_u32_e32 v155, s12, v226
	v_add_u32_e32 v156, s12, v227
	v_add_u32_e32 v157, s12, v228
	ds_read_b64_tr_b16 v[202:203], v154
	ds_read_b64_tr_b16 v[204:205], v155
	ds_read_b64_tr_b16 v[206:207], v156
	ds_read_b64_tr_b16 v[208:209], v157
	v_mfma_f32_16x16x16_bf16 v[96:99], v[88:89], v[0:1], 0
	v_mfma_f32_16x16x16_bf16 v[100:103], v[90:91], v[0:1], 0
	v_mfma_f32_16x16x16_bf16 v[104:107], v[92:93], v[0:1], 0
	v_mfma_f32_16x16x16_bf16 v[108:111], v[94:95], v[0:1], 0
	s_waitcnt lgkmcnt(0)
	s_add_i32 s93, s76, 0x80
	s_mov_b32 m0, s12
	v_add_u32_e32 v164, s93, v231
	v_med3_i32 v164, v164, 0, s40
	v_lshl_or_b32 v164, v164, 7, v222
	global_load_lds_dwordx4 v164, s[24:25]
	s_add_i32 m0, s12, 0x400
	v_add_u32_e32 v165, s93, v232
	v_med3_i32 v165, v165, 0, s40
	v_lshl_or_b32 v165, v165, 7, v222
	global_load_lds_dwordx4 v165, s[24:25]
	s_waitcnt vmcnt(8)
	v_add_u32_e32 v154, s13, v225
	v_add_u32_e32 v155, s13, v226
	v_add_u32_e32 v156, s13, v227
	v_add_u32_e32 v157, s13, v228
	ds_read_b64_tr_b16 v[88:89], v154
	ds_read_b64_tr_b16 v[90:91], v155
	ds_read_b64_tr_b16 v[92:93], v156
	ds_read_b64_tr_b16 v[94:95], v157
	v_mfma_f32_16x16x16_bf16 v[96:99], v[202:203], v[4:5], v[96:99]
	v_mfma_f32_16x16x16_bf16 v[112:115], v[202:203], v[36:37], 0
	v_mfma_f32_16x16x16_bf16 v[100:103], v[204:205], v[4:5], v[100:103]
	v_mfma_f32_16x16x16_bf16 v[116:119], v[204:205], v[36:37], 0
	v_mfma_f32_16x16x16_bf16 v[104:107], v[206:207], v[4:5], v[104:107]
	v_mfma_f32_16x16x16_bf16 v[120:123], v[206:207], v[36:37], 0
	v_mfma_f32_16x16x16_bf16 v[108:111], v[208:209], v[4:5], v[108:111]
	v_mfma_f32_16x16x16_bf16 v[124:127], v[208:209], v[36:37], 0
	s_waitcnt lgkmcnt(0)
	s_add_i32 s93, s76, 0xc0
	s_mov_b32 m0, s13
	v_add_u32_e32 v164, s93, v231
	v_med3_i32 v164, v164, 0, s40
	v_lshl_or_b32 v164, v164, 7, v222
	global_load_lds_dwordx4 v164, s[24:25]
	s_add_i32 m0, s13, 0x400
	v_add_u32_e32 v165, s93, v232
	v_med3_i32 v165, v165, 0, s40
	v_lshl_or_b32 v165, v165, 7, v222
	global_load_lds_dwordx4 v165, s[24:25]
	s_waitcnt vmcnt(8)
	v_add_u32_e32 v154, s14, v225
	v_add_u32_e32 v155, s14, v226
	v_add_u32_e32 v156, s14, v227
	v_add_u32_e32 v157, s14, v228
	ds_read_b64_tr_b16 v[202:203], v154
	ds_read_b64_tr_b16 v[204:205], v155
	ds_read_b64_tr_b16 v[206:207], v156
	ds_read_b64_tr_b16 v[208:209], v157
	v_mfma_f32_16x16x16_bf16 v[96:99], v[88:89], v[8:9], v[96:99]
	v_mfma_f32_16x16x16_bf16 v[112:115], v[88:89], v[40:41], v[112:115]
	v_mfma_f32_16x16x16_bf16 v[100:103], v[90:91], v[8:9], v[100:103]
	v_mfma_f32_16x16x16_bf16 v[116:119], v[90:91], v[40:41], v[116:119]
	v_mfma_f32_16x16x16_bf16 v[104:107], v[92:93], v[8:9], v[104:107]
	v_mfma_f32_16x16x16_bf16 v[120:123], v[92:93], v[40:41], v[120:123]
	v_mfma_f32_16x16x16_bf16 v[108:111], v[94:95], v[8:9], v[108:111]
	v_mfma_f32_16x16x16_bf16 v[124:127], v[94:95], v[40:41], v[124:127]
	s_waitcnt lgkmcnt(0)
	s_add_i32 s93, s76, 0x100
	s_mov_b32 m0, s14
	v_add_u32_e32 v164, s93, v231
	v_med3_i32 v164, v164, 0, s40
	v_lshl_or_b32 v164, v164, 7, v222
	global_load_lds_dwordx4 v164, s[24:25]
	s_add_i32 m0, s14, 0x400
	v_add_u32_e32 v165, s93, v232
	v_med3_i32 v165, v165, 0, s40
	v_lshl_or_b32 v165, v165, 7, v222
	global_load_lds_dwordx4 v165, s[24:25]
	s_waitcnt vmcnt(8)
	v_add_u32_e32 v154, s15, v225
	v_add_u32_e32 v155, s15, v226
	v_add_u32_e32 v156, s15, v227
	v_add_u32_e32 v157, s15, v228
	ds_read_b64_tr_b16 v[88:89], v154
	ds_read_b64_tr_b16 v[90:91], v155
	ds_read_b64_tr_b16 v[92:93], v156
	ds_read_b64_tr_b16 v[94:95], v157
	v_mfma_f32_16x16x16_bf16 v[96:99], v[202:203], v[12:13], v[96:99]
	v_mfma_f32_16x16x16_bf16 v[112:115], v[202:203], v[44:45], v[112:115]
	v_mfma_f32_16x16x16_bf16 v[100:103], v[204:205], v[12:13], v[100:103]
	v_mfma_f32_16x16x16_bf16 v[116:119], v[204:205], v[44:45], v[116:119]
	v_mfma_f32_16x16x16_bf16 v[104:107], v[206:207], v[12:13], v[104:107]
	v_mfma_f32_16x16x16_bf16 v[120:123], v[206:207], v[44:45], v[120:123]
	v_mfma_f32_16x16x16_bf16 v[108:111], v[208:209], v[12:13], v[108:111]
	v_mfma_f32_16x16x16_bf16 v[124:127], v[208:209], v[44:45], v[124:127]
	s_waitcnt lgkmcnt(0)
	s_add_i32 s93, s76, 0x140
	s_mov_b32 m0, s15
	v_add_u32_e32 v164, s93, v231
	v_med3_i32 v164, v164, 0, s40
	v_lshl_or_b32 v164, v164, 7, v222
	global_load_lds_dwordx4 v164, s[24:25]
	s_add_i32 m0, s15, 0x400
	v_add_u32_e32 v165, s93, v232
	v_med3_i32 v165, v165, 0, s40
	v_lshl_or_b32 v165, v165, 7, v222
	global_load_lds_dwordx4 v165, s[24:25]
	s_waitcnt vmcnt(8)
	v_add_u32_e32 v154, s16, v225
	v_add_u32_e32 v155, s16, v226
	v_add_u32_e32 v156, s16, v227
	v_add_u32_e32 v157, s16, v228
	ds_read_b64_tr_b16 v[202:203], v154
	ds_read_b64_tr_b16 v[204:205], v155
	ds_read_b64_tr_b16 v[206:207], v156
	ds_read_b64_tr_b16 v[208:209], v157
	v_mfma_f32_16x16x16_bf16 v[96:99], v[88:89], v[16:17], v[96:99]
	v_mfma_f32_16x16x16_bf16 v[112:115], v[88:89], v[48:49], v[112:115]
	v_mfma_f32_16x16x16_bf16 v[100:103], v[90:91], v[16:17], v[100:103]
	v_mfma_f32_16x16x16_bf16 v[116:119], v[90:91], v[48:49], v[116:119]
	v_mfma_f32_16x16x16_bf16 v[104:107], v[92:93], v[16:17], v[104:107]
	v_mfma_f32_16x16x16_bf16 v[120:123], v[92:93], v[48:49], v[120:123]
	v_mfma_f32_16x16x16_bf16 v[108:111], v[94:95], v[16:17], v[108:111]
	v_mfma_f32_16x16x16_bf16 v[124:127], v[94:95], v[48:49], v[124:127]
	s_waitcnt lgkmcnt(0)
	s_add_i32 s93, s79, 0
	s_mov_b32 m0, s16
	v_add_u32_e32 v164, s93, v162
	v_lshl_or_b32 v164, v164, 7, v220
	global_load_lds_dwordx4 v164, s[18:19]
	s_add_i32 m0, s16, 0x400
	v_add_u32_e32 v165, s93, v163
	v_lshl_or_b32 v165, v165, 7, v221
	global_load_lds_dwordx4 v165, s[18:19]
	s_waitcnt vmcnt(8)
	v_add_u32_e32 v154, s12, v225
	v_add_u32_e32 v155, s12, v226
	v_add_u32_e32 v156, s12, v227
	v_add_u32_e32 v157, s12, v228
	ds_read_b64_tr_b16 v[88:89], v154
	ds_read_b64_tr_b16 v[90:91], v155
	ds_read_b64_tr_b16 v[92:93], v156
	ds_read_b64_tr_b16 v[94:95], v157
	v_mfma_f32_16x16x16_bf16 v[96:99], v[202:203], v[20:21], v[96:99]
	v_mfma_f32_16x16x16_bf16 v[112:115], v[202:203], v[52:53], v[112:115]
	v_mfma_f32_16x16x16_bf16 v[100:103], v[204:205], v[20:21], v[100:103]
	v_mfma_f32_16x16x16_bf16 v[116:119], v[204:205], v[52:53], v[116:119]
	v_mfma_f32_16x16x16_bf16 v[104:107], v[206:207], v[20:21], v[104:107]
	v_mfma_f32_16x16x16_bf16 v[120:123], v[206:207], v[52:53], v[120:123]
	v_mfma_f32_16x16x16_bf16 v[108:111], v[208:209], v[20:21], v[108:111]
	v_mfma_f32_16x16x16_bf16 v[124:127], v[208:209], v[52:53], v[124:127]
	s_waitcnt lgkmcnt(0)
	s_add_i32 s93, s79, 0xfffffc00
	s_mov_b32 m0, s12
	v_add_u32_e32 v164, s93, v162
	v_med3_i32 v164, v164, 0, s40
	v_lshl_or_b32 v164, v164, 7, v220
	global_load_lds_dwordx4 v164, s[20:21]
	s_add_i32 m0, s12, 0x400
	v_add_u32_e32 v165, s93, v163
	v_med3_i32 v165, v165, 0, s40
	v_lshl_or_b32 v165, v165, 7, v221
	global_load_lds_dwordx4 v165, s[20:21]
	s_waitcnt vmcnt(8)
	v_add_u32_e32 v154, s13, v225
	v_add_u32_e32 v155, s13, v226
	v_add_u32_e32 v156, s13, v227
	v_add_u32_e32 v157, s13, v228
	ds_read_b64_tr_b16 v[202:203], v154
	ds_read_b64_tr_b16 v[204:205], v155
	ds_read_b64_tr_b16 v[206:207], v156
	ds_read_b64_tr_b16 v[208:209], v157
	v_mfma_f32_16x16x16_bf16 v[96:99], v[88:89], v[24:25], v[96:99]
	v_mfma_f32_16x16x16_bf16 v[112:115], v[88:89], v[56:57], v[112:115]
	v_mfma_f32_16x16x16_bf16 v[100:103], v[90:91], v[24:25], v[100:103]
	v_mfma_f32_16x16x16_bf16 v[116:119], v[90:91], v[56:57], v[116:119]
	v_mfma_f32_16x16x16_bf16 v[104:107], v[92:93], v[24:25], v[104:107]
	v_mfma_f32_16x16x16_bf16 v[120:123], v[92:93], v[56:57], v[120:123]
	v_mfma_f32_16x16x16_bf16 v[108:111], v[94:95], v[24:25], v[108:111]
	v_mfma_f32_16x16x16_bf16 v[124:127], v[94:95], v[56:57], v[124:127]
	s_waitcnt lgkmcnt(0)
	s_add_i32 s93, s79, 0xfffffd00
	s_mov_b32 m0, s13
	v_add_u32_e32 v164, s93, v162
	v_med3_i32 v164, v164, 0, s40
	v_lshl_or_b32 v164, v164, 7, v220
	global_load_lds_dwordx4 v164, s[20:21]
	s_add_i32 m0, s13, 0x400
	v_add_u32_e32 v165, s93, v163
	v_med3_i32 v165, v165, 0, s40
	v_lshl_or_b32 v165, v165, 7, v221
	global_load_lds_dwordx4 v165, s[20:21]
	s_waitcnt vmcnt(8)
	v_add_u32_e32 v154, s14, v225
	v_add_u32_e32 v155, s14, v226
	v_add_u32_e32 v156, s14, v227
	v_add_u32_e32 v157, s14, v228
	ds_read_b64_tr_b16 v[88:89], v154
	ds_read_b64_tr_b16 v[90:91], v155
	ds_read_b64_tr_b16 v[92:93], v156
	ds_read_b64_tr_b16 v[94:95], v157
	v_mfma_f32_16x16x16_bf16 v[96:99], v[202:203], v[28:29], v[96:99]
	v_mfma_f32_16x16x16_bf16 v[112:115], v[202:203], v[60:61], v[112:115]
	v_mfma_f32_16x16x16_bf16 v[100:103], v[204:205], v[28:29], v[100:103]
	v_mfma_f32_16x16x16_bf16 v[116:119], v[204:205], v[60:61], v[116:119]
	v_mfma_f32_16x16x16_bf16 v[104:107], v[206:207], v[28:29], v[104:107]
	v_mfma_f32_16x16x16_bf16 v[120:123], v[206:207], v[60:61], v[120:123]
	v_mfma_f32_16x16x16_bf16 v[108:111], v[208:209], v[28:29], v[108:111]
	v_mfma_f32_16x16x16_bf16 v[124:127], v[208:209], v[60:61], v[124:127]
	s_waitcnt lgkmcnt(0)
	s_add_i32 s93, s79, 0xfffffe00
	s_mov_b32 m0, s14
	v_add_u32_e32 v164, s93, v162
	v_med3_i32 v164, v164, 0, s40
	v_lshl_or_b32 v164, v164, 7, v220
	global_load_lds_dwordx4 v164, s[20:21]
	s_add_i32 m0, s14, 0x400
	v_add_u32_e32 v165, s93, v163
	v_med3_i32 v165, v165, 0, s40
	v_lshl_or_b32 v165, v165, 7, v221
	global_load_lds_dwordx4 v165, s[20:21]
	s_waitcnt vmcnt(8)
	v_add_u32_e32 v154, s15, v225
	v_add_u32_e32 v155, s15, v226
	v_add_u32_e32 v156, s15, v227
	v_add_u32_e32 v157, s15, v228
	ds_read_b64_tr_b16 v[202:203], v154
	ds_read_b64_tr_b16 v[204:205], v155
	ds_read_b64_tr_b16 v[206:207], v156
	ds_read_b64_tr_b16 v[208:209], v157
	v_mfma_f32_16x16x16_bf16 v[96:99], v[88:89], v[32:33], v[96:99]
	v_mfma_f32_16x16x16_bf16 v[112:115], v[88:89], v[64:65], v[112:115]
	v_mfma_f32_16x16x16_bf16 v[100:103], v[90:91], v[32:33], v[100:103]
	v_mfma_f32_16x16x16_bf16 v[116:119], v[90:91], v[64:65], v[116:119]
	v_mfma_f32_16x16x16_bf16 v[104:107], v[92:93], v[32:33], v[104:107]
	v_mfma_f32_16x16x16_bf16 v[120:123], v[92:93], v[64:65], v[120:123]
	v_mfma_f32_16x16x16_bf16 v[108:111], v[94:95], v[32:33], v[108:111]
	v_mfma_f32_16x16x16_bf16 v[124:127], v[94:95], v[64:65], v[124:127]
	s_waitcnt lgkmcnt(0)
	s_add_i32 s93, s79, 0xffffff00
	s_mov_b32 m0, s15
	v_add_u32_e32 v164, s93, v162
	v_med3_i32 v164, v164, 0, s40
	v_lshl_or_b32 v164, v164, 7, v220
	global_load_lds_dwordx4 v164, s[20:21]
	s_add_i32 m0, s15, 0x400
	v_add_u32_e32 v165, s93, v163
	v_med3_i32 v165, v165, 0, s40
	v_lshl_or_b32 v165, v165, 7, v221
	global_load_lds_dwordx4 v165, s[20:21]
	v_mfma_f32_16x16x16_bf16 v[112:115], v[202:203], v[68:69], v[112:115]
	v_mfma_f32_16x16x16_bf16 v[116:119], v[204:205], v[68:69], v[116:119]
	v_mfma_f32_16x16x16_bf16 v[120:123], v[206:207], v[68:69], v[120:123]
	v_mfma_f32_16x16x16_bf16 v[124:127], v[208:209], v[68:69], v[124:127]
	s_waitcnt lgkmcnt(0)
	v_max_f32_e32 v146, v144, v184
	v_sub_f32_e32 v148, v144, v146
	v_sub_f32_e32 v150, v184, v146
	v_exp_f32_e32 v148, v148
	v_exp_f32_e32 v150, v150
	v_mov_b32_e32 v184, v146
	v_mul_f32_e32 v185, v185, v150
	v_fmac_f32_e32 v185, v145, v148
	v_pk_mul_f32 v[96:97], v[150:151], v[96:97] op_sel_hi:[0,1]
	v_pk_mul_f32 v[98:99], v[150:151], v[98:99] op_sel_hi:[0,1]
	v_pk_mul_f32 v[100:101], v[150:151], v[100:101] op_sel_hi:[0,1]
	v_pk_mul_f32 v[102:103], v[150:151], v[102:103] op_sel_hi:[0,1]
	v_pk_mul_f32 v[104:105], v[150:151], v[104:105] op_sel_hi:[0,1]
	v_pk_mul_f32 v[106:107], v[150:151], v[106:107] op_sel_hi:[0,1]
	v_pk_mul_f32 v[108:109], v[150:151], v[108:109] op_sel_hi:[0,1]
	v_pk_mul_f32 v[110:111], v[150:151], v[110:111] op_sel_hi:[0,1]
	v_pk_fma_f32 v[96:97], v[148:149], v[128:129], v[96:97] op_sel_hi:[0,1,1]
	v_pk_fma_f32 v[98:99], v[148:149], v[130:131], v[98:99] op_sel_hi:[0,1,1]
	v_pk_fma_f32 v[100:101], v[148:149], v[132:133], v[100:101] op_sel_hi:[0,1,1]
	v_pk_fma_f32 v[102:103], v[148:149], v[134:135], v[102:103] op_sel_hi:[0,1,1]
	v_pk_fma_f32 v[104:105], v[148:149], v[136:137], v[104:105] op_sel_hi:[0,1,1]
	v_pk_fma_f32 v[106:107], v[148:149], v[138:139], v[106:107] op_sel_hi:[0,1,1]
	v_pk_fma_f32 v[108:109], v[148:149], v[140:141], v[108:109] op_sel_hi:[0,1,1]
	v_pk_fma_f32 v[110:111], v[148:149], v[142:143], v[110:111] op_sel_hi:[0,1,1]
	s_and_saveexec_b64 s[80:81], s[74:75]
	ds_write_b64 v194, v[184:185]
	s_mov_b64 exec, s[80:81]
	ds_write_b128 v190, v[96:99]
	ds_write_b128 v191, v[100:103]
	ds_write_b128 v192, v[104:107]
	ds_write_b128 v193, v[108:111]
	s_waitcnt lgkmcnt(0)
	v_max_f32_e32 v146, v182, v186
	v_sub_f32_e32 v148, v182, v146
	v_sub_f32_e32 v150, v186, v146
	v_exp_f32_e32 v148, v148
	v_exp_f32_e32 v150, v150
	v_mov_b32_e32 v186, v146
	v_mul_f32_e32 v187, v187, v150
	v_fmac_f32_e32 v187, v183, v148
	v_pk_mul_f32 v[112:113], v[150:151], v[112:113] op_sel_hi:[0,1]
	v_pk_mul_f32 v[114:115], v[150:151], v[114:115] op_sel_hi:[0,1]
	v_pk_mul_f32 v[116:117], v[150:151], v[116:117] op_sel_hi:[0,1]
	v_pk_mul_f32 v[118:119], v[150:151], v[118:119] op_sel_hi:[0,1]
	v_pk_mul_f32 v[120:121], v[150:151], v[120:121] op_sel_hi:[0,1]
	v_pk_mul_f32 v[122:123], v[150:151], v[122:123] op_sel_hi:[0,1]
	v_pk_mul_f32 v[124:125], v[150:151], v[124:125] op_sel_hi:[0,1]
	v_pk_mul_f32 v[126:127], v[150:151], v[126:127] op_sel_hi:[0,1]
	v_pk_fma_f32 v[112:113], v[148:149], v[166:167], v[112:113] op_sel_hi:[0,1,1]
	v_pk_fma_f32 v[114:115], v[148:149], v[168:169], v[114:115] op_sel_hi:[0,1,1]
	v_pk_fma_f32 v[116:117], v[148:149], v[170:171], v[116:117] op_sel_hi:[0,1,1]
	v_pk_fma_f32 v[118:119], v[148:149], v[172:173], v[118:119] op_sel_hi:[0,1,1]
	v_pk_fma_f32 v[120:121], v[148:149], v[174:175], v[120:121] op_sel_hi:[0,1,1]
	v_pk_fma_f32 v[122:123], v[148:149], v[176:177], v[122:123] op_sel_hi:[0,1,1]
	v_pk_fma_f32 v[124:125], v[148:149], v[178:179], v[124:125] op_sel_hi:[0,1,1]
	v_pk_fma_f32 v[126:127], v[148:149], v[180:181], v[126:127] op_sel_hi:[0,1,1]
	s_and_saveexec_b64 s[80:81], s[74:75]
	ds_write_b64 v199, v[186:187]
	s_mov_b64 exec, s[80:81]
	ds_write_b128 v195, v[112:115]
	ds_write_b128 v196, v[116:119]
	ds_write_b128 v197, v[120:123]
	ds_write_b128 v198, v[124:127]
	s_waitcnt lgkmcnt(0)
	s_barrier
	s_add_i32 s76, s38, s84
	s_add_i32 s79, s38, s85
	v_lshlrev_b32_e32 v231, 4, v218
	v_add_u32_e32 v232, 8, v218
	v_lshlrev_b32_e32 v232, 4, v232
	s_waitcnt vmcnt(8)
	v_add_u32_e32 v154, s16, v223
	v_add_u32_e32 v155, s16, v224
	ds_read_b128 v[72:75], v154
	ds_read_b128 v[76:79], v155
	s_waitcnt lgkmcnt(0)
	s_add_i32 s93, s76, 0
	s_mov_b32 m0, s16
	v_add_u32_e32 v164, s93, v231
	v_med3_i32 v164, v164, 0, s40
	v_lshl_or_b32 v164, v164, 7, v220
	global_load_lds_dwordx4 v164, s[20:21]
	s_add_i32 m0, s16, 0x400
	v_add_u32_e32 v165, s93, v232
	v_med3_i32 v165, v165, 0, s40
	v_lshl_or_b32 v165, v165, 7, v221
	global_load_lds_dwordx4 v165, s[20:21]
	s_waitcnt vmcnt(8)
	v_add_u32_e32 v154, s12, v223
	v_add_u32_e32 v155, s12, v224
	ds_read_b128 v[202:205], v154
	ds_read_b128 v[206:209], v155
	s_waitcnt lgkmcnt(0)
	s_add_i32 s93, s76, 0x100
	s_mov_b32 m0, s12
	v_add_u32_e32 v164, s93, v231
	v_med3_i32 v164, v164, 0, s40
	v_lshl_or_b32 v164, v164, 7, v220
	global_load_lds_dwordx4 v164, s[20:21]
	s_add_i32 m0, s12, 0x400
	v_add_u32_e32 v165, s93, v232
	v_med3_i32 v165, v165, 0, s40
	v_lshl_or_b32 v165, v165, 7, v221
	global_load_lds_dwordx4 v165, s[20:21]
	s_waitcnt vmcnt(8)
	v_add_u32_e32 v154, s13, v223
	v_add_u32_e32 v155, s13, v224
	ds_read_b128 v[88:91], v154
	ds_read_b128 v[92:95], v155
	v_mfma_f32_16x16x32_bf16 v[0:3], v[202:205], v[72:75], 0
	v_mfma_f32_16x16x32_bf16 v[0:3], v[206:209], v[76:79], v[0:3]
	s_waitcnt lgkmcnt(0)
	s_add_i32 s93, s76, 0x200
	s_mov_b32 m0, s13
	v_add_u32_e32 v164, s93, v231
	v_med3_i32 v164, v164, 0, s40
	v_lshl_or_b32 v164, v164, 7, v220
	global_load_lds_dwordx4 v164, s[20:21]
	s_add_i32 m0, s13, 0x400
	v_add_u32_e32 v165, s93, v232
	v_med3_i32 v165, v165, 0, s40
	v_lshl_or_b32 v165, v165, 7, v221
	global_load_lds_dwordx4 v165, s[20:21]
	s_waitcnt vmcnt(8)
	v_add_u32_e32 v154, s14, v223
	v_add_u32_e32 v155, s14, v224
	ds_read_b128 v[202:205], v154
	ds_read_b128 v[206:209], v155
	v_mfma_f32_16x16x32_bf16 v[4:7], v[88:91], v[72:75], 0
	v_mfma_f32_16x16x32_bf16 v[4:7], v[92:95], v[76:79], v[4:7]
	s_waitcnt lgkmcnt(0)
	s_add_i32 s93, s76, 0x300
	s_mov_b32 m0, s14
	v_add_u32_e32 v164, s93, v231
	v_med3_i32 v164, v164, 0, s40
	v_lshl_or_b32 v164, v164, 7, v220
	global_load_lds_dwordx4 v164, s[20:21]
	s_add_i32 m0, s14, 0x400
	v_add_u32_e32 v165, s93, v232
	v_med3_i32 v165, v165, 0, s40
	v_lshl_or_b32 v165, v165, 7, v221
	global_load_lds_dwordx4 v165, s[20:21]
	s_waitcnt vmcnt(8)
	v_add_u32_e32 v154, s15, v223
	v_add_u32_e32 v155, s15, v224
	ds_read_b128 v[88:91], v154
	ds_read_b128 v[92:95], v155
	v_mfma_f32_16x16x32_bf16 v[8:11], v[202:205], v[72:75], 0
	v_mfma_f32_16x16x32_bf16 v[8:11], v[206:209], v[76:79], v[8:11]
	s_waitcnt lgkmcnt(0)
	s_add_i32 s93, s76, 0x400
	s_mov_b32 m0, s15
	v_add_u32_e32 v164, s93, v231
	v_med3_i32 v164, v164, 0, s40
	v_lshl_or_b32 v164, v164, 7, v220
	global_load_lds_dwordx4 v164, s[20:21]
	s_add_i32 m0, s15, 0x400
	v_add_u32_e32 v165, s93, v232
	v_med3_i32 v165, v165, 0, s40
	v_lshl_or_b32 v165, v165, 7, v221
	global_load_lds_dwordx4 v165, s[20:21]
	s_waitcnt vmcnt(8)
	v_add_u32_e32 v154, s16, v223
	v_add_u32_e32 v155, s16, v224
	ds_read_b128 v[202:205], v154
	ds_read_b128 v[206:209], v155
	v_mfma_f32_16x16x32_bf16 v[12:15], v[88:91], v[72:75], 0
	v_mfma_f32_16x16x32_bf16 v[12:15], v[92:95], v[76:79], v[12:15]
	s_waitcnt lgkmcnt(0)
	s_add_i32 s93, s76, 0xfffffc00
	s_mov_b32 m0, s16
	v_add_u32_e32 v164, s93, v231
	v_med3_i32 v164, v164, 0, s40
	v_lshl_or_b32 v164, v164, 7, v222
	global_load_lds_dwordx4 v164, s[24:25]
	s_add_i32 m0, s16, 0x400
	v_add_u32_e32 v165, s93, v232
	v_med3_i32 v165, v165, 0, s40
	v_lshl_or_b32 v165, v165, 7, v222
	global_load_lds_dwordx4 v165, s[24:25]
	s_waitcnt vmcnt(8)
	v_add_u32_e32 v154, s12, v223
	v_add_u32_e32 v155, s12, v224
	ds_read_b128 v[88:91], v154
	ds_read_b128 v[92:95], v155
	v_mfma_f32_16x16x32_bf16 v[16:19], v[202:205], v[72:75], 0
	v_mfma_f32_16x16x32_bf16 v[16:19], v[206:209], v[76:79], v[16:19]
	s_waitcnt lgkmcnt(0)
	s_add_i32 s93, s76, 0xfffffd00
	s_mov_b32 m0, s12
	v_add_u32_e32 v164, s93, v231
	v_med3_i32 v164, v164, 0, s40
	v_lshl_or_b32 v164, v164, 7, v222
	global_load_lds_dwordx4 v164, s[24:25]
	s_add_i32 m0, s12, 0x400
	v_add_u32_e32 v165, s93, v232
	v_med3_i32 v165, v165, 0, s40
	v_lshl_or_b32 v165, v165, 7, v222
	global_load_lds_dwordx4 v165, s[24:25]
	s_waitcnt vmcnt(8)
	v_add_u32_e32 v154, s13, v223
	v_add_u32_e32 v155, s13, v224
	ds_read_b128 v[202:205], v154
	ds_read_b128 v[206:209], v155
	v_mfma_f32_16x16x32_bf16 v[20:23], v[88:91], v[72:75], 0
	v_mfma_f32_16x16x32_bf16 v[20:23], v[92:95], v[76:79], v[20:23]
	s_waitcnt lgkmcnt(0)
	s_add_i32 s93, s76, 0xfffffe00
	s_mov_b32 m0, s13
	v_add_u32_e32 v164, s93, v231
	v_med3_i32 v164, v164, 0, s40
	v_lshl_or_b32 v164, v164, 7, v222
	global_load_lds_dwordx4 v164, s[24:25]
	s_add_i32 m0, s13, 0x400
	v_add_u32_e32 v165, s93, v232
	v_med3_i32 v165, v165, 0, s40
	v_lshl_or_b32 v165, v165, 7, v222
	global_load_lds_dwordx4 v165, s[24:25]
	s_waitcnt vmcnt(8)
	v_add_u32_e32 v154, s14, v223
	v_add_u32_e32 v155, s14, v224
	ds_read_b128 v[88:91], v154
	ds_read_b128 v[92:95], v155
	v_mfma_f32_16x16x32_bf16 v[24:27], v[202:205], v[72:75], 0
	v_mfma_f32_16x16x32_bf16 v[24:27], v[206:209], v[76:79], v[24:27]
	s_waitcnt lgkmcnt(0)
	s_add_i32 s93, s76, 0xffffff00
	s_mov_b32 m0, s14
	v_add_u32_e32 v164, s93, v231
	v_med3_i32 v164, v164, 0, s40
	v_lshl_or_b32 v164, v164, 7, v222
	global_load_lds_dwordx4 v164, s[24:25]
	s_add_i32 m0, s14, 0x400
	v_add_u32_e32 v165, s93, v232
	v_med3_i32 v165, v165, 0, s40
	v_lshl_or_b32 v165, v165, 7, v222
	global_load_lds_dwordx4 v165, s[24:25]
	s_waitcnt vmcnt(8)
	v_add_u32_e32 v154, s15, v223
	v_add_u32_e32 v155, s15, v224
	ds_read_b128 v[202:205], v154
	ds_read_b128 v[206:209], v155
	v_mfma_f32_16x16x32_bf16 v[28:31], v[88:91], v[72:75], 0
	v_mfma_f32_16x16x32_bf16 v[28:31], v[92:95], v[76:79], v[28:31]
	s_waitcnt lgkmcnt(0)
	s_add_i32 s93, s76, 0
	s_mov_b32 m0, s15
	v_add_u32_e32 v164, s93, v231
	v_med3_i32 v164, v164, 0, s40
	v_lshl_or_b32 v164, v164, 7, v222
	global_load_lds_dwordx4 v164, s[24:25]
	s_add_i32 m0, s15, 0x400
	v_add_u32_e32 v165, s93, v232
	v_med3_i32 v165, v165, 0, s40
	v_lshl_or_b32 v165, v165, 7, v222
	global_load_lds_dwordx4 v165, s[24:25]
	s_waitcnt vmcnt(8)
	v_add_u32_e32 v154, s16, v225
	v_add_u32_e32 v155, s16, v226
	v_add_u32_e32 v156, s16, v227
	v_add_u32_e32 v157, s16, v228
	ds_read_b64_tr_b16 v[88:89], v154
	ds_read_b64_tr_b16 v[90:91], v155
	ds_read_b64_tr_b16 v[92:93], v156
	ds_read_b64_tr_b16 v[94:95], v157
	v_mfma_f32_16x16x32_bf16 v[32:35], v[202:205], v[72:75], 0
	v_mfma_f32_16x16x32_bf16 v[32:35], v[206:209], v[76:79], v[32:35]
	v_mov_b32_e32 v188, s84
	v_lshl_add_u32 v188, v216, 4, v188
	v_lshrrev_b32_e32 v146, 4, v188
	v_xor_b32_e32 v146, v146, v188
	v_and_b32_e32 v146, 15, v146
	v_lshlrev_b32_e32 v147, 8, v188
	v_or_b32_e32 v148, 0, v217
	v_xor_b32_e32 v148, v148, v146
	v_lshl_add_u32 v190, v148, 4, v147
	v_or_b32_e32 v148, 4, v217
	v_xor_b32_e32 v148, v148, v146
	v_lshl_add_u32 v191, v148, 4, v147
	v_or_b32_e32 v148, 8, v217
	v_xor_b32_e32 v148, v148, v146
	v_lshl_add_u32 v192, v148, 4, v147
	v_or_b32_e32 v148, 12, v217
	v_xor_b32_e32 v148, v148, v146
	v_lshl_add_u32 v193, v148, 4, v147
	v_lshlrev_b32_e32 v194, 3, v188
	v_add_u32_e32 v194, 0x10000, v194
	ds_read_b64 v[144:145], v194
	ds_read_b128 v[128:131], v190
	ds_read_b128 v[132:135], v191
	ds_read_b128 v[136:139], v192
	ds_read_b128 v[140:143], v193
	s_add_i32 s90, s76, 0x4f0
	s_cmp_gt_i32 s90, s40
	s_cselect_b32 s96, 1, 0
	s_cmp_lt_i32 s76, 0x400
	s_cselect_b32 s96, 1, s96
	s_ashr_i32 s77, s76, 4
	s_sub_i32 s77, 64, s77
	s_sub_i32 s78, s40, s76
	s_ashr_i32 s78, s78, 4
	s_add_i32 s78, s78, 64
	v_cndmask_b32_e64 v0, v0, v230, s[52:53]
	v_cndmask_b32_e64 v32, v32, v230, s[62:63]
	v_cndmask_b32_e64 v1, v1, v230, s[56:57]
	v_cndmask_b32_e64 v33, v33, v230, s[64:65]
	v_cndmask_b32_e64 v2, v2, v230, s[58:59]
	v_cndmask_b32_e64 v34, v34, v230, s[70:71]
	v_cndmask_b32_e64 v3, v3, v230, s[60:61]
	v_cndmask_b32_e64 v35, v35, v230, s[72:73]
	s_cmp_eq_u32 s96, 0
	s_cbranch_scc1 .Latt_noedge_5
	v_sub_u32_e32 v200, s77, v229
	s_sub_i32 s91, s78, s77
	v_sub_u32_e32 v150, 0, v200
	v_sub_u32_e32 v151, 1, v200
	v_sub_u32_e32 v152, 2, v200
	v_sub_u32_e32 v153, 3, v200
	v_cmp_lt_u32_e64 s[94:95], s91, v150
	v_cmp_lt_u32_e64 s[86:87], s91, v151
	v_cmp_lt_u32_e64 s[0:1], s91, v152
	v_cmp_lt_u32_e64 s[2:3], s91, v153
	v_cndmask_b32_e64 v0, v0, v230, s[94:95]
	v_cndmask_b32_e64 v1, v1, v230, s[86:87]
	v_cndmask_b32_e64 v2, v2, v230, s[0:1]
	v_cndmask_b32_e64 v3, v3, v230, s[2:3]
	v_sub_u32_e32 v150, 16, v200
	v_sub_u32_e32 v151, 17, v200
	v_sub_u32_e32 v152, 18, v200
	v_sub_u32_e32 v153, 19, v200
	v_cmp_lt_u32_e64 s[94:95], s91, v150
	v_cmp_lt_u32_e64 s[86:87], s91, v151
	v_cmp_lt_u32_e64 s[0:1], s91, v152
	v_cmp_lt_u32_e64 s[2:3], s91, v153
	v_cndmask_b32_e64 v4, v4, v230, s[94:95]
	v_cndmask_b32_e64 v5, v5, v230, s[86:87]
	v_cndmask_b32_e64 v6, v6, v230, s[0:1]
	v_cndmask_b32_e64 v7, v7, v230, s[2:3]
	v_sub_u32_e32 v150, 32, v200
	v_sub_u32_e32 v151, 33, v200
	v_sub_u32_e32 v152, 34, v200
	v_sub_u32_e32 v153, 35, v200
	v_cmp_lt_u32_e64 s[94:95], s91, v150
	v_cmp_lt_u32_e64 s[86:87], s91, v151
	v_cmp_lt_u32_e64 s[0:1], s91, v152
	v_cmp_lt_u32_e64 s[2:3], s91, v153
	v_cndmask_b32_e64 v8, v8, v230, s[94:95]
	v_cndmask_b32_e64 v9, v9, v230, s[86:87]
	v_cndmask_b32_e64 v10, v10, v230, s[0:1]
	v_cndmask_b32_e64 v11, v11, v230, s[2:3]
	v_sub_u32_e32 v150, 48, v200
	v_sub_u32_e32 v151, 49, v200
	v_sub_u32_e32 v152, 50, v200
	v_sub_u32_e32 v153, 51, v200
	v_cmp_lt_u32_e64 s[94:95], s91, v150
	v_cmp_lt_u32_e64 s[86:87], s91, v151
	v_cmp_lt_u32_e64 s[0:1], s91, v152
	v_cmp_lt_u32_e64 s[2:3], s91, v153
	v_cndmask_b32_e64 v12, v12, v230, s[94:95]
	v_cndmask_b32_e64 v13, v13, v230, s[86:87]
	v_cndmask_b32_e64 v14, v14, v230, s[0:1]
	v_cndmask_b32_e64 v15, v15, v230, s[2:3]
	v_sub_u32_e32 v150, 64, v200
	v_sub_u32_e32 v151, 0x41, v200
	v_sub_u32_e32 v152, 0x42, v200
	v_sub_u32_e32 v153, 0x43, v200
	v_cmp_lt_u32_e64 s[94:95], s91, v150
	v_cmp_lt_u32_e64 s[86:87], s91, v151
	v_cmp_lt_u32_e64 s[0:1], s91, v152
	v_cmp_lt_u32_e64 s[2:3], s91, v153
	v_cndmask_b32_e64 v16, v16, v230, s[94:95]
	v_cndmask_b32_e64 v17, v17, v230, s[86:87]
	v_cndmask_b32_e64 v18, v18, v230, s[0:1]
	v_cndmask_b32_e64 v19, v19, v230, s[2:3]
	v_sub_u32_e32 v150, 0x50, v200
	v_sub_u32_e32 v151, 0x51, v200
	v_sub_u32_e32 v152, 0x52, v200
	v_sub_u32_e32 v153, 0x53, v200
	v_cmp_lt_u32_e64 s[94:95], s91, v150
	v_cmp_lt_u32_e64 s[86:87], s91, v151
	v_cmp_lt_u32_e64 s[0:1], s91, v152
	v_cmp_lt_u32_e64 s[2:3], s91, v153
	v_cndmask_b32_e64 v20, v20, v230, s[94:95]
	v_cndmask_b32_e64 v21, v21, v230, s[86:87]
	v_cndmask_b32_e64 v22, v22, v230, s[0:1]
	v_cndmask_b32_e64 v23, v23, v230, s[2:3]
	v_sub_u32_e32 v150, 0x60, v200
	v_sub_u32_e32 v151, 0x61, v200
	v_sub_u32_e32 v152, 0x62, v200
	v_sub_u32_e32 v153, 0x63, v200
	v_cmp_lt_u32_e64 s[94:95], s91, v150
	v_cmp_lt_u32_e64 s[86:87], s91, v151
	v_cmp_lt_u32_e64 s[0:1], s91, v152
	v_cmp_lt_u32_e64 s[2:3], s91, v153
	v_cndmask_b32_e64 v24, v24, v230, s[94:95]
	v_cndmask_b32_e64 v25, v25, v230, s[86:87]
	v_cndmask_b32_e64 v26, v26, v230, s[0:1]
	v_cndmask_b32_e64 v27, v27, v230, s[2:3]
	v_sub_u32_e32 v150, 0x70, v200
	v_sub_u32_e32 v151, 0x71, v200
	v_sub_u32_e32 v152, 0x72, v200
	v_sub_u32_e32 v153, 0x73, v200
	v_cmp_lt_u32_e64 s[94:95], s91, v150
	v_cmp_lt_u32_e64 s[86:87], s91, v151
	v_cmp_lt_u32_e64 s[0:1], s91, v152
	v_cmp_lt_u32_e64 s[2:3], s91, v153
	v_cndmask_b32_e64 v28, v28, v230, s[94:95]
	v_cndmask_b32_e64 v29, v29, v230, s[86:87]
	v_cndmask_b32_e64 v30, v30, v230, s[0:1]
	v_cndmask_b32_e64 v31, v31, v230, s[2:3]
	v_sub_u32_e32 v150, 0x80, v200
	v_sub_u32_e32 v151, 0x81, v200
	v_sub_u32_e32 v152, 0x82, v200
	v_sub_u32_e32 v153, 0x83, v200
	v_cmp_lt_u32_e64 s[94:95], s91, v150
	v_cmp_lt_u32_e64 s[86:87], s91, v151
	v_cmp_lt_u32_e64 s[0:1], s91, v152
	v_cmp_lt_u32_e64 s[2:3], s91, v153
	v_cndmask_b32_e64 v32, v32, v230, s[94:95]
	v_cndmask_b32_e64 v33, v33, v230, s[86:87]
	v_cndmask_b32_e64 v34, v34, v230, s[0:1]
	v_cndmask_b32_e64 v35, v35, v230, s[2:3]
.Latt_noedge_5:
	s_nop 1
	v_max3_f32 v184, v0, v1, v2
	v_max3_f32 v184, v184, v3, v4
	v_max3_f32 v184, v184, v5, v6
	v_max3_f32 v184, v184, v7, v8
	v_max3_f32 v184, v184, v9, v10
	v_max3_f32 v184, v184, v11, v12
	v_max3_f32 v184, v184, v13, v14
	v_max3_f32 v184, v184, v15, v16
	v_max3_f32 v184, v184, v17, v18
	v_max3_f32 v184, v184, v19, v20
	v_max3_f32 v184, v184, v21, v22
	v_max3_f32 v184, v184, v23, v24
	v_max3_f32 v184, v184, v25, v26
	v_max3_f32 v184, v184, v27, v28
	v_max3_f32 v184, v184, v29, v30
	v_max3_f32 v184, v184, v31, v32
	v_max3_f32 v184, v184, v33, v34
	v_max_f32_e32 v184, v184, v35
	v_mov_b32_e32 v146, v184
	s_nop 1
	v_permlane16_swap_b32_e32 v184, v146
	v_max_f32_e32 v184, v184, v146
	v_mov_b32_e32 v146, v184
	s_nop 1
	v_permlane32_swap_b32_e32 v184, v146
	v_max_f32_e32 v184, v184, v146
	v_pk_add_f32 v[0:1], v[0:1], v[184:185] op_sel_hi:[1,0] neg_lo:[0,1] neg_hi:[0,1]
	v_pk_add_f32 v[2:3], v[2:3], v[184:185] op_sel_hi:[1,0] neg_lo:[0,1] neg_hi:[0,1]
	v_pk_add_f32 v[4:5], v[4:5], v[184:185] op_sel_hi:[1,0] neg_lo:[0,1] neg_hi:[0,1]
	v_pk_add_f32 v[6:7], v[6:7], v[184:185] op_sel_hi:[1,0] neg_lo:[0,1] neg_hi:[0,1]
	v_exp_f32_e32 v0, v0
	v_exp_f32_e32 v1, v1
	v_exp_f32_e32 v2, v2
	v_exp_f32_e32 v3, v3
	v_pk_add_f32 v[8:9], v[8:9], v[184:185] op_sel_hi:[1,0] neg_lo:[0,1] neg_hi:[0,1]
	v_pk_add_f32 v[10:11], v[10:11], v[184:185] op_sel_hi:[1,0] neg_lo:[0,1] neg_hi:[0,1]
	v_exp_f32_e32 v4, v4
	v_exp_f32_e32 v5, v5
	v_exp_f32_e32 v6, v6
	v_exp_f32_e32 v7, v7
	v_pk_add_f32 v[12:13], v[12:13], v[184:185] op_sel_hi:[1,0] neg_lo:[0,1] neg_hi:[0,1]
	v_pk_add_f32 v[14:15], v[14:15], v[184:185] op_sel_hi:[1,0] neg_lo:[0,1] neg_hi:[0,1]
	v_exp_f32_e32 v8, v8
	v_exp_f32_e32 v9, v9
	v_exp_f32_e32 v10, v10
	v_exp_f32_e32 v11, v11
	v_pk_add_f32 v[16:17], v[16:17], v[184:185] op_sel_hi:[1,0] neg_lo:[0,1] neg_hi:[0,1]
	v_pk_add_f32 v[18:19], v[18:19], v[184:185] op_sel_hi:[1,0] neg_lo:[0,1] neg_hi:[0,1]
	v_exp_f32_e32 v12, v12
	v_exp_f32_e32 v13, v13
	v_exp_f32_e32 v14, v14
	v_exp_f32_e32 v15, v15
	v_pk_add_f32 v[20:21], v[20:21], v[184:185] op_sel_hi:[1,0] neg_lo:[0,1] neg_hi:[0,1]
	v_pk_add_f32 v[22:23], v[22:23], v[184:185] op_sel_hi:[1,0] neg_lo:[0,1] neg_hi:[0,1]
	v_exp_f32_e32 v16, v16
	v_exp_f32_e32 v17, v17
	v_exp_f32_e32 v18, v18
	v_exp_f32_e32 v19, v19
	v_pk_add_f32 v[24:25], v[24:25], v[184:185] op_sel_hi:[1,0] neg_lo:[0,1] neg_hi:[0,1]
	v_pk_add_f32 v[26:27], v[26:27], v[184:185] op_sel_hi:[1,0] neg_lo:[0,1] neg_hi:[0,1]
	v_exp_f32_e32 v20, v20
	v_exp_f32_e32 v21, v21
	v_exp_f32_e32 v22, v22
	v_exp_f32_e32 v23, v23
	v_pk_add_f32 v[28:29], v[28:29], v[184:185] op_sel_hi:[1,0] neg_lo:[0,1] neg_hi:[0,1]
	v_pk_add_f32 v[30:31], v[30:31], v[184:185] op_sel_hi:[1,0] neg_lo:[0,1] neg_hi:[0,1]
	v_exp_f32_e32 v24, v24
	v_exp_f32_e32 v25, v25
	v_exp_f32_e32 v26, v26
	v_exp_f32_e32 v27, v27
	v_pk_add_f32 v[32:33], v[32:33], v[184:185] op_sel_hi:[1,0] neg_lo:[0,1] neg_hi:[0,1]
	v_pk_add_f32 v[34:35], v[34:35], v[184:185] op_sel_hi:[1,0] neg_lo:[0,1] neg_hi:[0,1]
	v_exp_f32_e32 v28, v28
	v_exp_f32_e32 v29, v29
	v_exp_f32_e32 v30, v30
	v_exp_f32_e32 v31, v31
	v_exp_f32_e32 v32, v32
	v_exp_f32_e32 v33, v33
	v_exp_f32_e32 v34, v34
	v_exp_f32_e32 v35, v35
	s_nop 0
	v_pk_add_f32 v[146:147], v[0:1], v[2:3]
	v_pk_add_f32 v[148:149], v[4:5], v[6:7]
	v_pk_add_f32 v[146:147], v[146:147], v[8:9]
	v_pk_add_f32 v[148:149], v[148:149], v[10:11]
	v_pk_add_f32 v[146:147], v[146:147], v[12:13]
	v_pk_add_f32 v[148:149], v[148:149], v[14:15]
	v_pk_add_f32 v[146:147], v[146:147], v[16:17]
	v_pk_add_f32 v[148:149], v[148:149], v[18:19]
	v_pk_add_f32 v[146:147], v[146:147], v[20:21]
	v_pk_add_f32 v[148:149], v[148:149], v[22:23]
	v_pk_add_f32 v[146:147], v[146:147], v[24:25]
	v_pk_add_f32 v[148:149], v[148:149], v[26:27]
	v_pk_add_f32 v[146:147], v[146:147], v[28:29]
	v_pk_add_f32 v[148:149], v[148:149], v[30:31]
	v_pk_add_f32 v[146:147], v[146:147], v[32:33]
	v_pk_add_f32 v[148:149], v[148:149], v[34:35]
	s_nop 0
	v_pk_add_f32 v[146:147], v[146:147], v[148:149]
	s_nop 0
	v_add_f32_e32 v185, v146, v147
	v_cvt_pk_bf16_f32 v0, v0, v1
	v_cvt_pk_bf16_f32 v1, v2, v3
	v_cvt_pk_bf16_f32 v4, v4, v5
	v_cvt_pk_bf16_f32 v5, v6, v7
	v_cvt_pk_bf16_f32 v8, v8, v9
	v_cvt_pk_bf16_f32 v9, v10, v11
	v_cvt_pk_bf16_f32 v12, v12, v13
	v_cvt_pk_bf16_f32 v13, v14, v15
	v_cvt_pk_bf16_f32 v16, v16, v17
	v_cvt_pk_bf16_f32 v17, v18, v19
	v_cvt_pk_bf16_f32 v20, v20, v21
	v_cvt_pk_bf16_f32 v21, v22, v23
	v_cvt_pk_bf16_f32 v24, v24, v25
	v_cvt_pk_bf16_f32 v25, v26, v27
	v_cvt_pk_bf16_f32 v28, v28, v29
	v_cvt_pk_bf16_f32 v29, v30, v31
	v_cvt_pk_bf16_f32 v32, v32, v33
	v_cvt_pk_bf16_f32 v33, v34, v35
	v_mov_b32_e32 v146, v185
	s_nop 1
	v_permlane16_swap_b32_e32 v185, v146
	v_add_f32_e32 v185, v185, v146
	v_mov_b32_e32 v146, v185
	s_nop 1
	v_permlane32_swap_b32_e32 v185, v146
	v_add_f32_e32 v185, v185, v146
	s_waitcnt lgkmcnt(0)
	s_add_i32 s93, s76, 0x100
	s_mov_b32 m0, s16
	v_add_u32_e32 v164, s93, v231
	v_med3_i32 v164, v164, 0, s40
	v_lshl_or_b32 v164, v164, 7, v222
	global_load_lds_dwordx4 v164, s[24:25]
	s_add_i32 m0, s16, 0x400
	v_add_u32_e32 v165, s93, v232
	v_med3_i32 v165, v165, 0, s40
	v_lshl_or_b32 v165, v165, 7, v222
	global_load_lds_dwordx4 v165, s[24:25]
	s_waitcnt vmcnt(8)
	v_add_u32_e32 v154, s12, v225
	v_add_u32_e32 v155, s12, v226
	v_add_u32_e32 v156, s12, v227
	v_add_u32_e32 v157, s12, v228
	ds_read_b64_tr_b16 v[202:203], v154
	ds_read_b64_tr_b16 v[204:205], v155
	ds_read_b64_tr_b16 v[206:207], v156
	ds_read_b64_tr_b16 v[208:209], v157
	v_mfma_f32_16x16x16_bf16 v[96:99], v[88:89], v[0:1], 0
	v_mfma_f32_16x16x16_bf16 v[100:103], v[90:91], v[0:1], 0
	v_mfma_f32_16x16x16_bf16 v[104:107], v[92:93], v[0:1], 0
	v_mfma_f32_16x16x16_bf16 v[108:111], v[94:95], v[0:1], 0
	s_waitcnt lgkmcnt(0)
	s_add_i32 s93, s76, 0x200
	s_mov_b32 m0, s12
	v_add_u32_e32 v164, s93, v231
	v_med3_i32 v164, v164, 0, s40
	v_lshl_or_b32 v164, v164, 7, v222
	global_load_lds_dwordx4 v164, s[24:25]
	s_add_i32 m0, s12, 0x400
	v_add_u32_e32 v165, s93, v232
	v_med3_i32 v165, v165, 0, s40
	v_lshl_or_b32 v165, v165, 7, v222
	global_load_lds_dwordx4 v165, s[24:25]
	s_waitcnt vmcnt(8)
	v_add_u32_e32 v154, s13, v225
	v_add_u32_e32 v155, s13, v226
	v_add_u32_e32 v156, s13, v227
	v_add_u32_e32 v157, s13, v228
	ds_read_b64_tr_b16 v[88:89], v154
	ds_read_b64_tr_b16 v[90:91], v155
	ds_read_b64_tr_b16 v[92:93], v156
	ds_read_b64_tr_b16 v[94:95], v157
	v_mfma_f32_16x16x16_bf16 v[96:99], v[202:203], v[4:5], v[96:99]
	v_mfma_f32_16x16x16_bf16 v[100:103], v[204:205], v[4:5], v[100:103]
	v_mfma_f32_16x16x16_bf16 v[104:107], v[206:207], v[4:5], v[104:107]
	v_mfma_f32_16x16x16_bf16 v[108:111], v[208:209], v[4:5], v[108:111]
	s_waitcnt lgkmcnt(0)
	s_add_i32 s93, s76, 0x300
	s_mov_b32 m0, s13
	v_add_u32_e32 v164, s93, v231
	v_med3_i32 v164, v164, 0, s40
	v_lshl_or_b32 v164, v164, 7, v222
	global_load_lds_dwordx4 v164, s[24:25]
	s_add_i32 m0, s13, 0x400
	v_add_u32_e32 v165, s93, v232
	v_med3_i32 v165, v165, 0, s40
	v_lshl_or_b32 v165, v165, 7, v222
	global_load_lds_dwordx4 v165, s[24:25]
	s_waitcnt vmcnt(8)
	v_add_u32_e32 v154, s14, v225
	v_add_u32_e32 v155, s14, v226
	v_add_u32_e32 v156, s14, v227
	v_add_u32_e32 v157, s14, v228
	ds_read_b64_tr_b16 v[202:203], v154
	ds_read_b64_tr_b16 v[204:205], v155
	ds_read_b64_tr_b16 v[206:207], v156
	ds_read_b64_tr_b16 v[208:209], v157
	v_mfma_f32_16x16x16_bf16 v[96:99], v[88:89], v[8:9], v[96:99]
	v_mfma_f32_16x16x16_bf16 v[100:103], v[90:91], v[8:9], v[100:103]
	v_mfma_f32_16x16x16_bf16 v[104:107], v[92:93], v[8:9], v[104:107]
	v_mfma_f32_16x16x16_bf16 v[108:111], v[94:95], v[8:9], v[108:111]
	s_waitcnt lgkmcnt(0)
	s_add_i32 s93, s76, 0x400
	s_mov_b32 m0, s14
	v_add_u32_e32 v164, s93, v231
	v_med3_i32 v164, v164, 0, s40
	v_lshl_or_b32 v164, v164, 7, v222
	global_load_lds_dwordx4 v164, s[24:25]
	s_add_i32 m0, s14, 0x400
	v_add_u32_e32 v165, s93, v232
	v_med3_i32 v165, v165, 0, s40
	v_lshl_or_b32 v165, v165, 7, v222
	global_load_lds_dwordx4 v165, s[24:25]
	s_waitcnt vmcnt(8)
	v_add_u32_e32 v154, s15, v225
	v_add_u32_e32 v155, s15, v226
	v_add_u32_e32 v156, s15, v227
	v_add_u32_e32 v157, s15, v228
	ds_read_b64_tr_b16 v[88:89], v154
	ds_read_b64_tr_b16 v[90:91], v155
	ds_read_b64_tr_b16 v[92:93], v156
	ds_read_b64_tr_b16 v[94:95], v157
	v_mfma_f32_16x16x16_bf16 v[96:99], v[202:203], v[12:13], v[96:99]
	v_mfma_f32_16x16x16_bf16 v[100:103], v[204:205], v[12:13], v[100:103]
	v_mfma_f32_16x16x16_bf16 v[104:107], v[206:207], v[12:13], v[104:107]
	v_mfma_f32_16x16x16_bf16 v[108:111], v[208:209], v[12:13], v[108:111]
	s_waitcnt lgkmcnt(0)
	s_add_i32 s93, s79, 0
	s_mov_b32 m0, s15
	v_add_u32_e32 v164, s93, v231
	v_lshl_or_b32 v164, v164, 7, v220
	global_load_lds_dwordx4 v164, s[18:19]
	s_add_i32 m0, s15, 0x400
	v_add_u32_e32 v165, s93, v232
	v_lshl_or_b32 v165, v165, 7, v221
	global_load_lds_dwordx4 v165, s[18:19]
	s_waitcnt vmcnt(8)
	v_add_u32_e32 v154, s16, v225
	v_add_u32_e32 v155, s16, v226
	v_add_u32_e32 v156, s16, v227
	v_add_u32_e32 v157, s16, v228
	ds_read_b64_tr_b16 v[202:203], v154
	ds_read_b64_tr_b16 v[204:205], v155
	ds_read_b64_tr_b16 v[206:207], v156
	ds_read_b64_tr_b16 v[208:209], v157
	v_mfma_f32_16x16x16_bf16 v[96:99], v[88:89], v[16:17], v[96:99]
	v_mfma_f32_16x16x16_bf16 v[100:103], v[90:91], v[16:17], v[100:103]
	v_mfma_f32_16x16x16_bf16 v[104:107], v[92:93], v[16:17], v[104:107]
	v_mfma_f32_16x16x16_bf16 v[108:111], v[94:95], v[16:17], v[108:111]
	s_waitcnt lgkmcnt(0)
	s_add_i32 s93, s79, 0xfffffc00
	s_mov_b32 m0, s16
	v_add_u32_e32 v164, s93, v231
	v_med3_i32 v164, v164, 0, s40
	v_lshl_or_b32 v164, v164, 7, v220
	global_load_lds_dwordx4 v164, s[20:21]
	s_add_i32 m0, s16, 0x400
	v_add_u32_e32 v165, s93, v232
	v_med3_i32 v165, v165, 0, s40
	v_lshl_or_b32 v165, v165, 7, v221
	global_load_lds_dwordx4 v165, s[20:21]
	s_waitcnt vmcnt(8)
	v_add_u32_e32 v154, s12, v225
	v_add_u32_e32 v155, s12, v226
	v_add_u32_e32 v156, s12, v227
	v_add_u32_e32 v157, s12, v228
	ds_read_b64_tr_b16 v[88:89], v154
	ds_read_b64_tr_b16 v[90:91], v155
	ds_read_b64_tr_b16 v[92:93], v156
	ds_read_b64_tr_b16 v[94:95], v157
	v_mfma_f32_16x16x16_bf16 v[96:99], v[202:203], v[20:21], v[96:99]
	v_mfma_f32_16x16x16_bf16 v[100:103], v[204:205], v[20:21], v[100:103]
	v_mfma_f32_16x16x16_bf16 v[104:107], v[206:207], v[20:21], v[104:107]
	v_mfma_f32_16x16x16_bf16 v[108:111], v[208:209], v[20:21], v[108:111]
	s_waitcnt lgkmcnt(0)
	s_add_i32 s93, s79, 0xfffffd00
	s_mov_b32 m0, s12
	v_add_u32_e32 v164, s93, v231
	v_med3_i32 v164, v164, 0, s40
	v_lshl_or_b32 v164, v164, 7, v220
	global_load_lds_dwordx4 v164, s[20:21]
	s_add_i32 m0, s12, 0x400
	v_add_u32_e32 v165, s93, v232
	v_med3_i32 v165, v165, 0, s40
	v_lshl_or_b32 v165, v165, 7, v221
	global_load_lds_dwordx4 v165, s[20:21]
	s_waitcnt vmcnt(8)
	v_add_u32_e32 v154, s13, v225
	v_add_u32_e32 v155, s13, v226
	v_add_u32_e32 v156, s13, v227
	v_add_u32_e32 v157, s13, v228
	ds_read_b64_tr_b16 v[202:203], v154
	ds_read_b64_tr_b16 v[204:205], v155
	ds_read_b64_tr_b16 v[206:207], v156
	ds_read_b64_tr_b16 v[208:209], v157
	v_mfma_f32_16x16x16_bf16 v[96:99], v[88:89], v[24:25], v[96:99]
	v_mfma_f32_16x16x16_bf16 v[100:103], v[90:91], v[24:25], v[100:103]
	v_mfma_f32_16x16x16_bf16 v[104:107], v[92:93], v[24:25], v[104:107]
	v_mfma_f32_16x16x16_bf16 v[108:111], v[94:95], v[24:25], v[108:111]
	s_waitcnt lgkmcnt(0)
	s_add_i32 s93, s79, 0xfffffe00
	s_mov_b32 m0, s13
	v_add_u32_e32 v164, s93, v231
	v_med3_i32 v164, v164, 0, s40
	v_lshl_or_b32 v164, v164, 7, v220
	global_load_lds_dwordx4 v164, s[20:21]
	s_add_i32 m0, s13, 0x400
	v_add_u32_e32 v165, s93, v232
	v_med3_i32 v165, v165, 0, s40
	v_lshl_or_b32 v165, v165, 7, v221
	global_load_lds_dwordx4 v165, s[20:21]
	s_waitcnt vmcnt(8)
	v_add_u32_e32 v154, s14, v225
	v_add_u32_e32 v155, s14, v226
	v_add_u32_e32 v156, s14, v227
	v_add_u32_e32 v157, s14, v228
	ds_read_b64_tr_b16 v[88:89], v154
	ds_read_b64_tr_b16 v[90:91], v155
	ds_read_b64_tr_b16 v[92:93], v156
	ds_read_b64_tr_b16 v[94:95], v157
	v_mfma_f32_16x16x16_bf16 v[96:99], v[202:203], v[28:29], v[96:99]
	v_mfma_f32_16x16x16_bf16 v[100:103], v[204:205], v[28:29], v[100:103]
	v_mfma_f32_16x16x16_bf16 v[104:107], v[206:207], v[28:29], v[104:107]
	v_mfma_f32_16x16x16_bf16 v[108:111], v[208:209], v[28:29], v[108:111]
	s_waitcnt lgkmcnt(0)
	s_add_i32 s93, s79, 0xffffff00
	s_mov_b32 m0, s14
	v_add_u32_e32 v164, s93, v231
	v_med3_i32 v164, v164, 0, s40
	v_lshl_or_b32 v164, v164, 7, v220
	global_load_lds_dwordx4 v164, s[20:21]
	s_add_i32 m0, s14, 0x400
	v_add_u32_e32 v165, s93, v232
	v_med3_i32 v165, v165, 0, s40
	v_lshl_or_b32 v165, v165, 7, v221
	global_load_lds_dwordx4 v165, s[20:21]
	v_mfma_f32_16x16x16_bf16 v[96:99], v[88:89], v[32:33], v[96:99]
	v_mfma_f32_16x16x16_bf16 v[100:103], v[90:91], v[32:33], v[100:103]
	v_mfma_f32_16x16x16_bf16 v[104:107], v[92:93], v[32:33], v[104:107]
	v_mfma_f32_16x16x16_bf16 v[108:111], v[94:95], v[32:33], v[108:111]
	s_waitcnt lgkmcnt(0)
	v_max_f32_e32 v146, v144, v184
	v_sub_f32_e32 v148, v144, v146
	v_sub_f32_e32 v150, v184, v146
	v_exp_f32_e32 v148, v148
	v_exp_f32_e32 v150, v150
	v_mov_b32_e32 v184, v146
	v_mul_f32_e32 v185, v185, v150
	v_fmac_f32_e32 v185, v145, v148
	v_pk_mul_f32 v[96:97], v[150:151], v[96:97] op_sel_hi:[0,1]
	v_pk_mul_f32 v[98:99], v[150:151], v[98:99] op_sel_hi:[0,1]
	v_pk_mul_f32 v[100:101], v[150:151], v[100:101] op_sel_hi:[0,1]
	v_pk_mul_f32 v[102:103], v[150:151], v[102:103] op_sel_hi:[0,1]
	v_pk_mul_f32 v[104:105], v[150:151], v[104:105] op_sel_hi:[0,1]
	v_pk_mul_f32 v[106:107], v[150:151], v[106:107] op_sel_hi:[0,1]
	v_pk_mul_f32 v[108:109], v[150:151], v[108:109] op_sel_hi:[0,1]
	v_pk_mul_f32 v[110:111], v[150:151], v[110:111] op_sel_hi:[0,1]
	v_pk_fma_f32 v[96:97], v[148:149], v[128:129], v[96:97] op_sel_hi:[0,1,1]
	v_pk_fma_f32 v[98:99], v[148:149], v[130:131], v[98:99] op_sel_hi:[0,1,1]
	v_pk_fma_f32 v[100:101], v[148:149], v[132:133], v[100:101] op_sel_hi:[0,1,1]
	v_pk_fma_f32 v[102:103], v[148:149], v[134:135], v[102:103] op_sel_hi:[0,1,1]
	v_pk_fma_f32 v[104:105], v[148:149], v[136:137], v[104:105] op_sel_hi:[0,1,1]
	v_pk_fma_f32 v[106:107], v[148:149], v[138:139], v[106:107] op_sel_hi:[0,1,1]
	v_pk_fma_f32 v[108:109], v[148:149], v[140:141], v[108:109] op_sel_hi:[0,1,1]
	v_pk_fma_f32 v[110:111], v[148:149], v[142:143], v[110:111] op_sel_hi:[0,1,1]
	v_div_scale_f32 v147, s[94:95], v185, v185, 1.0
	v_rcp_f32_e32 v148, v147
	v_div_scale_f32 v149, vcc, 1.0, v185, 1.0
	v_fma_f32 v150, -v147, v148, 1.0
	v_fmac_f32_e32 v148, v150, v148
	v_mul_f32_e32 v150, v149, v148
	v_fma_f32 v151, -v147, v150, v149
	v_fmac_f32_e32 v150, v151, v148
	v_fma_f32 v147, -v147, v150, v149
	s_nop 1
	v_div_fmas_f32 v147, v147, v148, v150
	v_div_fixup_f32 v152, v147, v185, 1.0
	v_pk_mul_f32 v[96:97], v[152:153], v[96:97] op_sel_hi:[0,1]
	v_pk_mul_f32 v[98:99], v[152:153], v[98:99] op_sel_hi:[0,1]
	v_pk_mul_f32 v[100:101], v[152:153], v[100:101] op_sel_hi:[0,1]
	v_pk_mul_f32 v[102:103], v[152:153], v[102:103] op_sel_hi:[0,1]
	v_pk_mul_f32 v[104:105], v[152:153], v[104:105] op_sel_hi:[0,1]
	v_pk_mul_f32 v[106:107], v[152:153], v[106:107] op_sel_hi:[0,1]
	v_pk_mul_f32 v[108:109], v[152:153], v[108:109] op_sel_hi:[0,1]
	v_pk_mul_f32 v[110:111], v[152:153], v[110:111] op_sel_hi:[0,1]
	v_mul_f32_e32 v155, v97, v97
	v_mul_f32_e32 v156, v99, v99
	v_fmac_f32_e32 v155, v96, v96
	v_fmac_f32_e32 v156, v98, v98
	v_add_f32_e32 v154, v155, v156
	v_mul_f32_e32 v155, v101, v101
	v_mul_f32_e32 v156, v103, v103
	v_fmac_f32_e32 v155, v100, v100
	v_fmac_f32_e32 v156, v102, v102
	v_add_f32_e32 v155, v155, v156
	v_add_f32_e32 v154, v154, v155
	v_mul_f32_e32 v155, v105, v105
	v_mul_f32_e32 v156, v107, v107
	v_fmac_f32_e32 v155, v104, v104
	v_fmac_f32_e32 v156, v106, v106
	v_add_f32_e32 v155, v155, v156
	v_add_f32_e32 v154, v154, v155
	v_mul_f32_e32 v155, v109, v109
	v_mul_f32_e32 v156, v111, v111
	v_fmac_f32_e32 v155, v108, v108
	v_fmac_f32_e32 v156, v110, v110
	v_add_f32_e32 v155, v155, v156
	v_add_f32_e32 v154, v154, v155
	v_cvt_pk_bf16_f32 v96, v96, v97
	v_cvt_pk_bf16_f32 v97, v98, v99
	v_cvt_pk_bf16_f32 v100, v100, v101
	v_cvt_pk_bf16_f32 v101, v102, v103
	v_cvt_pk_bf16_f32 v104, v104, v105
	v_cvt_pk_bf16_f32 v105, v106, v107
	v_cvt_pk_bf16_f32 v108, v108, v109
	v_cvt_pk_bf16_f32 v109, v110, v111
	v_add_u32_e32 v157, s42, v188
	s_lshl_b32 s90, s43, 7
	v_lshlrev_b32_e32 v158, 11, v157
	v_add3_u32 v158, v158, s90, v233
	v_mov_b32_e32 v160, v96
	v_mov_b32_e32 v161, v97
	v_mov_b32_e32 v162, v100
	v_mov_b32_e32 v163, v101
	s_nop 1
	v_permlane16_swap_b32_e32 v160, v162
	v_permlane16_swap_b32_e32 v161, v163
	s_nop 1
	global_store_dwordx4 v158, v[160:163], s[48:49] offset:0
	s_nop 1
	v_mov_b32_e32 v160, v104
	v_mov_b32_e32 v161, v105
	v_mov_b32_e32 v162, v108
	v_mov_b32_e32 v163, v109
	s_nop 1
	v_permlane16_swap_b32_e32 v160, v162
	v_permlane16_swap_b32_e32 v161, v163
	s_nop 1
	global_store_dwordx4 v158, v[160:163], s[48:49] offset:64
	s_nop 1
	v_mov_b32_e32 v155, v154
	s_nop 1
	v_permlane16_swap_b32_e32 v154, v155
	v_add_f32_e32 v154, v154, v155
	v_mov_b32_e32 v155, v154
	s_nop 1
	v_permlane32_swap_b32_e32 v154, v155
	v_add_f32_e32 v154, v154, v155
	v_mul_u32_u24_e32 v157, 48, v157
	s_lshl_b32 s90, s43, 2
	v_add_u32_e32 v157, s90, v157
	s_and_saveexec_b64 s[80:81], s[74:75]
	global_store_dword v157, v154, s[50:51]
	s_mov_b64 exec, s[80:81]
	s_add_i32 s76, s38, s85
	s_add_i32 s79, s39, s82
	v_lshlrev_b32_e32 v231, 4, v218
	v_add_u32_e32 v232, 8, v218
	v_lshlrev_b32_e32 v232, 4, v232
	v_lshlrev_b32_e32 v162, 0, v218
	v_add_u32_e32 v163, 8, v218
	v_lshlrev_b32_e32 v163, 0, v163
	s_waitcnt vmcnt(8)
	v_add_u32_e32 v154, s15, v223
	v_add_u32_e32 v155, s15, v224
	ds_read_b128 v[72:75], v154
	ds_read_b128 v[76:79], v155
	s_waitcnt lgkmcnt(0)
	s_add_i32 s93, s76, 0
	s_mov_b32 m0, s15
	v_add_u32_e32 v164, s93, v231
	v_med3_i32 v164, v164, 0, s40
	v_lshl_or_b32 v164, v164, 7, v220
	global_load_lds_dwordx4 v164, s[20:21]
	s_add_i32 m0, s15, 0x400
	v_add_u32_e32 v165, s93, v232
	v_med3_i32 v165, v165, 0, s40
	v_lshl_or_b32 v165, v165, 7, v221
	global_load_lds_dwordx4 v165, s[20:21]
	s_waitcnt vmcnt(8)
	v_add_u32_e32 v154, s16, v223
	v_add_u32_e32 v155, s16, v224
	ds_read_b128 v[202:205], v154
	ds_read_b128 v[206:209], v155
	s_waitcnt lgkmcnt(0)
	s_add_i32 s93, s76, 0x100
	s_mov_b32 m0, s16
	v_add_u32_e32 v164, s93, v231
	v_med3_i32 v164, v164, 0, s40
	v_lshl_or_b32 v164, v164, 7, v220
	global_load_lds_dwordx4 v164, s[20:21]
	s_add_i32 m0, s16, 0x400
	v_add_u32_e32 v165, s93, v232
	v_med3_i32 v165, v165, 0, s40
	v_lshl_or_b32 v165, v165, 7, v221
	global_load_lds_dwordx4 v165, s[20:21]
	s_waitcnt vmcnt(8)
	v_add_u32_e32 v154, s12, v223
	v_add_u32_e32 v155, s12, v224
	ds_read_b128 v[88:91], v154
	ds_read_b128 v[92:95], v155
	v_mfma_f32_16x16x32_bf16 v[0:3], v[202:205], v[72:75], 0
	v_mfma_f32_16x16x32_bf16 v[0:3], v[206:209], v[76:79], v[0:3]
	s_waitcnt lgkmcnt(0)
	s_add_i32 s93, s76, 0x200
	s_mov_b32 m0, s12
	v_add_u32_e32 v164, s93, v231
	v_med3_i32 v164, v164, 0, s40
	v_lshl_or_b32 v164, v164, 7, v220
	global_load_lds_dwordx4 v164, s[20:21]
	s_add_i32 m0, s12, 0x400
	v_add_u32_e32 v165, s93, v232
	v_med3_i32 v165, v165, 0, s40
	v_lshl_or_b32 v165, v165, 7, v221
	global_load_lds_dwordx4 v165, s[20:21]
	s_waitcnt vmcnt(8)
	v_add_u32_e32 v154, s13, v223
	v_add_u32_e32 v155, s13, v224
	ds_read_b128 v[202:205], v154
	ds_read_b128 v[206:209], v155
	v_mfma_f32_16x16x32_bf16 v[4:7], v[88:91], v[72:75], 0
	v_mfma_f32_16x16x32_bf16 v[4:7], v[92:95], v[76:79], v[4:7]
	s_waitcnt lgkmcnt(0)
	s_add_i32 s93, s76, 0x300
	s_mov_b32 m0, s13
	v_add_u32_e32 v164, s93, v231
	v_med3_i32 v164, v164, 0, s40
	v_lshl_or_b32 v164, v164, 7, v220
	global_load_lds_dwordx4 v164, s[20:21]
	s_add_i32 m0, s13, 0x400
	v_add_u32_e32 v165, s93, v232
	v_med3_i32 v165, v165, 0, s40
	v_lshl_or_b32 v165, v165, 7, v221
	global_load_lds_dwordx4 v165, s[20:21]
	s_waitcnt vmcnt(8)
	v_add_u32_e32 v154, s14, v223
	v_add_u32_e32 v155, s14, v224
	ds_read_b128 v[88:91], v154
	ds_read_b128 v[92:95], v155
	v_mfma_f32_16x16x32_bf16 v[8:11], v[202:205], v[72:75], 0
	v_mfma_f32_16x16x32_bf16 v[8:11], v[206:209], v[76:79], v[8:11]
	s_waitcnt lgkmcnt(0)
	s_add_i32 s93, s76, 0x400
	s_mov_b32 m0, s14
	v_add_u32_e32 v164, s93, v231
	v_med3_i32 v164, v164, 0, s40
	v_lshl_or_b32 v164, v164, 7, v220
	global_load_lds_dwordx4 v164, s[20:21]
	s_add_i32 m0, s14, 0x400
	v_add_u32_e32 v165, s93, v232
	v_med3_i32 v165, v165, 0, s40
	v_lshl_or_b32 v165, v165, 7, v221
	global_load_lds_dwordx4 v165, s[20:21]
	s_waitcnt vmcnt(8)
	v_add_u32_e32 v154, s15, v223
	v_add_u32_e32 v155, s15, v224
	ds_read_b128 v[202:205], v154
	ds_read_b128 v[206:209], v155
	v_mfma_f32_16x16x32_bf16 v[12:15], v[88:91], v[72:75], 0
	v_mfma_f32_16x16x32_bf16 v[12:15], v[92:95], v[76:79], v[12:15]
	s_waitcnt lgkmcnt(0)
	s_add_i32 s93, s76, 0xfffffc00
	s_mov_b32 m0, s15
	v_add_u32_e32 v164, s93, v231
	v_med3_i32 v164, v164, 0, s40
	v_lshl_or_b32 v164, v164, 7, v222
	global_load_lds_dwordx4 v164, s[24:25]
	s_add_i32 m0, s15, 0x400
	v_add_u32_e32 v165, s93, v232
	v_med3_i32 v165, v165, 0, s40
	v_lshl_or_b32 v165, v165, 7, v222
	global_load_lds_dwordx4 v165, s[24:25]
	s_waitcnt vmcnt(8)
	v_add_u32_e32 v154, s16, v223
	v_add_u32_e32 v155, s16, v224
	ds_read_b128 v[88:91], v154
	ds_read_b128 v[92:95], v155
	v_mfma_f32_16x16x32_bf16 v[16:19], v[202:205], v[72:75], 0
	v_mfma_f32_16x16x32_bf16 v[16:19], v[206:209], v[76:79], v[16:19]
	s_waitcnt lgkmcnt(0)
	s_add_i32 s93, s76, 0xfffffd00
	s_mov_b32 m0, s16
	v_add_u32_e32 v164, s93, v231
	v_med3_i32 v164, v164, 0, s40
	v_lshl_or_b32 v164, v164, 7, v222
	global_load_lds_dwordx4 v164, s[24:25]
	s_add_i32 m0, s16, 0x400
	v_add_u32_e32 v165, s93, v232
	v_med3_i32 v165, v165, 0, s40
	v_lshl_or_b32 v165, v165, 7, v222
	global_load_lds_dwordx4 v165, s[24:25]
	s_waitcnt vmcnt(8)
	v_add_u32_e32 v154, s12, v223
	v_add_u32_e32 v155, s12, v224
	ds_read_b128 v[202:205], v154
	ds_read_b128 v[206:209], v155
	v_mfma_f32_16x16x32_bf16 v[20:23], v[88:91], v[72:75], 0
	v_mfma_f32_16x16x32_bf16 v[20:23], v[92:95], v[76:79], v[20:23]
	s_waitcnt lgkmcnt(0)
	s_add_i32 s93, s76, 0xfffffe00
	s_mov_b32 m0, s12
	v_add_u32_e32 v164, s93, v231
	v_med3_i32 v164, v164, 0, s40
	v_lshl_or_b32 v164, v164, 7, v222
	global_load_lds_dwordx4 v164, s[24:25]
	s_add_i32 m0, s12, 0x400
	v_add_u32_e32 v165, s93, v232
	v_med3_i32 v165, v165, 0, s40
	v_lshl_or_b32 v165, v165, 7, v222
	global_load_lds_dwordx4 v165, s[24:25]
	s_waitcnt vmcnt(8)
	v_add_u32_e32 v154, s13, v223
	v_add_u32_e32 v155, s13, v224
	ds_read_b128 v[88:91], v154
	ds_read_b128 v[92:95], v155
	v_mfma_f32_16x16x32_bf16 v[24:27], v[202:205], v[72:75], 0
	v_mfma_f32_16x16x32_bf16 v[24:27], v[206:209], v[76:79], v[24:27]
	s_waitcnt lgkmcnt(0)
	s_add_i32 s93, s76, 0xffffff00
	s_mov_b32 m0, s13
	v_add_u32_e32 v164, s93, v231
	v_med3_i32 v164, v164, 0, s40
	v_lshl_or_b32 v164, v164, 7, v222
	global_load_lds_dwordx4 v164, s[24:25]
	s_add_i32 m0, s13, 0x400
	v_add_u32_e32 v165, s93, v232
	v_med3_i32 v165, v165, 0, s40
	v_lshl_or_b32 v165, v165, 7, v222
	global_load_lds_dwordx4 v165, s[24:25]
	s_waitcnt vmcnt(8)
	v_add_u32_e32 v154, s14, v223
	v_add_u32_e32 v155, s14, v224
	ds_read_b128 v[202:205], v154
	ds_read_b128 v[206:209], v155
	v_mfma_f32_16x16x32_bf16 v[28:31], v[88:91], v[72:75], 0
	v_mfma_f32_16x16x32_bf16 v[28:31], v[92:95], v[76:79], v[28:31]
	s_waitcnt lgkmcnt(0)
	s_add_i32 s93, s76, 0
	s_mov_b32 m0, s14
	v_add_u32_e32 v164, s93, v231
	v_med3_i32 v164, v164, 0, s40
	v_lshl_or_b32 v164, v164, 7, v222
	global_load_lds_dwordx4 v164, s[24:25]
	s_add_i32 m0, s14, 0x400
	v_add_u32_e32 v165, s93, v232
	v_med3_i32 v165, v165, 0, s40
	v_lshl_or_b32 v165, v165, 7, v222
	global_load_lds_dwordx4 v165, s[24:25]
	s_waitcnt vmcnt(8)
	v_add_u32_e32 v154, s15, v225
	v_add_u32_e32 v155, s15, v226
	v_add_u32_e32 v156, s15, v227
	v_add_u32_e32 v157, s15, v228
	ds_read_b64_tr_b16 v[88:89], v154
	ds_read_b64_tr_b16 v[90:91], v155
	ds_read_b64_tr_b16 v[92:93], v156
	ds_read_b64_tr_b16 v[94:95], v157
	v_mfma_f32_16x16x32_bf16 v[32:35], v[202:205], v[72:75], 0
	v_mfma_f32_16x16x32_bf16 v[32:35], v[206:209], v[76:79], v[32:35]
	v_mov_b32_e32 v188, s85
	v_lshl_add_u32 v188, v216, 4, v188
	v_lshrrev_b32_e32 v146, 4, v188
	v_xor_b32_e32 v146, v146, v188
	v_and_b32_e32 v146, 15, v146
	v_lshlrev_b32_e32 v147, 8, v188
	v_or_b32_e32 v148, 0, v217
	v_xor_b32_e32 v148, v148, v146
	v_lshl_add_u32 v190, v148, 4, v147
	v_or_b32_e32 v148, 4, v217
	v_xor_b32_e32 v148, v148, v146
	v_lshl_add_u32 v191, v148, 4, v147
	v_or_b32_e32 v148, 8, v217
	v_xor_b32_e32 v148, v148, v146
	v_lshl_add_u32 v192, v148, 4, v147
	v_or_b32_e32 v148, 12, v217
	v_xor_b32_e32 v148, v148, v146
	v_lshl_add_u32 v193, v148, 4, v147
	v_lshlrev_b32_e32 v194, 3, v188
	v_add_u32_e32 v194, 0x10000, v194
	ds_read_b64 v[144:145], v194
	ds_read_b128 v[128:131], v190
	ds_read_b128 v[132:135], v191
	ds_read_b128 v[136:139], v192
	ds_read_b128 v[140:143], v193
	s_add_i32 s90, s76, 0x4f0
	s_cmp_gt_i32 s90, s40
	s_cselect_b32 s96, 1, 0
	s_cmp_lt_i32 s76, 0x400
	s_cselect_b32 s96, 1, s96
	s_ashr_i32 s77, s76, 4
	s_sub_i32 s77, 64, s77
	s_sub_i32 s78, s40, s76
	s_ashr_i32 s78, s78, 4
	s_add_i32 s78, s78, 64
	v_cndmask_b32_e64 v0, v0, v230, s[52:53]
	v_cndmask_b32_e64 v32, v32, v230, s[62:63]
	v_cndmask_b32_e64 v1, v1, v230, s[56:57]
	v_cndmask_b32_e64 v33, v33, v230, s[64:65]
	v_cndmask_b32_e64 v2, v2, v230, s[58:59]
	v_cndmask_b32_e64 v34, v34, v230, s[70:71]
	v_cndmask_b32_e64 v3, v3, v230, s[60:61]
	v_cndmask_b32_e64 v35, v35, v230, s[72:73]
	s_cmp_eq_u32 s96, 0
	s_cbranch_scc1 .Latt_noedge_6
	v_sub_u32_e32 v200, s77, v229
	s_sub_i32 s91, s78, s77
	v_sub_u32_e32 v150, 0, v200
	v_sub_u32_e32 v151, 1, v200
	v_sub_u32_e32 v152, 2, v200
	v_sub_u32_e32 v153, 3, v200
	v_cmp_lt_u32_e64 s[94:95], s91, v150
	v_cmp_lt_u32_e64 s[86:87], s91, v151
	v_cmp_lt_u32_e64 s[0:1], s91, v152
	v_cmp_lt_u32_e64 s[2:3], s91, v153
	v_cndmask_b32_e64 v0, v0, v230, s[94:95]
	v_cndmask_b32_e64 v1, v1, v230, s[86:87]
	v_cndmask_b32_e64 v2, v2, v230, s[0:1]
	v_cndmask_b32_e64 v3, v3, v230, s[2:3]
	v_sub_u32_e32 v150, 16, v200
	v_sub_u32_e32 v151, 17, v200
	v_sub_u32_e32 v152, 18, v200
	v_sub_u32_e32 v153, 19, v200
	v_cmp_lt_u32_e64 s[94:95], s91, v150
	v_cmp_lt_u32_e64 s[86:87], s91, v151
	v_cmp_lt_u32_e64 s[0:1], s91, v152
	v_cmp_lt_u32_e64 s[2:3], s91, v153
	v_cndmask_b32_e64 v4, v4, v230, s[94:95]
	v_cndmask_b32_e64 v5, v5, v230, s[86:87]
	v_cndmask_b32_e64 v6, v6, v230, s[0:1]
	v_cndmask_b32_e64 v7, v7, v230, s[2:3]
	v_sub_u32_e32 v150, 32, v200
	v_sub_u32_e32 v151, 33, v200
	v_sub_u32_e32 v152, 34, v200
	v_sub_u32_e32 v153, 35, v200
	v_cmp_lt_u32_e64 s[94:95], s91, v150
	v_cmp_lt_u32_e64 s[86:87], s91, v151
	v_cmp_lt_u32_e64 s[0:1], s91, v152
	v_cmp_lt_u32_e64 s[2:3], s91, v153
	v_cndmask_b32_e64 v8, v8, v230, s[94:95]
	v_cndmask_b32_e64 v9, v9, v230, s[86:87]
	v_cndmask_b32_e64 v10, v10, v230, s[0:1]
	v_cndmask_b32_e64 v11, v11, v230, s[2:3]
	v_sub_u32_e32 v150, 48, v200
	v_sub_u32_e32 v151, 49, v200
	v_sub_u32_e32 v152, 50, v200
	v_sub_u32_e32 v153, 51, v200
	v_cmp_lt_u32_e64 s[94:95], s91, v150
	v_cmp_lt_u32_e64 s[86:87], s91, v151
	v_cmp_lt_u32_e64 s[0:1], s91, v152
	v_cmp_lt_u32_e64 s[2:3], s91, v153
	v_cndmask_b32_e64 v12, v12, v230, s[94:95]
	v_cndmask_b32_e64 v13, v13, v230, s[86:87]
	v_cndmask_b32_e64 v14, v14, v230, s[0:1]
	v_cndmask_b32_e64 v15, v15, v230, s[2:3]
	v_sub_u32_e32 v150, 64, v200
	v_sub_u32_e32 v151, 0x41, v200
	v_sub_u32_e32 v152, 0x42, v200
	v_sub_u32_e32 v153, 0x43, v200
	v_cmp_lt_u32_e64 s[94:95], s91, v150
	v_cmp_lt_u32_e64 s[86:87], s91, v151
	v_cmp_lt_u32_e64 s[0:1], s91, v152
	v_cmp_lt_u32_e64 s[2:3], s91, v153
	v_cndmask_b32_e64 v16, v16, v230, s[94:95]
	v_cndmask_b32_e64 v17, v17, v230, s[86:87]
	v_cndmask_b32_e64 v18, v18, v230, s[0:1]
	v_cndmask_b32_e64 v19, v19, v230, s[2:3]
	v_sub_u32_e32 v150, 0x50, v200
	v_sub_u32_e32 v151, 0x51, v200
	v_sub_u32_e32 v152, 0x52, v200
	v_sub_u32_e32 v153, 0x53, v200
	v_cmp_lt_u32_e64 s[94:95], s91, v150
	v_cmp_lt_u32_e64 s[86:87], s91, v151
	v_cmp_lt_u32_e64 s[0:1], s91, v152
	v_cmp_lt_u32_e64 s[2:3], s91, v153
	v_cndmask_b32_e64 v20, v20, v230, s[94:95]
	v_cndmask_b32_e64 v21, v21, v230, s[86:87]
	v_cndmask_b32_e64 v22, v22, v230, s[0:1]
	v_cndmask_b32_e64 v23, v23, v230, s[2:3]
	v_sub_u32_e32 v150, 0x60, v200
	v_sub_u32_e32 v151, 0x61, v200
	v_sub_u32_e32 v152, 0x62, v200
	v_sub_u32_e32 v153, 0x63, v200
	v_cmp_lt_u32_e64 s[94:95], s91, v150
	v_cmp_lt_u32_e64 s[86:87], s91, v151
	v_cmp_lt_u32_e64 s[0:1], s91, v152
	v_cmp_lt_u32_e64 s[2:3], s91, v153
	v_cndmask_b32_e64 v24, v24, v230, s[94:95]
	v_cndmask_b32_e64 v25, v25, v230, s[86:87]
	v_cndmask_b32_e64 v26, v26, v230, s[0:1]
	v_cndmask_b32_e64 v27, v27, v230, s[2:3]
	v_sub_u32_e32 v150, 0x70, v200
	v_sub_u32_e32 v151, 0x71, v200
	v_sub_u32_e32 v152, 0x72, v200
	v_sub_u32_e32 v153, 0x73, v200
	v_cmp_lt_u32_e64 s[94:95], s91, v150
	v_cmp_lt_u32_e64 s[86:87], s91, v151
	v_cmp_lt_u32_e64 s[0:1], s91, v152
	v_cmp_lt_u32_e64 s[2:3], s91, v153
	v_cndmask_b32_e64 v28, v28, v230, s[94:95]
	v_cndmask_b32_e64 v29, v29, v230, s[86:87]
	v_cndmask_b32_e64 v30, v30, v230, s[0:1]
	v_cndmask_b32_e64 v31, v31, v230, s[2:3]
	v_sub_u32_e32 v150, 0x80, v200
	v_sub_u32_e32 v151, 0x81, v200
	v_sub_u32_e32 v152, 0x82, v200
	v_sub_u32_e32 v153, 0x83, v200
	v_cmp_lt_u32_e64 s[94:95], s91, v150
	v_cmp_lt_u32_e64 s[86:87], s91, v151
	v_cmp_lt_u32_e64 s[0:1], s91, v152
	v_cmp_lt_u32_e64 s[2:3], s91, v153
	v_cndmask_b32_e64 v32, v32, v230, s[94:95]
	v_cndmask_b32_e64 v33, v33, v230, s[86:87]
	v_cndmask_b32_e64 v34, v34, v230, s[0:1]
	v_cndmask_b32_e64 v35, v35, v230, s[2:3]
.Latt_noedge_6:
	s_nop 1
	v_max3_f32 v184, v0, v1, v2
	v_max3_f32 v184, v184, v3, v4
	v_max3_f32 v184, v184, v5, v6
	v_max3_f32 v184, v184, v7, v8
	v_max3_f32 v184, v184, v9, v10
	v_max3_f32 v184, v184, v11, v12
	v_max3_f32 v184, v184, v13, v14
	v_max3_f32 v184, v184, v15, v16
	v_max3_f32 v184, v184, v17, v18
	v_max3_f32 v184, v184, v19, v20
	v_max3_f32 v184, v184, v21, v22
	v_max3_f32 v184, v184, v23, v24
	v_max3_f32 v184, v184, v25, v26
	v_max3_f32 v184, v184, v27, v28
	v_max3_f32 v184, v184, v29, v30
	v_max3_f32 v184, v184, v31, v32
	v_max3_f32 v184, v184, v33, v34
	v_max_f32_e32 v184, v184, v35
	v_mov_b32_e32 v146, v184
	s_nop 1
	v_permlane16_swap_b32_e32 v184, v146
	v_max_f32_e32 v184, v184, v146
	v_mov_b32_e32 v146, v184
	s_nop 1
	v_permlane32_swap_b32_e32 v184, v146
	v_max_f32_e32 v184, v184, v146
	v_pk_add_f32 v[0:1], v[0:1], v[184:185] op_sel_hi:[1,0] neg_lo:[0,1] neg_hi:[0,1]
	v_pk_add_f32 v[2:3], v[2:3], v[184:185] op_sel_hi:[1,0] neg_lo:[0,1] neg_hi:[0,1]
	v_pk_add_f32 v[4:5], v[4:5], v[184:185] op_sel_hi:[1,0] neg_lo:[0,1] neg_hi:[0,1]
	v_pk_add_f32 v[6:7], v[6:7], v[184:185] op_sel_hi:[1,0] neg_lo:[0,1] neg_hi:[0,1]
	v_exp_f32_e32 v0, v0
	v_exp_f32_e32 v1, v1
	v_exp_f32_e32 v2, v2
	v_exp_f32_e32 v3, v3
	v_pk_add_f32 v[8:9], v[8:9], v[184:185] op_sel_hi:[1,0] neg_lo:[0,1] neg_hi:[0,1]
	v_pk_add_f32 v[10:11], v[10:11], v[184:185] op_sel_hi:[1,0] neg_lo:[0,1] neg_hi:[0,1]
	v_exp_f32_e32 v4, v4
	v_exp_f32_e32 v5, v5
	v_exp_f32_e32 v6, v6
	v_exp_f32_e32 v7, v7
	v_pk_add_f32 v[12:13], v[12:13], v[184:185] op_sel_hi:[1,0] neg_lo:[0,1] neg_hi:[0,1]
	v_pk_add_f32 v[14:15], v[14:15], v[184:185] op_sel_hi:[1,0] neg_lo:[0,1] neg_hi:[0,1]
	v_exp_f32_e32 v8, v8
	v_exp_f32_e32 v9, v9
	v_exp_f32_e32 v10, v10
	v_exp_f32_e32 v11, v11
	v_pk_add_f32 v[16:17], v[16:17], v[184:185] op_sel_hi:[1,0] neg_lo:[0,1] neg_hi:[0,1]
	v_pk_add_f32 v[18:19], v[18:19], v[184:185] op_sel_hi:[1,0] neg_lo:[0,1] neg_hi:[0,1]
	v_exp_f32_e32 v12, v12
	v_exp_f32_e32 v13, v13
	v_exp_f32_e32 v14, v14
	v_exp_f32_e32 v15, v15
	v_pk_add_f32 v[20:21], v[20:21], v[184:185] op_sel_hi:[1,0] neg_lo:[0,1] neg_hi:[0,1]
	v_pk_add_f32 v[22:23], v[22:23], v[184:185] op_sel_hi:[1,0] neg_lo:[0,1] neg_hi:[0,1]
	v_exp_f32_e32 v16, v16
	v_exp_f32_e32 v17, v17
	v_exp_f32_e32 v18, v18
	v_exp_f32_e32 v19, v19
	v_pk_add_f32 v[24:25], v[24:25], v[184:185] op_sel_hi:[1,0] neg_lo:[0,1] neg_hi:[0,1]
	v_pk_add_f32 v[26:27], v[26:27], v[184:185] op_sel_hi:[1,0] neg_lo:[0,1] neg_hi:[0,1]
	v_exp_f32_e32 v20, v20
	v_exp_f32_e32 v21, v21
	v_exp_f32_e32 v22, v22
	v_exp_f32_e32 v23, v23
	v_pk_add_f32 v[28:29], v[28:29], v[184:185] op_sel_hi:[1,0] neg_lo:[0,1] neg_hi:[0,1]
	v_pk_add_f32 v[30:31], v[30:31], v[184:185] op_sel_hi:[1,0] neg_lo:[0,1] neg_hi:[0,1]
	v_exp_f32_e32 v24, v24
	v_exp_f32_e32 v25, v25
	v_exp_f32_e32 v26, v26
	v_exp_f32_e32 v27, v27
	v_pk_add_f32 v[32:33], v[32:33], v[184:185] op_sel_hi:[1,0] neg_lo:[0,1] neg_hi:[0,1]
	v_pk_add_f32 v[34:35], v[34:35], v[184:185] op_sel_hi:[1,0] neg_lo:[0,1] neg_hi:[0,1]
	v_exp_f32_e32 v28, v28
	v_exp_f32_e32 v29, v29
	v_exp_f32_e32 v30, v30
	v_exp_f32_e32 v31, v31
	v_exp_f32_e32 v32, v32
	v_exp_f32_e32 v33, v33
	v_exp_f32_e32 v34, v34
	v_exp_f32_e32 v35, v35
	s_nop 0
	v_pk_add_f32 v[146:147], v[0:1], v[2:3]
	v_pk_add_f32 v[148:149], v[4:5], v[6:7]
	v_pk_add_f32 v[146:147], v[146:147], v[8:9]
	v_pk_add_f32 v[148:149], v[148:149], v[10:11]
	v_pk_add_f32 v[146:147], v[146:147], v[12:13]
	v_pk_add_f32 v[148:149], v[148:149], v[14:15]
	v_pk_add_f32 v[146:147], v[146:147], v[16:17]
	v_pk_add_f32 v[148:149], v[148:149], v[18:19]
	v_pk_add_f32 v[146:147], v[146:147], v[20:21]
	v_pk_add_f32 v[148:149], v[148:149], v[22:23]
	v_pk_add_f32 v[146:147], v[146:147], v[24:25]
	v_pk_add_f32 v[148:149], v[148:149], v[26:27]
	v_pk_add_f32 v[146:147], v[146:147], v[28:29]
	v_pk_add_f32 v[148:149], v[148:149], v[30:31]
	v_pk_add_f32 v[146:147], v[146:147], v[32:33]
	v_pk_add_f32 v[148:149], v[148:149], v[34:35]
	s_nop 0
	v_pk_add_f32 v[146:147], v[146:147], v[148:149]
	s_nop 0
	v_add_f32_e32 v185, v146, v147
	v_cvt_pk_bf16_f32 v0, v0, v1
	v_cvt_pk_bf16_f32 v1, v2, v3
	v_cvt_pk_bf16_f32 v4, v4, v5
	v_cvt_pk_bf16_f32 v5, v6, v7
	v_cvt_pk_bf16_f32 v8, v8, v9
	v_cvt_pk_bf16_f32 v9, v10, v11
	v_cvt_pk_bf16_f32 v12, v12, v13
	v_cvt_pk_bf16_f32 v13, v14, v15
	v_cvt_pk_bf16_f32 v16, v16, v17
	v_cvt_pk_bf16_f32 v17, v18, v19
	v_cvt_pk_bf16_f32 v20, v20, v21
	v_cvt_pk_bf16_f32 v21, v22, v23
	v_cvt_pk_bf16_f32 v24, v24, v25
	v_cvt_pk_bf16_f32 v25, v26, v27
	v_cvt_pk_bf16_f32 v28, v28, v29
	v_cvt_pk_bf16_f32 v29, v30, v31
	v_cvt_pk_bf16_f32 v32, v32, v33
	v_cvt_pk_bf16_f32 v33, v34, v35
	v_mov_b32_e32 v146, v185
	s_nop 1
	v_permlane16_swap_b32_e32 v185, v146
	v_add_f32_e32 v185, v185, v146
	v_mov_b32_e32 v146, v185
	s_nop 1
	v_permlane32_swap_b32_e32 v185, v146
	v_add_f32_e32 v185, v185, v146
	s_waitcnt lgkmcnt(0)
	s_add_i32 s93, s76, 0x100
	s_mov_b32 m0, s15
	v_add_u32_e32 v164, s93, v231
	v_med3_i32 v164, v164, 0, s40
	v_lshl_or_b32 v164, v164, 7, v222
	global_load_lds_dwordx4 v164, s[24:25]
	s_add_i32 m0, s15, 0x400
	v_add_u32_e32 v165, s93, v232
	v_med3_i32 v165, v165, 0, s40
	v_lshl_or_b32 v165, v165, 7, v222
	global_load_lds_dwordx4 v165, s[24:25]
	s_waitcnt vmcnt(8)
	v_add_u32_e32 v154, s16, v225
	v_add_u32_e32 v155, s16, v226
	v_add_u32_e32 v156, s16, v227
	v_add_u32_e32 v157, s16, v228
	ds_read_b64_tr_b16 v[202:203], v154
	ds_read_b64_tr_b16 v[204:205], v155
	ds_read_b64_tr_b16 v[206:207], v156
	ds_read_b64_tr_b16 v[208:209], v157
	v_mfma_f32_16x16x16_bf16 v[96:99], v[88:89], v[0:1], 0
	v_mfma_f32_16x16x16_bf16 v[100:103], v[90:91], v[0:1], 0
	v_mfma_f32_16x16x16_bf16 v[104:107], v[92:93], v[0:1], 0
	v_mfma_f32_16x16x16_bf16 v[108:111], v[94:95], v[0:1], 0
	s_waitcnt lgkmcnt(0)
	s_add_i32 s93, s76, 0x200
	s_mov_b32 m0, s16
	v_add_u32_e32 v164, s93, v231
	v_med3_i32 v164, v164, 0, s40
	v_lshl_or_b32 v164, v164, 7, v222
	global_load_lds_dwordx4 v164, s[24:25]
	s_add_i32 m0, s16, 0x400
	v_add_u32_e32 v165, s93, v232
	v_med3_i32 v165, v165, 0, s40
	v_lshl_or_b32 v165, v165, 7, v222
	global_load_lds_dwordx4 v165, s[24:25]
	s_waitcnt vmcnt(8)
	v_add_u32_e32 v154, s12, v225
	v_add_u32_e32 v155, s12, v226
	v_add_u32_e32 v156, s12, v227
	v_add_u32_e32 v157, s12, v228
	ds_read_b64_tr_b16 v[88:89], v154
	ds_read_b64_tr_b16 v[90:91], v155
	ds_read_b64_tr_b16 v[92:93], v156
	ds_read_b64_tr_b16 v[94:95], v157
	v_mfma_f32_16x16x16_bf16 v[96:99], v[202:203], v[4:5], v[96:99]
	v_mfma_f32_16x16x16_bf16 v[100:103], v[204:205], v[4:5], v[100:103]
	v_mfma_f32_16x16x16_bf16 v[104:107], v[206:207], v[4:5], v[104:107]
	v_mfma_f32_16x16x16_bf16 v[108:111], v[208:209], v[4:5], v[108:111]
	s_waitcnt lgkmcnt(0)
	s_add_i32 s93, s76, 0x300
	s_mov_b32 m0, s12
	v_add_u32_e32 v164, s93, v231
	v_med3_i32 v164, v164, 0, s40
	v_lshl_or_b32 v164, v164, 7, v222
	global_load_lds_dwordx4 v164, s[24:25]
	s_add_i32 m0, s12, 0x400
	v_add_u32_e32 v165, s93, v232
	v_med3_i32 v165, v165, 0, s40
	v_lshl_or_b32 v165, v165, 7, v222
	global_load_lds_dwordx4 v165, s[24:25]
	s_waitcnt vmcnt(8)
	v_add_u32_e32 v154, s13, v225
	v_add_u32_e32 v155, s13, v226
	v_add_u32_e32 v156, s13, v227
	v_add_u32_e32 v157, s13, v228
	ds_read_b64_tr_b16 v[202:203], v154
	ds_read_b64_tr_b16 v[204:205], v155
	ds_read_b64_tr_b16 v[206:207], v156
	ds_read_b64_tr_b16 v[208:209], v157
	v_mfma_f32_16x16x16_bf16 v[96:99], v[88:89], v[8:9], v[96:99]
	v_mfma_f32_16x16x16_bf16 v[100:103], v[90:91], v[8:9], v[100:103]
	v_mfma_f32_16x16x16_bf16 v[104:107], v[92:93], v[8:9], v[104:107]
	v_mfma_f32_16x16x16_bf16 v[108:111], v[94:95], v[8:9], v[108:111]
	s_waitcnt lgkmcnt(0)
	s_add_i32 s93, s76, 0x400
	s_mov_b32 m0, s13
	v_add_u32_e32 v164, s93, v231
	v_med3_i32 v164, v164, 0, s40
	v_lshl_or_b32 v164, v164, 7, v222
	global_load_lds_dwordx4 v164, s[24:25]
	s_add_i32 m0, s13, 0x400
	v_add_u32_e32 v165, s93, v232
	v_med3_i32 v165, v165, 0, s40
	v_lshl_or_b32 v165, v165, 7, v222
	global_load_lds_dwordx4 v165, s[24:25]
	s_waitcnt vmcnt(8)
	v_add_u32_e32 v154, s14, v225
	v_add_u32_e32 v155, s14, v226
	v_add_u32_e32 v156, s14, v227
	v_add_u32_e32 v157, s14, v228
	ds_read_b64_tr_b16 v[88:89], v154
	ds_read_b64_tr_b16 v[90:91], v155
	ds_read_b64_tr_b16 v[92:93], v156
	ds_read_b64_tr_b16 v[94:95], v157
	v_mfma_f32_16x16x16_bf16 v[96:99], v[202:203], v[12:13], v[96:99]
	v_mfma_f32_16x16x16_bf16 v[100:103], v[204:205], v[12:13], v[100:103]
	v_mfma_f32_16x16x16_bf16 v[104:107], v[206:207], v[12:13], v[104:107]
	v_mfma_f32_16x16x16_bf16 v[108:111], v[208:209], v[12:13], v[108:111]
	s_waitcnt lgkmcnt(0)
	s_add_i32 s93, s79, 0
	s_mov_b32 m0, s14
	v_add_u32_e32 v164, s93, v162
	v_lshl_or_b32 v164, v164, 7, v220
	global_load_lds_dwordx4 v164, s[30:31]
	s_add_i32 m0, s14, 0x400
	v_add_u32_e32 v165, s93, v163
	v_lshl_or_b32 v165, v165, 7, v221
	global_load_lds_dwordx4 v165, s[30:31]
	s_waitcnt vmcnt(8)
	v_add_u32_e32 v154, s15, v225
	v_add_u32_e32 v155, s15, v226
	v_add_u32_e32 v156, s15, v227
	v_add_u32_e32 v157, s15, v228
	ds_read_b64_tr_b16 v[202:203], v154
	ds_read_b64_tr_b16 v[204:205], v155
	ds_read_b64_tr_b16 v[206:207], v156
	ds_read_b64_tr_b16 v[208:209], v157
	v_mfma_f32_16x16x16_bf16 v[96:99], v[88:89], v[16:17], v[96:99]
	v_mfma_f32_16x16x16_bf16 v[100:103], v[90:91], v[16:17], v[100:103]
	v_mfma_f32_16x16x16_bf16 v[104:107], v[92:93], v[16:17], v[104:107]
	v_mfma_f32_16x16x16_bf16 v[108:111], v[94:95], v[16:17], v[108:111]
	s_waitcnt lgkmcnt(0)
	s_add_i32 s93, s79, 16
	s_mov_b32 m0, s15
	v_add_u32_e32 v164, s93, v162
	v_lshl_or_b32 v164, v164, 7, v220
	global_load_lds_dwordx4 v164, s[30:31]
	s_add_i32 m0, s15, 0x400
	v_add_u32_e32 v165, s93, v163
	v_lshl_or_b32 v165, v165, 7, v221
	global_load_lds_dwordx4 v165, s[30:31]
	s_waitcnt vmcnt(8)
	v_add_u32_e32 v154, s16, v225
	v_add_u32_e32 v155, s16, v226
	v_add_u32_e32 v156, s16, v227
	v_add_u32_e32 v157, s16, v228
	ds_read_b64_tr_b16 v[88:89], v154
	ds_read_b64_tr_b16 v[90:91], v155
	ds_read_b64_tr_b16 v[92:93], v156
	ds_read_b64_tr_b16 v[94:95], v157
	v_mfma_f32_16x16x16_bf16 v[96:99], v[202:203], v[20:21], v[96:99]
	v_mfma_f32_16x16x16_bf16 v[100:103], v[204:205], v[20:21], v[100:103]
	v_mfma_f32_16x16x16_bf16 v[104:107], v[206:207], v[20:21], v[104:107]
	v_mfma_f32_16x16x16_bf16 v[108:111], v[208:209], v[20:21], v[108:111]
	s_waitcnt lgkmcnt(0)
	s_add_i32 s93, s79, 0xffffffc0
	s_mov_b32 m0, s16
	v_add_u32_e32 v164, s93, v162
	v_med3_i32 v164, v164, 0, s41
	v_lshl_or_b32 v164, v164, 7, v220
	global_load_lds_dwordx4 v164, s[34:35]
	s_add_i32 m0, s16, 0x400
	v_add_u32_e32 v165, s93, v163
	v_med3_i32 v165, v165, 0, s41
	v_lshl_or_b32 v165, v165, 7, v221
	global_load_lds_dwordx4 v165, s[34:35]
	s_waitcnt vmcnt(8)
	v_add_u32_e32 v154, s12, v225
	v_add_u32_e32 v155, s12, v226
	v_add_u32_e32 v156, s12, v227
	v_add_u32_e32 v157, s12, v228
	ds_read_b64_tr_b16 v[202:203], v154
	ds_read_b64_tr_b16 v[204:205], v155
	ds_read_b64_tr_b16 v[206:207], v156
	ds_read_b64_tr_b16 v[208:209], v157
	v_mfma_f32_16x16x16_bf16 v[96:99], v[88:89], v[24:25], v[96:99]
	v_mfma_f32_16x16x16_bf16 v[100:103], v[90:91], v[24:25], v[100:103]
	v_mfma_f32_16x16x16_bf16 v[104:107], v[92:93], v[24:25], v[104:107]
	v_mfma_f32_16x16x16_bf16 v[108:111], v[94:95], v[24:25], v[108:111]
	s_waitcnt lgkmcnt(0)
	s_add_i32 s93, s79, 0xffffffd0
	s_mov_b32 m0, s12
	v_add_u32_e32 v164, s93, v162
	v_med3_i32 v164, v164, 0, s41
	v_lshl_or_b32 v164, v164, 7, v220
	global_load_lds_dwordx4 v164, s[34:35]
	s_add_i32 m0, s12, 0x400
	v_add_u32_e32 v165, s93, v163
	v_med3_i32 v165, v165, 0, s41
	v_lshl_or_b32 v165, v165, 7, v221
	global_load_lds_dwordx4 v165, s[34:35]
	s_waitcnt vmcnt(8)
	v_add_u32_e32 v154, s13, v225
	v_add_u32_e32 v155, s13, v226
	v_add_u32_e32 v156, s13, v227
	v_add_u32_e32 v157, s13, v228
	ds_read_b64_tr_b16 v[88:89], v154
	ds_read_b64_tr_b16 v[90:91], v155
	ds_read_b64_tr_b16 v[92:93], v156
	ds_read_b64_tr_b16 v[94:95], v157
	v_mfma_f32_16x16x16_bf16 v[96:99], v[202:203], v[28:29], v[96:99]
	v_mfma_f32_16x16x16_bf16 v[100:103], v[204:205], v[28:29], v[100:103]
	v_mfma_f32_16x16x16_bf16 v[104:107], v[206:207], v[28:29], v[104:107]
	v_mfma_f32_16x16x16_bf16 v[108:111], v[208:209], v[28:29], v[108:111]
	s_waitcnt lgkmcnt(0)
	s_add_i32 s93, s79, 0xffffffe0
	s_mov_b32 m0, s13
	v_add_u32_e32 v164, s93, v162
	v_med3_i32 v164, v164, 0, s41
	v_lshl_or_b32 v164, v164, 7, v220
	global_load_lds_dwordx4 v164, s[34:35]
	s_add_i32 m0, s13, 0x400
	v_add_u32_e32 v165, s93, v163
	v_med3_i32 v165, v165, 0, s41
	v_lshl_or_b32 v165, v165, 7, v221
	global_load_lds_dwordx4 v165, s[34:35]
	v_mfma_f32_16x16x16_bf16 v[96:99], v[88:89], v[32:33], v[96:99]
	v_mfma_f32_16x16x16_bf16 v[100:103], v[90:91], v[32:33], v[100:103]
	v_mfma_f32_16x16x16_bf16 v[104:107], v[92:93], v[32:33], v[104:107]
	v_mfma_f32_16x16x16_bf16 v[108:111], v[94:95], v[32:33], v[108:111]
	s_waitcnt lgkmcnt(0)
	v_max_f32_e32 v146, v144, v184
	v_sub_f32_e32 v148, v144, v146
	v_sub_f32_e32 v150, v184, v146
	v_exp_f32_e32 v148, v148
	v_exp_f32_e32 v150, v150
	v_mov_b32_e32 v184, v146
	v_mul_f32_e32 v185, v185, v150
	v_fmac_f32_e32 v185, v145, v148
	v_pk_mul_f32 v[96:97], v[150:151], v[96:97] op_sel_hi:[0,1]
	v_pk_mul_f32 v[98:99], v[150:151], v[98:99] op_sel_hi:[0,1]
	v_pk_mul_f32 v[100:101], v[150:151], v[100:101] op_sel_hi:[0,1]
	v_pk_mul_f32 v[102:103], v[150:151], v[102:103] op_sel_hi:[0,1]
	v_pk_mul_f32 v[104:105], v[150:151], v[104:105] op_sel_hi:[0,1]
	v_pk_mul_f32 v[106:107], v[150:151], v[106:107] op_sel_hi:[0,1]
	v_pk_mul_f32 v[108:109], v[150:151], v[108:109] op_sel_hi:[0,1]
	v_pk_mul_f32 v[110:111], v[150:151], v[110:111] op_sel_hi:[0,1]
	v_pk_fma_f32 v[96:97], v[148:149], v[128:129], v[96:97] op_sel_hi:[0,1,1]
	v_pk_fma_f32 v[98:99], v[148:149], v[130:131], v[98:99] op_sel_hi:[0,1,1]
	v_pk_fma_f32 v[100:101], v[148:149], v[132:133], v[100:101] op_sel_hi:[0,1,1]
	v_pk_fma_f32 v[102:103], v[148:149], v[134:135], v[102:103] op_sel_hi:[0,1,1]
	v_pk_fma_f32 v[104:105], v[148:149], v[136:137], v[104:105] op_sel_hi:[0,1,1]
	v_pk_fma_f32 v[106:107], v[148:149], v[138:139], v[106:107] op_sel_hi:[0,1,1]
	v_pk_fma_f32 v[108:109], v[148:149], v[140:141], v[108:109] op_sel_hi:[0,1,1]
	v_pk_fma_f32 v[110:111], v[148:149], v[142:143], v[110:111] op_sel_hi:[0,1,1]
	v_div_scale_f32 v147, s[94:95], v185, v185, 1.0
	v_rcp_f32_e32 v148, v147
	v_div_scale_f32 v149, vcc, 1.0, v185, 1.0
	v_fma_f32 v150, -v147, v148, 1.0
	v_fmac_f32_e32 v148, v150, v148
	v_mul_f32_e32 v150, v149, v148
	v_fma_f32 v151, -v147, v150, v149
	v_fmac_f32_e32 v150, v151, v148
	v_fma_f32 v147, -v147, v150, v149
	s_nop 1
	v_div_fmas_f32 v147, v147, v148, v150
	v_div_fixup_f32 v152, v147, v185, 1.0
	v_pk_mul_f32 v[96:97], v[152:153], v[96:97] op_sel_hi:[0,1]
	v_pk_mul_f32 v[98:99], v[152:153], v[98:99] op_sel_hi:[0,1]
	v_pk_mul_f32 v[100:101], v[152:153], v[100:101] op_sel_hi:[0,1]
	v_pk_mul_f32 v[102:103], v[152:153], v[102:103] op_sel_hi:[0,1]
	v_pk_mul_f32 v[104:105], v[152:153], v[104:105] op_sel_hi:[0,1]
	v_pk_mul_f32 v[106:107], v[152:153], v[106:107] op_sel_hi:[0,1]
	v_pk_mul_f32 v[108:109], v[152:153], v[108:109] op_sel_hi:[0,1]
	v_pk_mul_f32 v[110:111], v[152:153], v[110:111] op_sel_hi:[0,1]
	v_mul_f32_e32 v155, v97, v97
	v_mul_f32_e32 v156, v99, v99
	v_fmac_f32_e32 v155, v96, v96
	v_fmac_f32_e32 v156, v98, v98
	v_add_f32_e32 v154, v155, v156
	v_mul_f32_e32 v155, v101, v101
	v_mul_f32_e32 v156, v103, v103
	v_fmac_f32_e32 v155, v100, v100
	v_fmac_f32_e32 v156, v102, v102
	v_add_f32_e32 v155, v155, v156
	v_add_f32_e32 v154, v154, v155
	v_mul_f32_e32 v155, v105, v105
	v_mul_f32_e32 v156, v107, v107
	v_fmac_f32_e32 v155, v104, v104
	v_fmac_f32_e32 v156, v106, v106
	v_add_f32_e32 v155, v155, v156
	v_add_f32_e32 v154, v154, v155
	v_mul_f32_e32 v155, v109, v109
	v_mul_f32_e32 v156, v111, v111
	v_fmac_f32_e32 v155, v108, v108
	v_fmac_f32_e32 v156, v110, v110
	v_add_f32_e32 v155, v155, v156
	v_add_f32_e32 v154, v154, v155
	v_cvt_pk_bf16_f32 v96, v96, v97
	v_cvt_pk_bf16_f32 v97, v98, v99
	v_cvt_pk_bf16_f32 v100, v100, v101
	v_cvt_pk_bf16_f32 v101, v102, v103
	v_cvt_pk_bf16_f32 v104, v104, v105
	v_cvt_pk_bf16_f32 v105, v106, v107
	v_cvt_pk_bf16_f32 v108, v108, v109
	v_cvt_pk_bf16_f32 v109, v110, v111
	v_add_u32_e32 v157, s42, v188
	s_lshl_b32 s90, s43, 7
	v_lshlrev_b32_e32 v158, 11, v157
	v_add3_u32 v158, v158, s90, v233
	v_mov_b32_e32 v160, v96
	v_mov_b32_e32 v161, v97
	v_mov_b32_e32 v162, v100
	v_mov_b32_e32 v163, v101
	s_nop 1
	v_permlane16_swap_b32_e32 v160, v162
	v_permlane16_swap_b32_e32 v161, v163
	s_nop 1
	global_store_dwordx4 v158, v[160:163], s[48:49] offset:0
	s_nop 1
	v_mov_b32_e32 v160, v104
	v_mov_b32_e32 v161, v105
	v_mov_b32_e32 v162, v108
	v_mov_b32_e32 v163, v109
	s_nop 1
	v_permlane16_swap_b32_e32 v160, v162
	v_permlane16_swap_b32_e32 v161, v163
	s_nop 1
	global_store_dwordx4 v158, v[160:163], s[48:49] offset:64
	s_nop 1
	v_mov_b32_e32 v155, v154
	s_nop 1
	v_permlane16_swap_b32_e32 v154, v155
	v_add_f32_e32 v154, v154, v155
	v_mov_b32_e32 v155, v154
	s_nop 1
	v_permlane32_swap_b32_e32 v154, v155
	v_add_f32_e32 v154, v154, v155
	v_mul_u32_u24_e32 v157, 48, v157
	s_lshl_b32 s90, s43, 2
	v_add_u32_e32 v157, s90, v157
	s_and_saveexec_b64 s[80:81], s[74:75]
	global_store_dword v157, v154, s[50:51]
	s_mov_b64 exec, s[80:81]
	s_waitcnt lgkmcnt(0)
	s_barrier
	s_mov_b32 s90, s14
	s_mov_b32 s91, s15
	s_mov_b32 s92, s16
	s_mov_b32 s93, s12
	s_mov_b32 s97, s13
	s_mov_b32 s12, s90
	s_mov_b32 s13, s91
	s_mov_b32 s14, s92
	s_mov_b32 s15, s93
	s_mov_b32 s16, s97
	s_mov_b64 s[18:19], s[30:31]
	s_mov_b64 s[20:21], s[34:35]
	s_mov_b64 s[24:25], s[36:37]
	s_mov_b32 s38, s39
	s_mov_b32 s40, s41
	s_mov_b32 s42, s44
	s_mov_b32 s43, s45
	s_add_i32 s11, s11, s66
	s_cmpk_lt_u32 s11, 0x900
	s_cbranch_scc1 .Latt_unit
	v_readlane_b32 s0, v244, 20
	s_bfe_u32 s3, s0, 0x20006
.LBB0_320:
	v_readlane_b32 s2, v244, 31
	s_waitcnt vmcnt(0)
	s_cmpk_lt_i32 s2, 0x300
	s_cselect_b64 s[8:9], -1, 0
	v_readlane_b32 s72, v244, 32
	v_readlane_b32 s50, v244, 36
	v_readlane_b32 s70, v244, 2
	v_readlane_b32 s76, v244, 38
	v_mov_b32_e32 v55, v214
	s_and_b64 vcc, exec, s[8:9]
	v_readlane_b32 s49, v244, 28
	v_readlane_b32 s73, v244, 33
	v_readlane_b32 s74, v244, 34
	v_readlane_b32 s75, v244, 35
	v_readlane_b32 s51, v244, 37
	v_readlane_b32 s64, v244, 30
	v_readlane_b32 s65, v244, 29
	v_readlane_b32 s71, v244, 3
	v_readlane_b32 s77, v244, 39
	s_waitcnt vmcnt(0) lgkmcnt(0)
	s_barrier
	s_cbranch_vccz .LBB0_336
	v_bfe_u32 v34, v55, 4, 2
	s_lshl_b32 s0, s3, 12
	v_lshlrev_b32_e32 v0, 9, v34
	v_and_b32_e32 v35, 15, v55
	v_or3_b32 v0, s0, v0, v35
	v_lshlrev_b32_e32 v32, 2, v0
	v_mov_b32_e32 v33, 0
	v_lshl_add_u64 v[0:1], s[26:27], 0, v[32:33]
	v_add_co_u32_e32 v14, vcc, 0x2000, v0
	global_load_dword v0, v32, s[26:27] offset:448
	global_load_dword v2, v32, s[26:27] offset:192
	v_addc_co_u32_e32 v15, vcc, 0, v1, vcc
	global_load_dword v1, v[14:15], off offset:448
	global_load_dword v3, v[14:15], off offset:192
	global_load_dword v4, v[14:15], off offset:960
	global_load_dword v5, v[14:15], off offset:704
	global_load_dword v6, v[14:15], off offset:1472
	global_load_dword v7, v[14:15], off offset:1216
	global_load_dword v8, v[14:15], off offset:1984
	global_load_dword v9, v[14:15], off offset:1728
	global_load_dword v10, v32, s[26:27] offset:960
	global_load_dword v11, v32, s[26:27] offset:704
	global_load_dword v12, v32, s[26:27] offset:1472
	global_load_dword v13, v32, s[26:27] offset:1216
	global_load_dword v16, v32, s[26:27] offset:1984
	global_load_dword v17, v32, s[26:27] offset:1728
	global_load_dword v18, v[14:15], off offset:384
	global_load_dword v19, v[14:15], off offset:320
	global_load_dword v24, v[14:15], off offset:256
	global_load_dword v20, v[14:15], off offset:128
	global_load_dword v21, v32, s[26:27] offset:384
	global_load_dword v22, v32, s[26:27] offset:320
	global_load_dword v28, v32, s[26:27] offset:256
	global_load_dword v23, v32, s[26:27] offset:128
	global_load_dword v25, v[14:15], off offset:896
	global_load_dword v26, v[14:15], off offset:832
	global_load_dword v27, v[14:15], off offset:768
	global_load_dword v29, v[14:15], off offset:640
	global_load_dword v30, v32, s[26:27] offset:896
	global_load_dword v31, v32, s[26:27] offset:832
	global_load_dword v36, v32, s[26:27] offset:768
	global_load_dword v37, v32, s[26:27] offset:640
	global_load_dword v38, v[14:15], off offset:1408
	global_load_dword v39, v[14:15], off offset:1344
	global_load_dword v40, v[14:15], off offset:1280
	global_load_dword v41, v[14:15], off offset:1152
	global_load_dword v42, v32, s[26:27] offset:1408
	global_load_dword v43, v32, s[26:27] offset:1344
	global_load_dword v44, v32, s[26:27] offset:1280
	global_load_dword v45, v32, s[26:27] offset:1152
	global_load_dword v46, v[14:15], off offset:1920
	global_load_dword v47, v[14:15], off offset:1856
	global_load_dword v48, v[14:15], off offset:1792
	global_load_dword v49, v[14:15], off offset:1664
	global_load_dword v50, v32, s[26:27] offset:1920
	global_load_dword v51, v32, s[26:27] offset:1856
	global_load_dword v52, v32, s[26:27] offset:1792
	global_load_dword v53, v32, s[26:27] offset:1664
	s_movk_i32 s14, 0x7fff
	s_mov_b32 s15, 0xffff0000
	v_readlane_b32 s4, v244, 20
	s_movk_i32 s16, 0x210
	s_lshr_b32 s4, s4, 3
	s_and_b32 s4, s4, 0x1fffffe0
	s_lshl_b32 s6, s3, 7
	v_or_b32_e32 v83, s4, v35
	s_add_i32 s4, s6, 0
	s_movk_i32 s0, 0xa00
	v_or_b32_e32 v87, 16, v83
	v_cmp_gt_i32_e64 s[0:1], s0, v55
	v_lshlrev_b32_e32 v86, 4, v83
	v_lshlrev_b32_e32 v88, 4, v87
	s_movk_i32 s19, 0xf800
	s_movk_i32 s24, 0x800
	s_movk_i32 s25, 0x7ff
	v_mov_b32_e32 v91, 0x358637bd
	v_mov_b32_e32 v92, 0x260
	s_waitcnt vmcnt(43)
	v_bfe_u32 v57, v4, 16, 1
	s_waitcnt vmcnt(42)
	v_bfe_u32 v58, v5, 16, 1
	s_waitcnt vmcnt(41)
	v_bfe_u32 v59, v6, 16, 1
	s_waitcnt vmcnt(40)
	v_bfe_u32 v60, v7, 16, 1
	s_waitcnt vmcnt(39)
	v_bfe_u32 v61, v8, 16, 1
	s_waitcnt vmcnt(38)
	v_bfe_u32 v62, v9, 16, 1
	v_bfe_u32 v54, v0, 16, 1
	v_bfe_u32 v56, v2, 16, 1
	v_add3_u32 v54, v0, v54, s14
	v_add3_u32 v56, v2, v56, s14
	v_bfe_u32 v0, v1, 16, 1
	v_bfe_u32 v2, v3, 16, 1
	v_add3_u32 v0, v1, v0, s14
	v_add3_u32 v1, v3, v2, s14
	v_add3_u32 v3, v5, v58, s14
	v_add3_u32 v5, v7, v60, s14
	v_add3_u32 v2, v4, v57, s14
	v_add3_u32 v4, v6, v59, s14
	v_lshrrev_b32_e32 v1, 16, v1
	v_lshrrev_b32_e32 v3, 16, v3
	v_lshrrev_b32_e32 v5, 16, v5
	v_and_or_b32 v0, v0, s15, v1
	v_and_or_b32 v1, v2, s15, v3
	v_and_or_b32 v2, v4, s15, v5
	v_lshrrev_b32_e32 v4, 16, v56
	v_add3_u32 v7, v9, v62, s14
	v_and_or_b32 v4, v54, s15, v4
	global_load_dword v54, v[14:15], off offset:64
	v_add3_u32 v6, v8, v61, s14
	v_lshrrev_b32_e32 v7, 16, v7
	v_and_or_b32 v3, v6, s15, v7
	s_waitcnt vmcnt(37)
	v_bfe_u32 v6, v11, 16, 1
	global_load_dword v56, v[14:15], off offset:576
	global_load_dword v57, v[14:15], off offset:1088
	global_load_dword v58, v[14:15], off offset:1600
	v_bfe_u32 v5, v10, 16, 1
	v_add3_u32 v6, v11, v6, s14
	v_add3_u32 v5, v10, v5, s14
	v_lshrrev_b32_e32 v6, 16, v6
	s_waitcnt vmcnt(38)
	v_bfe_u32 v7, v13, 16, 1
	v_and_or_b32 v5, v5, s15, v6
	v_bfe_u32 v6, v12, 16, 1
	v_add3_u32 v7, v13, v7, s14
	v_add3_u32 v6, v12, v6, s14
	v_lshrrev_b32_e32 v7, 16, v7
	s_waitcnt vmcnt(36)
	v_bfe_u32 v8, v17, 16, 1
	v_and_or_b32 v6, v6, s15, v7
	v_bfe_u32 v7, v16, 16, 1
	v_add3_u32 v8, v17, v8, s14
	v_add3_u32 v7, v16, v7, s14
	v_lshrrev_b32_e32 v8, 16, v8
	s_waitcnt vmcnt(32)
	v_bfe_u32 v9, v20, 16, 1
	v_and_or_b32 v7, v7, s15, v8
	v_bfe_u32 v8, v18, 16, 1
	v_add3_u32 v9, v20, v9, s14
	v_add3_u32 v8, v18, v8, s14
	v_lshrrev_b32_e32 v9, 16, v9
	global_load_dword v20, v32, s[26:27] offset:64
	v_and_or_b32 v8, v8, s15, v9
	s_waitcnt vmcnt(28)
	v_bfe_u32 v9, v25, 16, 1
	v_add3_u32 v9, v25, v9, s14
	s_waitcnt vmcnt(25)
	v_bfe_u32 v10, v29, 16, 1
	global_load_dword v25, v32, s[26:27] offset:576
	v_add3_u32 v10, v29, v10, s14
	v_lshrrev_b32_e32 v10, 16, v10
	s_waitcnt vmcnt(18)
	v_bfe_u32 v11, v41, 16, 1
	global_load_dword v29, v32, s[26:27] offset:1088
	v_and_or_b32 v9, v9, s15, v10
	v_bfe_u32 v10, v38, 16, 1
	v_add3_u32 v11, v41, v11, s14
	v_add3_u32 v10, v38, v10, s14
	v_lshrrev_b32_e32 v11, 16, v11
	s_waitcnt vmcnt(11)
	v_bfe_u32 v12, v49, 16, 1
	global_load_dword v38, v32, s[26:27] offset:1600
	v_and_or_b32 v10, v10, s15, v11
	v_bfe_u32 v11, v46, 16, 1
	v_add3_u32 v12, v49, v12, s14
	v_add3_u32 v11, v46, v11, s14
	v_lshrrev_b32_e32 v12, 16, v12
	v_bfe_u32 v13, v23, 16, 1
	v_and_or_b32 v11, v11, s15, v12
	v_bfe_u32 v12, v21, 16, 1
	v_add3_u32 v13, v23, v13, s14
	v_add3_u32 v12, v21, v12, s14
	global_load_dword v41, v[14:15], off
	v_lshrrev_b32_e32 v13, 16, v13
	v_and_or_b32 v12, v12, s15, v13
	v_bfe_u32 v13, v30, 16, 1
	v_bfe_u32 v16, v37, 16, 1
	v_add3_u32 v13, v30, v13, s14
	v_add3_u32 v16, v37, v16, s14
	global_load_dword v37, v[14:15], off offset:1536
	global_load_dword v30, v[14:15], off offset:1024
	global_load_dword v46, v[14:15], off offset:512
	v_lshrrev_b32_e32 v16, 16, v16
	v_and_or_b32 v13, v13, s15, v16
	v_bfe_u32 v16, v42, 16, 1
	v_bfe_u32 v17, v45, 16, 1
	v_add3_u32 v16, v42, v16, s14
	v_add3_u32 v17, v45, v17, s14
	global_load_dword v49, v32, s[26:27] offset:1024
	global_load_dword v45, v32, s[26:27] offset:512
	global_load_dword v42, v32, s[26:27]
	v_lshrrev_b32_e32 v17, 16, v17
	global_load_dword v32, v32, s[26:27] offset:1536
	v_and_or_b32 v14, v16, s15, v17
	s_waitcnt vmcnt(16)
	v_bfe_u32 v16, v53, 16, 1
	v_bfe_u32 v15, v50, 16, 1
	v_add3_u32 v16, v53, v16, s14
	v_add3_u32 v15, v50, v15, s14
	v_lshrrev_b32_e32 v16, 16, v16
	s_waitcnt vmcnt(15)
	v_bfe_u32 v17, v54, 16, 1
	v_and_or_b32 v15, v15, s15, v16
	v_bfe_u32 v16, v19, 16, 1
	v_add3_u32 v17, v54, v17, s14
	v_add3_u32 v16, v19, v16, s14
	v_lshrrev_b32_e32 v17, 16, v17
	s_waitcnt vmcnt(14)
	v_bfe_u32 v18, v56, 16, 1
	v_and_or_b32 v16, v16, s15, v17
	v_bfe_u32 v17, v26, 16, 1
	v_add3_u32 v18, v56, v18, s14
	v_add3_u32 v17, v26, v17, s14
	v_lshrrev_b32_e32 v18, 16, v18
	s_waitcnt vmcnt(13)
	v_bfe_u32 v19, v57, 16, 1
	v_and_or_b32 v17, v17, s15, v18
	v_bfe_u32 v18, v39, 16, 1
	v_add3_u32 v19, v57, v19, s14
	v_add3_u32 v18, v39, v18, s14
	v_lshrrev_b32_e32 v19, 16, v19
	s_waitcnt vmcnt(12)
	v_bfe_u32 v21, v58, 16, 1
	v_and_or_b32 v18, v18, s15, v19
	v_bfe_u32 v19, v47, 16, 1
	v_add3_u32 v21, v58, v21, s14
	v_add3_u32 v19, v47, v19, s14
	v_lshrrev_b32_e32 v21, 16, v21
	v_and_or_b32 v19, v19, s15, v21
	v_bfe_u32 v21, v22, 16, 1
	v_add3_u32 v21, v22, v21, s14
	s_waitcnt vmcnt(11)
	v_bfe_u32 v22, v20, 16, 1
	v_add3_u32 v20, v20, v22, s14
	v_lshrrev_b32_e32 v20, 16, v20
	v_and_or_b32 v20, v21, s15, v20
	s_waitcnt vmcnt(10)
	v_bfe_u32 v22, v25, 16, 1
	v_bfe_u32 v21, v31, 16, 1
	v_add3_u32 v22, v25, v22, s14
	v_add3_u32 v21, v31, v21, s14
	v_lshrrev_b32_e32 v22, 16, v22
	s_waitcnt vmcnt(9)
	v_bfe_u32 v23, v29, 16, 1
	v_and_or_b32 v21, v21, s15, v22
	v_bfe_u32 v22, v43, 16, 1
	v_add3_u32 v23, v29, v23, s14
	v_add3_u32 v22, v43, v22, s14
	v_lshrrev_b32_e32 v23, 16, v23
	s_waitcnt vmcnt(8)
	v_bfe_u32 v25, v38, 16, 1
	v_and_or_b32 v22, v22, s15, v23
	v_bfe_u32 v23, v51, 16, 1
	v_add3_u32 v25, v38, v25, s14
	v_add3_u32 v23, v51, v23, s14
	v_lshrrev_b32_e32 v25, 16, v25
	v_and_or_b32 v23, v23, s15, v25
	v_bfe_u32 v25, v24, 16, 1
	v_add3_u32 v24, v24, v25, s14
	v_ashrrev_i32_e32 v57, 3, v55
	s_mov_b32 s26, 0xf800000
	s_waitcnt vmcnt(7)
	v_bfe_u32 v25, v41, 16, 1
	v_add3_u32 v25, v41, v25, s14
	v_lshrrev_b32_e32 v25, 16, v25
	v_and_or_b32 v24, v24, s15, v25
	v_bfe_u32 v25, v27, 16, 1
	v_add3_u32 v25, v27, v25, s14
	s_waitcnt vmcnt(6)
	v_bfe_u32 v29, v37, 16, 1
	s_waitcnt vmcnt(5)
	v_bfe_u32 v27, v30, 16, 1
	s_waitcnt vmcnt(4)
	v_bfe_u32 v26, v46, 16, 1
	v_add3_u32 v26, v46, v26, s14
	v_lshrrev_b32_e32 v26, 16, v26
	v_and_or_b32 v25, v25, s15, v26
	v_bfe_u32 v26, v40, 16, 1
	v_add3_u32 v27, v30, v27, s14
	v_add3_u32 v26, v40, v26, s14
	v_lshrrev_b32_e32 v27, 16, v27
	v_and_or_b32 v26, v26, s15, v27
	v_bfe_u32 v27, v48, 16, 1
	v_add3_u32 v29, v37, v29, s14
	v_add3_u32 v27, v48, v27, s14
	v_lshrrev_b32_e32 v29, 16, v29
	v_and_or_b32 v27, v27, s15, v29
	v_bfe_u32 v29, v28, 16, 1
	v_add3_u32 v28, v28, v29, s14
	s_waitcnt vmcnt(1)
	v_bfe_u32 v29, v42, 16, 1
	v_add3_u32 v29, v42, v29, s14
	v_lshrrev_b32_e32 v29, 16, v29
	v_bfe_u32 v30, v45, 16, 1
	v_and_or_b32 v28, v28, s15, v29
	v_bfe_u32 v29, v36, 16, 1
	v_add3_u32 v30, v45, v30, s14
	v_add3_u32 v29, v36, v29, s14
	v_lshrrev_b32_e32 v30, 16, v30
	v_bfe_u32 v31, v49, 16, 1
	v_and_or_b32 v29, v29, s15, v30
	v_bfe_u32 v30, v44, 16, 1
	v_add3_u32 v31, v49, v31, s14
	v_add3_u32 v30, v44, v30, s14
	v_lshrrev_b32_e32 v31, 16, v31
	s_waitcnt vmcnt(0)
	v_bfe_u32 v36, v32, 16, 1
	v_and_or_b32 v30, v30, s15, v31
	v_bfe_u32 v31, v52, 16, 1
	v_add3_u32 v32, v32, v36, s14
	v_add3_u32 v31, v52, v31, s14
	v_lshrrev_b32_e32 v32, 16, v32
	v_and_or_b32 v31, v31, s15, v32
	v_and_b32_e32 v32, 7, v55
	v_bfe_u32 v36, v55, 1, 2
	v_lshlrev_b32_e64 v82, v36, 1
	v_lshlrev_b32_e32 v36, 6, v32
	v_mul_lo_u32 v32, v57, s16
	v_add_u32_e32 v37, 0, v32
	v_lshlrev_b32_e32 v32, 4, v34
	v_add_u32_e32 v38, s4, v32
	s_lshl_b32 s4, s3, 8
	s_add_u32 s4, s28, s4
	s_addc_u32 s5, s29, 0
	v_lshl_add_u64 v[48:49], s[4:5], 0, v[32:33]
	global_load_dwordx4 v[160:163], v[48:49], off
	global_load_dwordx4 v[164:167], v[48:49], off offset:64
	global_load_dwordx4 v[168:171], v[48:49], off offset:192
	global_load_dwordx4 v[172:175], v[48:49], off offset:128
	v_mbcnt_hi_u32_b32 v32, -1, v215
	v_and_b32_e32 v39, 64, v32
	v_xor_b32_e32 v35, 16, v32
	v_add_u32_e32 v39, 64, v39
	v_cmp_lt_i32_e32 vcc, v35, v39
	s_lshl_b32 s3, s3, 2
	s_add_i32 s3, s3, 0
	v_cndmask_b32_e32 v35, v32, v35, vcc
	v_lshlrev_b32_e32 v84, 2, v35
	v_xor_b32_e32 v35, 32, v32
	v_cmp_lt_i32_e32 vcc, v35, v39
	s_add_i32 s3, s3, 0x12900
	s_add_u32 s6, s74, s6
	v_cndmask_b32_e32 v32, v32, v35, vcc
	v_lshlrev_b32_e32 v85, 2, v32
	s_addc_u32 s7, s75, 0
	v_lshlrev_b32_e32 v32, 3, v34
	v_cmp_eq_u32_e64 s[4:5], 0, v34
	v_lshl_add_u64 v[34:35], s[6:7], 0, v[32:33]
	s_mov_b64 s[6:7], 0x18800000
	v_lshl_add_u64 v[50:51], v[34:35], 0, s[6:7]
	v_lshlrev_b32_e32 v32, 4, v55
	v_readlane_b32 s6, v244, 24
	v_and_b32_e32 v32, 0x1f0, v32
	v_readlane_b32 s7, v244, 25
	v_add_u32_e32 v54, 0, v32
	s_lshl_b32 s17, s66, 6
	v_lshl_add_u64 v[52:53], s[6:7], 0, v[32:33]
	v_add_u32_e32 v33, 0, v36
	s_lshl_b32 s6, s2, 6
	v_mul_lo_u32 v32, v83, s16
	v_add_u32_e32 v56, 0x1080, v33
	v_add_u32_e32 v33, s6, v57
	v_sub_u32_e32 v89, v33, v82
	s_sub_i32 s18, 0, s6
	v_add_u32_e32 v90, v37, v36
	v_add_u32_e32 v93, v38, v32
	s_add_i32 s27, 0, 0x12900
	s_mov_b32 s28, s2
	s_lshl_b32 s98, s28, 6
	s_cmpk_lt_i32 s28, 0x100
	s_cselect_b32 s99, s19, 0x7fffc000
	s_cselect_b32 s100, s24, 0x4000
	s_and_b32 s99, s99, s98
	s_sub_i32 s98, s98, s99
	s_add_i32 s98, s98, -8
	v_ashrrev_i32_e32 v128, 5, v55
	v_add_u32_e32 v129, s98, v128
	v_mov_b32_e32 v131, v129
	v_cmp_gt_u32_e32 vcc, s100, v131
	v_add_u32_e32 v152, s99, v131
	v_ashrrev_i32_e32 v153, 31, v152
	v_lshlrev_b64 v[152:153], 9, v[152:153]
	v_lshl_add_u64 v[152:153], v[52:53], 0, v[152:153]
	s_and_saveexec_b64 s[12:13], vcc
	global_load_dwordx4 v[132:135], v[152:153], off
	s_or_b64 exec, exec, s[12:13]
	v_add_u32_e32 v131, 16, v129
	v_cmp_gt_u32_e32 vcc, s100, v131
	v_add_u32_e32 v152, s99, v131
	v_ashrrev_i32_e32 v153, 31, v152
	v_lshlrev_b64 v[152:153], 9, v[152:153]
	v_lshl_add_u64 v[152:153], v[52:53], 0, v[152:153]
	s_and_saveexec_b64 s[12:13], vcc
	global_load_dwordx4 v[136:139], v[152:153], off
	s_or_b64 exec, exec, s[12:13]
	v_add_u32_e32 v131, 32, v129
	v_cmp_gt_u32_e32 vcc, s100, v131
	v_add_u32_e32 v152, s99, v131
	v_ashrrev_i32_e32 v153, 31, v152
	v_lshlrev_b64 v[152:153], 9, v[152:153]
	v_lshl_add_u64 v[152:153], v[52:53], 0, v[152:153]
	s_and_saveexec_b64 s[12:13], vcc
	global_load_dwordx4 v[140:143], v[152:153], off
	s_or_b64 exec, exec, s[12:13]
	v_add_u32_e32 v131, 48, v129
	v_cmp_gt_u32_e32 vcc, s100, v131
	v_add_u32_e32 v152, s99, v131
	v_ashrrev_i32_e32 v153, 31, v152
	v_lshlrev_b64 v[152:153], 9, v[152:153]
	v_lshl_add_u64 v[152:153], v[52:53], 0, v[152:153]
	s_and_saveexec_b64 s[12:13], vcc
	global_load_dwordx4 v[144:147], v[152:153], off
	s_or_b64 exec, exec, s[12:13]
	v_add_u32_e32 v131, 64, v129
	v_cmp_gt_u32_e32 vcc, s100, v131
	v_add_u32_e32 v152, s99, v131
	v_ashrrev_i32_e32 v153, 31, v152
	v_lshlrev_b64 v[152:153], 9, v[152:153]
	v_lshl_add_u64 v[152:153], v[52:53], 0, v[152:153]
	s_and_saveexec_b64 s[12:13], vcc
	global_load_dwordx4 v[148:151], v[152:153], off
	s_or_b64 exec, exec, s[12:13]
	s_branch .LBB0_323

.LBB0_332:
	s_or_b64 exec, exec, s[6:7]
	v_sub_u32_e32 v74, v77, v76
	v_cvt_f32_i32_e32 v94, v74
	ds_read_b128 v[74:77], v90 offset:4224
	ds_read_b128 v[78:81], v90 offset:4240
	v_mov_b32_e32 v104, v72
	v_mov_b32_e32 v105, v70
	v_div_scale_f32 v95, s[6:7], v94, v94, 1.0
	v_rcp_f32_e32 v96, v95
	v_div_scale_f32 v97, vcc, 1.0, v94, 1.0
	v_mov_b32_e32 v70, v73
	v_fma_f32 v98, -v95, v96, 1.0
	v_fmac_f32_e32 v96, v98, v96
	v_mul_f32_e32 v98, v97, v96
	v_fma_f32 v99, -v95, v98, v97
	v_fmac_f32_e32 v98, v99, v96
	v_fma_f32 v95, -v95, v98, v97
	v_div_fmas_f32 v95, v95, v96, v98
	v_div_fixup_f32 v102, v95, v94, 1.0
	s_waitcnt lgkmcnt(1)
	v_and_b32_e32 v73, 0xffff0000, v75
	v_and_b32_e32 v72, 0xffff0000, v74
	v_pk_fma_f32 v[70:71], v[102:103], v[70:71], v[72:73] op_sel_hi:[0,1,1] neg_lo:[0,0,1] neg_hi:[0,0,1]
	v_mov_b32_e32 v72, v68
	v_mov_b32_e32 v73, v66
	v_mov_b32_e32 v66, v69
	v_and_b32_e32 v69, 0xffff0000, v77
	v_and_b32_e32 v68, 0xffff0000, v76
	v_lshlrev_b32_e32 v107, 16, v75
	v_lshlrev_b32_e32 v106, 16, v74
	v_lshlrev_b32_e32 v75, 16, v77
	v_lshlrev_b32_e32 v74, 16, v76
	v_pk_fma_f32 v[66:67], v[102:103], v[66:67], v[68:69] op_sel_hi:[0,1,1] neg_lo:[0,0,1] neg_hi:[0,0,1]
	v_pk_fma_f32 v[104:105], v[102:103], v[104:105], v[106:107] op_sel_hi:[0,1,1] neg_lo:[0,0,1] neg_hi:[0,0,1]
	v_pk_fma_f32 v[72:73], v[102:103], v[72:73], v[74:75] op_sel_hi:[0,1,1] neg_lo:[0,0,1] neg_hi:[0,0,1]
	v_bfe_u32 v68, v67, 16, 1
	v_bfe_u32 v69, v66, 16, 1
	v_bfe_u32 v74, v71, 16, 1
	v_bfe_u32 v75, v70, 16, 1
	v_add3_u32 v70, v70, v75, s14
	v_add3_u32 v71, v71, v74, s14
	v_add3_u32 v66, v66, v69, s14
	v_add3_u32 v67, v67, v68, s14
	v_bfe_u32 v68, v104, 16, 1
	v_bfe_u32 v69, v105, 16, 1
	v_bfe_u32 v74, v72, 16, 1
	v_bfe_u32 v75, v73, 16, 1
	v_add3_u32 v73, v73, v75, s14
	v_add3_u32 v72, v72, v74, s14
	v_add3_u32 v69, v105, v69, s14
	v_add3_u32 v68, v104, v68, s14
	v_lshrrev_b32_e32 v74, 16, v68
	v_lshrrev_b32_e32 v75, 16, v69
	v_lshrrev_b32_e32 v68, 16, v72
	v_lshrrev_b32_e32 v69, 16, v73
	v_and_or_b32 v69, v67, s15, v69
	v_and_or_b32 v68, v66, s15, v68
	v_and_or_b32 v67, v71, s15, v75
	v_and_or_b32 v66, v70, s15, v74
	ds_read_b128 v[94:97], v90 offset:4256
	ds_read_b128 v[98:101], v90 offset:4272
	ds_write_b128 v90, v[66:69] offset:42240
	v_mov_b32_e32 v66, v64
	v_mov_b32_e32 v67, v62
	v_mov_b32_e32 v62, v65
	s_waitcnt lgkmcnt(3)
	v_and_b32_e32 v65, 0xffff0000, v79
	v_and_b32_e32 v64, 0xffff0000, v78
	v_lshlrev_b32_e32 v69, 16, v79
	v_lshlrev_b32_e32 v68, 16, v78
	v_pk_fma_f32 v[62:63], v[102:103], v[62:63], v[64:65] op_sel_hi:[0,1,1] neg_lo:[0,0,1] neg_hi:[0,0,1]
	v_mov_b32_e32 v64, v60
	v_mov_b32_e32 v65, v58
	v_mov_b32_e32 v58, v61
	v_and_b32_e32 v61, 0xffff0000, v81
	v_and_b32_e32 v60, 0xffff0000, v80
	v_pk_fma_f32 v[66:67], v[102:103], v[66:67], v[68:69] op_sel_hi:[0,1,1] neg_lo:[0,0,1] neg_hi:[0,0,1]
	v_lshlrev_b32_e32 v69, 16, v81
	v_lshlrev_b32_e32 v68, 16, v80
	v_pk_fma_f32 v[58:59], v[102:103], v[58:59], v[60:61] op_sel_hi:[0,1,1] neg_lo:[0,0,1] neg_hi:[0,0,1]
	v_pk_fma_f32 v[64:65], v[102:103], v[64:65], v[68:69] op_sel_hi:[0,1,1] neg_lo:[0,0,1] neg_hi:[0,0,1]
	v_bfe_u32 v60, v59, 16, 1
	v_bfe_u32 v61, v58, 16, 1
	v_bfe_u32 v68, v63, 16, 1
	v_bfe_u32 v69, v62, 16, 1
	v_add3_u32 v62, v62, v69, s14
	v_add3_u32 v63, v63, v68, s14
	v_add3_u32 v58, v58, v61, s14
	v_add3_u32 v59, v59, v60, s14
	v_bfe_u32 v60, v66, 16, 1
	v_bfe_u32 v61, v67, 16, 1
	v_bfe_u32 v68, v64, 16, 1
	v_bfe_u32 v69, v65, 16, 1
	v_add3_u32 v65, v65, v69, s14
	v_add3_u32 v64, v64, v68, s14
	v_add3_u32 v61, v67, v61, s14
	v_add3_u32 v60, v66, v60, s14
	v_lshrrev_b32_e32 v66, 16, v60
	v_lshrrev_b32_e32 v67, 16, v61
	v_lshrrev_b32_e32 v60, 16, v64
	v_lshrrev_b32_e32 v61, 16, v65
	v_and_or_b32 v61, v59, s15, v61
	v_and_or_b32 v60, v58, s15, v60
	v_and_or_b32 v59, v63, s15, v67
	v_and_or_b32 v58, v62, s15, v66
	ds_write_b128 v90, v[58:61] offset:42256
	v_mov_b32_e32 v58, v46
	v_mov_b32_e32 v59, v44
	v_mov_b32_e32 v44, v47
	s_waitcnt lgkmcnt(3)
	v_and_b32_e32 v47, 0xffff0000, v95
	v_and_b32_e32 v46, 0xffff0000, v94
	v_lshlrev_b32_e32 v61, 16, v95
	v_lshlrev_b32_e32 v60, 16, v94
	v_pk_fma_f32 v[44:45], v[102:103], v[44:45], v[46:47] op_sel_hi:[0,1,1] neg_lo:[0,0,1] neg_hi:[0,0,1]
	v_mov_b32_e32 v46, v42
	v_mov_b32_e32 v47, v40
	v_mov_b32_e32 v40, v43
	v_and_b32_e32 v43, 0xffff0000, v97
	v_and_b32_e32 v42, 0xffff0000, v96
	v_pk_fma_f32 v[58:59], v[102:103], v[58:59], v[60:61] op_sel_hi:[0,1,1] neg_lo:[0,0,1] neg_hi:[0,0,1]
	v_lshlrev_b32_e32 v61, 16, v97
	v_lshlrev_b32_e32 v60, 16, v96
	v_pk_fma_f32 v[40:41], v[102:103], v[40:41], v[42:43] op_sel_hi:[0,1,1] neg_lo:[0,0,1] neg_hi:[0,0,1]
	v_pk_fma_f32 v[46:47], v[102:103], v[46:47], v[60:61] op_sel_hi:[0,1,1] neg_lo:[0,0,1] neg_hi:[0,0,1]
	v_bfe_u32 v42, v41, 16, 1
	v_bfe_u32 v43, v40, 16, 1
	v_bfe_u32 v60, v45, 16, 1
	v_bfe_u32 v61, v44, 16, 1
	v_add3_u32 v44, v44, v61, s14
	v_add3_u32 v45, v45, v60, s14
	v_add3_u32 v40, v40, v43, s14
	v_add3_u32 v41, v41, v42, s14
	v_bfe_u32 v42, v58, 16, 1
	v_bfe_u32 v43, v59, 16, 1
	v_bfe_u32 v60, v46, 16, 1
	v_bfe_u32 v61, v47, 16, 1
	v_add3_u32 v47, v47, v61, s14
	v_add3_u32 v46, v46, v60, s14
	v_add3_u32 v43, v59, v43, s14
	v_add3_u32 v42, v58, v42, s14
	v_lshrrev_b32_e32 v58, 16, v42
	v_lshrrev_b32_e32 v59, 16, v43
	v_lshrrev_b32_e32 v42, 16, v46
	v_lshrrev_b32_e32 v43, 16, v47
	v_and_or_b32 v43, v41, s15, v43
	v_and_or_b32 v42, v40, s15, v42
	v_and_or_b32 v41, v45, s15, v59
	v_and_or_b32 v40, v44, s15, v58
	ds_write_b128 v90, v[40:43] offset:42272
	v_mov_b32_e32 v40, v38
	v_mov_b32_e32 v41, v36
	v_mov_b32_e32 v36, v39
	s_waitcnt lgkmcnt(3)
	v_and_b32_e32 v39, 0xffff0000, v99
	v_and_b32_e32 v38, 0xffff0000, v98
	v_lshlrev_b32_e32 v43, 16, v99
	v_lshlrev_b32_e32 v42, 16, v98
	v_pk_fma_f32 v[36:37], v[102:103], v[36:37], v[38:39] op_sel_hi:[0,1,1] neg_lo:[0,0,1] neg_hi:[0,0,1]
	v_mov_b32_e32 v38, v34
	v_mov_b32_e32 v39, v32
	v_mov_b32_e32 v32, v35
	v_and_b32_e32 v35, 0xffff0000, v101
	v_and_b32_e32 v34, 0xffff0000, v100
	v_pk_fma_f32 v[40:41], v[102:103], v[40:41], v[42:43] op_sel_hi:[0,1,1] neg_lo:[0,0,1] neg_hi:[0,0,1]
	v_lshlrev_b32_e32 v43, 16, v101
	v_lshlrev_b32_e32 v42, 16, v100
	v_pk_fma_f32 v[32:33], v[102:103], v[32:33], v[34:35] op_sel_hi:[0,1,1] neg_lo:[0,0,1] neg_hi:[0,0,1]
	v_pk_fma_f32 v[38:39], v[102:103], v[38:39], v[42:43] op_sel_hi:[0,1,1] neg_lo:[0,0,1] neg_hi:[0,0,1]
	v_bfe_u32 v34, v33, 16, 1
	v_bfe_u32 v35, v32, 16, 1
	v_bfe_u32 v42, v37, 16, 1
	v_bfe_u32 v43, v36, 16, 1
	v_add3_u32 v36, v36, v43, s14
	v_add3_u32 v37, v37, v42, s14
	v_add3_u32 v32, v32, v35, s14
	v_add3_u32 v33, v33, v34, s14
	v_bfe_u32 v34, v40, 16, 1
	v_bfe_u32 v35, v41, 16, 1
	v_bfe_u32 v42, v38, 16, 1
	v_bfe_u32 v43, v39, 16, 1
	v_add3_u32 v39, v39, v43, s14
	v_add3_u32 v38, v38, v42, s14
	v_add3_u32 v35, v41, v35, s14
	v_add3_u32 v34, v40, v34, s14
	v_lshrrev_b32_e32 v40, 16, v34
	v_lshrrev_b32_e32 v41, 16, v35
	v_lshrrev_b32_e32 v34, 16, v38
	v_lshrrev_b32_e32 v35, 16, v39
	v_and_or_b32 v35, v33, s15, v35
	v_and_or_b32 v34, v32, s15, v34
	v_and_or_b32 v33, v37, s15, v41
	v_and_or_b32 v32, v36, s15, v40
	ds_write_b128 v90, v[32:35] offset:42288
	s_waitcnt lgkmcnt(0)
	s_barrier
	ds_read_b128 v[58:61], v93 offset:42240
	ds_read_b128 v[62:65], v93 offset:42304
	s_waitcnt lgkmcnt(1)
	v_mfma_f32_16x16x32_bf16 v[32:35], v[28:31], v[58:61], 0
	v_mfma_f32_16x16x32_bf16 v[40:43], v[20:23], v[58:61], 0
	s_waitcnt lgkmcnt(0)
	v_mfma_f32_16x16x32_bf16 v[66:69], v[24:27], v[62:65], v[32:35]
	v_mov_b64_e32 v[36:37], v[160:161]
	v_mov_b64_e32 v[38:39], v[162:163]
	s_nop 3
	v_mov_b64_e32 v[32:33], v[164:165]
	v_mov_b64_e32 v[34:35], v[166:167]
	v_mov_b64_e32 v[44:45], v[168:169]
	v_mov_b64_e32 v[46:47], v[170:171]
	s_waitcnt vmcnt(2)
	v_pk_mul_f32 v[78:79], v[68:69], v[38:39]
	v_mfma_f32_16x16x32_bf16 v[70:73], v[16:19], v[62:65], v[40:43]
	v_mul_f32_e64 v80, v66, v36
	v_mul_f32_e64 v81, v67, v37
	s_nop 0
	v_mov_b64_e32 v[40:41], v[172:173]
	v_mov_b64_e32 v[42:43], v[174:175]
	v_mfma_f32_16x16x32_bf16 v[74:77], v[12:15], v[58:61], 0
	v_mfma_f32_16x16x32_bf16 v[58:61], v[4:7], v[58:61], 0
	v_mfma_f32_16x16x32_bf16 v[58:61], v[0:3], v[62:65], v[58:61]
	v_mfma_f32_16x16x32_bf16 v[94:97], v[8:11], v[62:65], v[74:77]
	s_waitcnt vmcnt(2)
	s_nop 3
	v_pk_mul_f32 v[74:75], v[72:73], v[34:35]
	s_waitcnt vmcnt(1)
	v_pk_mul_f32 v[68:69], v[58:59], v[44:45]
	v_mul_f32_e32 v58, v81, v81
	v_mul_f32_e32 v59, v79, v79
	v_pk_mul_f32 v[76:77], v[70:71], v[32:33]
	v_fmac_f32_e32 v58, v80, v80
	v_fmac_f32_e32 v59, v78, v78
	v_pk_mul_f32 v[64:65], v[60:61], v[46:47]
	v_add_f32_e32 v58, v58, v59
	v_mul_f32_e32 v59, v77, v77
	v_mul_f32_e32 v60, v75, v75
	v_fmac_f32_e32 v59, v76, v76
	v_fmac_f32_e32 v60, v74, v74
	v_add_f32_e32 v59, v59, v60
	v_add_f32_e32 v58, v58, v59
	s_waitcnt vmcnt(0)
	v_pk_mul_f32 v[70:71], v[96:97], v[42:43]
	v_pk_mul_f32 v[72:73], v[94:95], v[40:41]
	v_mul_f32_e32 v60, v71, v71
	v_mul_f32_e32 v59, v73, v73
	v_fmac_f32_e32 v59, v72, v72
	v_fmac_f32_e32 v60, v70, v70
	v_add_f32_e32 v59, v59, v60
	v_add_f32_e32 v58, v58, v59
	v_mul_f32_e32 v59, v69, v69
	v_mul_f32_e32 v60, v65, v65
	v_fmac_f32_e32 v59, v68, v68
	v_fmac_f32_e32 v60, v64, v64
	v_add_f32_e32 v59, v59, v60
	v_add_f32_e32 v58, v58, v59
	ds_bpermute_b32 v59, v84, v58
	s_waitcnt lgkmcnt(0)
	v_add_f32_e32 v58, v58, v59
	ds_bpermute_b32 v59, v85, v58
	s_and_saveexec_b64 s[6:7], s[4:5]
	s_cbranch_execz .LBB0_334
	s_waitcnt lgkmcnt(0)
	v_add_f32_e32 v58, v58, v59
	v_add_u32_e32 v59, s3, v86
	ds_write_b32 v59, v58
